# speedup vs baseline: 1.0199x; 1.0199x over previous
; DEVI int opq_tid() { int t = threadIdx.x; asm volatile("" : "+v"(t)); return t; }
; DEVI void phase0(const Params& P) {
;   const int tid = opq_tid();
;   float* tl = (float*)g_shm;
;   for (int t = blockIdx.x; t < P.ntiles; t += gridDim.x) {
;     int ji = 0;
;     for (int j = 1; j < NJOBS; ++j) if (t >= P.jobs[j].tile0) ji = j;
;     const Job jb = P.jobs[ji];
;     const int lt = t - jb.tile0, nkt = jb.K >> 6, kt = lt % nkt, ntile = lt / nkt;
;     const int k0 = kt * 64, n0 = ntile * 256;
;     {
;       const int nc4 = (tid & 63) * 4; const int sc = map_col(jb.mode, n0 + nc4, jb.N);
; #pragma unroll
;       for (int i = 0; i < 8; ++i) {
;         const int kr = (tid >> 6) + i * 8;
;         float4 v = make_float4(0.f, 0.f, 0.f, 0.f);
;         if (sc >= 0) v = *(const float4*)(jb.src + (long)(k0 + kr) * jb.N + sc);
;         *(float4*)(tl + kr * 260 + nc4) = v;
_Z14fwd_megakernel6Params:
	v_readfirstlane_b32 s101, v0
	s_nop 3
	s_bfe_u32 s101, s101, 0x10008
	s_mov_b64 s[50:51], s[0:1]
	s_load_dword s62, s[50:51], 0x4a8
	s_load_dwordx2 s[34:35], s[50:51], 0x88
	s_load_dword s16, s[50:51], 0x4a0
	s_add_u32 s0, s50, 0x4a8
	s_addc_u32 s1, s51, 0
	v_and_b32_e32 v167, 0x3ff, v0
	v_writelane_b32 v253, s0, 0
	v_mov_b32_e32 v10, v167
	s_mov_b32 s80, s2
	v_writelane_b32 v253, s1, 1
	s_waitcnt lgkmcnt(0)
	s_cmp_ge_i32 s2, s16
	v_lshlrev_b32_e32 v1, 2, v10
	v_ashrrev_i32_e32 v18, 6, v10
	s_cbranch_scc1 .LBB0_15
	s_load_dword s17, s[50:51], 0xd8
	s_load_dword s18, s[50:51], 0x100
	s_load_dword s19, s[50:51], 0x128
	s_load_dword s20, s[50:51], 0x150
	s_load_dword s21, s[50:51], 0x178
	s_load_dword s22, s[50:51], 0x1a0
	s_load_dword s23, s[50:51], 0x1c8
	s_load_dword s24, s[50:51], 0x1f0
	s_load_dword s25, s[50:51], 0x218
	s_load_dword s26, s[50:51], 0x240
	s_load_dword s27, s[50:51], 0x268
	s_load_dword s28, s[50:51], 0x290
	s_load_dword s29, s[50:51], 0x2b8
	s_load_dword s30, s[50:51], 0x2e0
	s_load_dword s31, s[50:51], 0x308
	s_load_dword s33, s[50:51], 0x330
	s_load_dword s36, s[50:51], 0x358
	s_load_dword s37, s[50:51], 0x380
	s_load_dword s38, s[50:51], 0x3a8
	s_load_dword s39, s[50:51], 0x3d0
	s_load_dword s40, s[50:51], 0x3f8
	s_load_dword s41, s[50:51], 0x420
	s_load_dword s42, s[50:51], 0x448
	s_load_dword s43, s[50:51], 0x470
	s_load_dword s44, s[50:51], 0x498
	v_lshlrev_b32_e32 v3, 1, v10
	v_lshlrev_b32_e32 v2, 2, v10
	v_and_b32_e32 v3, 0x60, v3
	v_and_b32_e32 v11, 0xfc, v2
	v_and_or_b32 v19, v2, 28, v3
	v_and_b32_e32 v2, 8, v10
	v_cmp_eq_u32_e64 s[4:5], 0, v2
	v_lshlrev_b32_e32 v2, 3, v10
	v_and_b32_e32 v2, 56, v2
	v_ashrrev_i32_e32 v20, 3, v10
	v_lshlrev_b32_e32 v4, 2, v20
	s_movk_i32 s0, 0x410
	v_mul_u32_u24_e32 v5, 0x410, v2
	v_lshlrev_b32_e32 v3, 2, v11
	v_mov_b32_e32 v13, 0
	v_mul_lo_u32 v6, v18, s0
	v_add_u32_e32 v26, v4, v5
	s_mov_b32 s8, 0
	v_add_u32_e32 v21, 32, v18
	v_add_u32_e32 v22, 40, v18
	v_add_u32_e32 v23, 48, v18
	v_add_u32_e32 v24, 56, v18
	v_add_u32_e32 v25, v3, v6
	v_lshlrev_b32_e32 v14, 1, v2
	v_mov_b32_e32 v15, v13
	v_add_u32_e32 v27, 16, v26
	v_add_u32_e32 v28, 32, v26
	v_add_u32_e32 v29, 48, v26
	v_add_u32_e32 v30, 64, v26
	v_add_u32_e32 v31, 0x50, v26
	v_add_u32_e32 v32, 0x60, v26
	v_add_u32_e32 v33, 0x70, v26
	s_mov_b32 s45, s80
	s_branch .LBB0_3

; #define WAIT_V0() asm volatile("s_waitcnt vmcnt(0)" ::: "memory")
; #define SBAR() __builtin_amdgcn_sched_barrier(0)
; template <int EPI>
; DEVI void gemm_tile(const u16* __restrict__ Ab, long lda, const u16* __restrict__ Bb, long ldb, int K, const EpiArgs& e,
;                     bool have0 = false, const u16* __restrict__ nA = nullptr, const u16* __restrict__ nB = nullptr) {
;     ...
;   f32x4 acc[8][4];
; #pragma unroll
;   for (int m = 0; m < 8; ++m)
; #pragma unroll
;     for (int n = 0; n < 4; ++n) acc[m][n] = f32x4{0.f, 0.f, 0.f, 0.f};
;   const int nt = K / BK;
;   if (!have0) GLDS_STAGE(0, 0);
;   WAIT_V0(); __syncthreads();
;   for (int t = 0; t < nt; ++t) {
;     const int cur = t & 1;
;     if (t + 1 < nt) GLDS_STAGE(cur ^ 1, t + 1);
;     else if (nA) {
; #pragma unroll
;       for (int i = 0; i < GL; ++i) {
;         __builtin_amdgcn_global_load_lds((const unsigned*)(nA + (long)i * 64 * lda + toffA), (unsigned*)(g_shm + wid * 1024 + i * 8192), 16, 0, 0);
;         __builtin_amdgcn_global_load_lds((const unsigned*)(nB + (long)i * 64 * ldb + toffB), (unsigned*)(g_shm + TILE_B + wid * 1024 + i * 8192), 16, 0, 0);
;       }
;     }
;     const char* sb = g_shm + cur * STAGE_B;
; #pragma unroll
;     for (int ks = 0; ks < 2; ++ks) {
;       bf16x8 Bf[4];
; #pragma unroll
;       for (int n = 0; n < 4; ++n) Bf[n] = *(const bf16x8*)(sb + b_base + n * 2048 + ks * 1024);
; #pragma unroll
;       for (int mh = 0; mh < 2; ++mh) {
;         bf16x8 At[4];
; #pragma unroll
;         for (int m = 0; m < 4; ++m) At[m] = *(const bf16x8*)(sb + a_base + (mh * 4 + m) * 2048 + ks * 1024);
;         __builtin_amdgcn_s_setprio(1);
; #pragma unroll
;         for (int m = 0; m < 4; ++m)
; #pragma unroll
;           for (int n = 0; n < 4; ++n) acc[mh * 4 + m][n] = __builtin_amdgcn_mfma_f32_16x16x32_bf16(Bf[n], At[m], acc[mh * 4 + m][n], 0, 0, 0);
;         __builtin_amdgcn_s_setprio(0);
;       }
;       SBAR();
;     }
;     if (t + 1 < nt) { WAIT_V0(); __syncthreads(); }
;   }
.LBB0_150:
	s_and_b32 s3, s2, 0x10000
	v_or_b32_e32 v149, s3, v147
	v_add_u32_e32 v169, v149, v148
	v_add_u32_e32 v149, v149, v146
	ds_read_b128 v[150:153], v169 offset:32768
	ds_read_b128 v[154:157], v169 offset:34816
	ds_read_b128 v[158:161], v169 offset:36864
	ds_read_b128 v[162:165], v169 offset:38912
	ds_read_b128 v[170:173], v149
	ds_read_b128 v[174:177], v149 offset:2048
	ds_read_b128 v[214:217], v149 offset:4096
	ds_read_b128 v[218:221], v149 offset:6144
	v_writelane_b32 v240, s4, 0
	v_writelane_b32 v240, s5, 1
	v_writelane_b32 v240, s6, 2
	v_writelane_b32 v240, s7, 3
	v_writelane_b32 v240, s8, 4
	v_writelane_b32 v240, s9, 5
	v_writelane_b32 v240, s10, 6
	v_readfirstlane_b32 s4, v132
	v_readfirstlane_b32 s5, v133
	s_nop 1
	v_subrev_u32_e32 v238, s4, v132
	s_add_u32 s4, s4, s14
	s_addc_u32 s5, s5, s15
	v_readfirstlane_b32 s6, v134
	v_readfirstlane_b32 s7, v135
	s_nop 1
	v_subrev_u32_e32 v239, s6, v134
	s_add_u32 s6, s6, s14
	s_addc_u32 s7, s7, s15
	v_readfirstlane_b32 s10, v140
	s_xor_b32 s8, s3, 0x10000
	s_nop 0
	s_add_i32 s10, s10, s8
	s_add_i32 m0, s10, 0x0
	s_add_u32 s8, s4, s20
	s_addc_u32 s9, s5, s21
	global_load_lds_dwordx4 v238, s[8:9]
	s_add_i32 m0, s10, 0x8000
	s_add_u32 s8, s6, s24
	s_addc_u32 s9, s7, s25
	global_load_lds_dwordx4 v239, s[8:9]
	s_add_i32 m0, s10, 0x2000
	s_add_u32 s8, s4, s22
	s_addc_u32 s9, s5, s23
	global_load_lds_dwordx4 v238, s[8:9]
.Lkl_150:
	s_waitcnt lgkmcnt(3)
	v_mfma_f32_16x16x32_bf16 v[126:129], v[150:153], v[170:173], v[126:129]
	v_mfma_f32_16x16x32_bf16 v[122:125], v[154:157], v[170:173], v[122:125]
	v_mfma_f32_16x16x32_bf16 v[118:121], v[158:161], v[170:173], v[118:121]
	v_mfma_f32_16x16x32_bf16 v[114:117], v[162:165], v[170:173], v[114:117]
	ds_read_b128 v[170:173], v149 offset:8192
	ds_read_b128 v[222:225], v169 offset:33792
	s_add_i32 m0, s10, 0xa000
	s_add_u32 s8, s6, 0x20080
	s_addc_u32 s9, s7, 0
	global_load_lds_dwordx4 v239, s[8:9]
	s_waitcnt lgkmcnt(4)
	v_mfma_f32_16x16x32_bf16 v[110:113], v[150:153], v[174:177], v[110:113]
	v_mfma_f32_16x16x32_bf16 v[106:109], v[154:157], v[174:177], v[106:109]
	v_mfma_f32_16x16x32_bf16 v[102:105], v[158:161], v[174:177], v[102:105]
	v_mfma_f32_16x16x32_bf16 v[98:101], v[162:165], v[174:177], v[98:101]
	ds_read_b128 v[174:177], v149 offset:10240
	ds_read_b128 v[226:229], v169 offset:35840
	s_add_i32 m0, s10, 0x4000
	s_add_u32 s8, s4, s26
	s_addc_u32 s9, s5, s27
	global_load_lds_dwordx4 v238, s[8:9]
	s_waitcnt lgkmcnt(5)
	v_mfma_f32_16x16x32_bf16 v[94:97], v[150:153], v[214:217], v[94:97]
	v_mfma_f32_16x16x32_bf16 v[90:93], v[154:157], v[214:217], v[90:93]
	v_mfma_f32_16x16x32_bf16 v[86:89], v[158:161], v[214:217], v[86:89]
	v_mfma_f32_16x16x32_bf16 v[82:85], v[162:165], v[214:217], v[82:85]
	ds_read_b128 v[214:217], v149 offset:12288
	ds_read_b128 v[230:233], v169 offset:37888
	s_add_i32 m0, s10, 0xc000
	s_add_u32 s8, s6, 0x40080
	s_addc_u32 s9, s7, 0
	global_load_lds_dwordx4 v239, s[8:9]
	s_waitcnt lgkmcnt(6)
	v_mfma_f32_16x16x32_bf16 v[78:81], v[150:153], v[218:221], v[78:81]
	v_mfma_f32_16x16x32_bf16 v[74:77], v[154:157], v[218:221], v[74:77]
	v_mfma_f32_16x16x32_bf16 v[70:73], v[158:161], v[218:221], v[70:73]
	v_mfma_f32_16x16x32_bf16 v[66:69], v[162:165], v[218:221], v[66:69]
	ds_read_b128 v[218:221], v149 offset:14336
	ds_read_b128 v[234:237], v169 offset:39936
	s_add_i32 m0, s10, 0x6000
	s_add_u32 s8, s4, s30
	s_addc_u32 s9, s5, s31
	global_load_lds_dwordx4 v238, s[8:9]
	s_waitcnt lgkmcnt(7)
	v_mfma_f32_16x16x32_bf16 v[62:65], v[150:153], v[170:173], v[62:65]
	v_mfma_f32_16x16x32_bf16 v[58:61], v[154:157], v[170:173], v[58:61]
	v_mfma_f32_16x16x32_bf16 v[54:57], v[158:161], v[170:173], v[54:57]
	v_mfma_f32_16x16x32_bf16 v[50:53], v[162:165], v[170:173], v[50:53]
	ds_read_b128 v[170:173], v149 offset:1024
	s_add_i32 m0, s10, 0xe000
	s_add_u32 s8, s6, 0x60080
	s_addc_u32 s9, s7, 0
	global_load_lds_dwordx4 v239, s[8:9]
	s_waitcnt lgkmcnt(6)
	v_mfma_f32_16x16x32_bf16 v[46:49], v[150:153], v[174:177], v[46:49]
	v_mfma_f32_16x16x32_bf16 v[42:45], v[154:157], v[174:177], v[42:45]
	v_mfma_f32_16x16x32_bf16 v[38:41], v[158:161], v[174:177], v[38:41]
	v_mfma_f32_16x16x32_bf16 v[34:37], v[162:165], v[174:177], v[34:37]
	ds_read_b128 v[174:177], v149 offset:3072
	s_waitcnt lgkmcnt(5)
	v_mfma_f32_16x16x32_bf16 v[30:33], v[150:153], v[214:217], v[30:33]
	v_mfma_f32_16x16x32_bf16 v[26:29], v[154:157], v[214:217], v[26:29]
	v_mfma_f32_16x16x32_bf16 v[22:25], v[158:161], v[214:217], v[22:25]
	v_mfma_f32_16x16x32_bf16 v[18:21], v[162:165], v[214:217], v[18:21]
	ds_read_b128 v[214:217], v149 offset:5120
	s_waitcnt lgkmcnt(4)
	v_mfma_f32_16x16x32_bf16 v[14:17], v[150:153], v[218:221], v[14:17]
	v_mfma_f32_16x16x32_bf16 v[10:13], v[154:157], v[218:221], v[10:13]
	v_mfma_f32_16x16x32_bf16 v[6:9], v[158:161], v[218:221], v[6:9]
	v_mfma_f32_16x16x32_bf16 v[2:5], v[162:165], v[218:221], v[2:5]
	ds_read_b128 v[218:221], v149 offset:7168
	s_waitcnt lgkmcnt(3)
	v_mfma_f32_16x16x32_bf16 v[126:129], v[222:225], v[170:173], v[126:129]
	v_mfma_f32_16x16x32_bf16 v[122:125], v[226:229], v[170:173], v[122:125]
	v_mfma_f32_16x16x32_bf16 v[118:121], v[230:233], v[170:173], v[118:121]
	v_mfma_f32_16x16x32_bf16 v[114:117], v[234:237], v[170:173], v[114:117]
	ds_read_b128 v[170:173], v149 offset:9216
	s_waitcnt lgkmcnt(3)
; #define WAIT_V0() asm volatile("s_waitcnt vmcnt(0)" ::: "memory")
; #define SBAR() __builtin_amdgcn_sched_barrier(0)
; template <int EPI>
; DEVI void gemm_tile(const u16* __restrict__ Ab, long lda, const u16* __restrict__ Bb, long ldb, int K, const EpiArgs& e,
;                     bool have0 = false, const u16* __restrict__ nA = nullptr, const u16* __restrict__ nB = nullptr) {
;     ...
;   f32x4 acc[8][4];
; #pragma unroll
;   for (int m = 0; m < 8; ++m)
; #pragma unroll
;     for (int n = 0; n < 4; ++n) acc[m][n] = f32x4{0.f, 0.f, 0.f, 0.f};
;   const int nt = K / BK;
;   if (!have0) GLDS_STAGE(0, 0);
;   WAIT_V0(); __syncthreads();
;   for (int t = 0; t < nt; ++t) {
;     const int cur = t & 1;
;     if (t + 1 < nt) GLDS_STAGE(cur ^ 1, t + 1);
;     else if (nA) {
; #pragma unroll
;       for (int i = 0; i < GL; ++i) {
;         __builtin_amdgcn_global_load_lds((const unsigned*)(nA + (long)i * 64 * lda + toffA), (unsigned*)(g_shm + wid * 1024 + i * 8192), 16, 0, 0);
;         __builtin_amdgcn_global_load_lds((const unsigned*)(nB + (long)i * 64 * ldb + toffB), (unsigned*)(g_shm + TILE_B + wid * 1024 + i * 8192), 16, 0, 0);
;       }
;     }
;     const char* sb = g_shm + cur * STAGE_B;
; #pragma unroll
;     for (int ks = 0; ks < 2; ++ks) {
;       bf16x8 Bf[4];
; #pragma unroll
;       for (int n = 0; n < 4; ++n) Bf[n] = *(const bf16x8*)(sb + b_base + n * 2048 + ks * 1024);
; #pragma unroll
;       for (int mh = 0; mh < 2; ++mh) {
;         bf16x8 At[4];
; #pragma unroll
;         for (int m = 0; m < 4; ++m) At[m] = *(const bf16x8*)(sb + a_base + (mh * 4 + m) * 2048 + ks * 1024);
;         __builtin_amdgcn_s_setprio(1);
; #pragma unroll
;         for (int m = 0; m < 4; ++m)
; #pragma unroll
;           for (int n = 0; n < 4; ++n) acc[mh * 4 + m][n] = __builtin_amdgcn_mfma_f32_16x16x32_bf16(Bf[n], At[m], acc[mh * 4 + m][n], 0, 0, 0);
;         __builtin_amdgcn_s_setprio(0);
;       }
;       SBAR();
;     }
;     if (t + 1 < nt) { WAIT_V0(); __syncthreads(); }
;   }
	v_mfma_f32_16x16x32_bf16 v[110:113], v[222:225], v[174:177], v[110:113]
	v_mfma_f32_16x16x32_bf16 v[106:109], v[226:229], v[174:177], v[106:109]
	v_mfma_f32_16x16x32_bf16 v[102:105], v[230:233], v[174:177], v[102:105]
	v_mfma_f32_16x16x32_bf16 v[98:101], v[234:237], v[174:177], v[98:101]
	ds_read_b128 v[174:177], v149 offset:11264
	s_waitcnt lgkmcnt(3)
	v_mfma_f32_16x16x32_bf16 v[94:97], v[222:225], v[214:217], v[94:97]
	v_mfma_f32_16x16x32_bf16 v[90:93], v[226:229], v[214:217], v[90:93]
	v_mfma_f32_16x16x32_bf16 v[86:89], v[230:233], v[214:217], v[86:89]
	v_mfma_f32_16x16x32_bf16 v[82:85], v[234:237], v[214:217], v[82:85]
	ds_read_b128 v[214:217], v149 offset:13312
	s_waitcnt lgkmcnt(3)
	v_mfma_f32_16x16x32_bf16 v[78:81], v[222:225], v[218:221], v[78:81]
	v_mfma_f32_16x16x32_bf16 v[74:77], v[226:229], v[218:221], v[74:77]
	v_mfma_f32_16x16x32_bf16 v[70:73], v[230:233], v[218:221], v[70:73]
	v_mfma_f32_16x16x32_bf16 v[66:69], v[234:237], v[218:221], v[66:69]
	ds_read_b128 v[218:221], v149 offset:15360
	s_waitcnt lgkmcnt(3)
	v_mfma_f32_16x16x32_bf16 v[62:65], v[222:225], v[170:173], v[62:65]
	v_mfma_f32_16x16x32_bf16 v[58:61], v[226:229], v[170:173], v[58:61]
	v_mfma_f32_16x16x32_bf16 v[54:57], v[230:233], v[170:173], v[54:57]
	v_mfma_f32_16x16x32_bf16 v[50:53], v[234:237], v[170:173], v[50:53]
	s_waitcnt lgkmcnt(2)
	v_mfma_f32_16x16x32_bf16 v[46:49], v[222:225], v[174:177], v[46:49]
	v_mfma_f32_16x16x32_bf16 v[42:45], v[226:229], v[174:177], v[42:45]
	v_mfma_f32_16x16x32_bf16 v[38:41], v[230:233], v[174:177], v[38:41]
	v_mfma_f32_16x16x32_bf16 v[34:37], v[234:237], v[174:177], v[34:37]
	s_waitcnt lgkmcnt(0)
	s_add_i32 s2, s2, 0x10000
	s_waitcnt vmcnt(0)
	s_add_u32 s14, s14, 0x80
	s_addc_u32 s15, s15, 0
	s_cmpk_eq_i32 s14, 0x780
	s_waitcnt vmcnt(0)
	s_barrier
	s_cselect_b32 s100, 1, 0
	s_and_b32 s3, s2, 0x10000
	v_or_b32_e32 v149, s3, v147
	v_add_u32_e32 v169, v149, v148
	v_add_u32_e32 v149, v149, v146
	ds_read_b128 v[150:153], v169 offset:32768
	ds_read_b128 v[154:157], v169 offset:34816
	ds_read_b128 v[158:161], v169 offset:36864
	ds_read_b128 v[162:165], v169 offset:38912
	ds_read_b128 v[170:173], v149
	ds_read_b128 v[174:177], v149 offset:2048
	s_add_u32 s4, s4, 0x80
	s_addc_u32 s5, s5, 0
	s_add_u32 s6, s6, 0x80
	s_addc_u32 s7, s7, 0
	s_cmp_eq_u32 s100, 1
	s_cbranch_scc1 .Lkl_150_s1
	v_readfirstlane_b32 s10, v140
	s_xor_b32 s8, s3, 0x10000
	s_nop 0
	s_add_i32 s10, s10, s8
	s_add_i32 m0, s10, 0x0
	s_add_u32 s8, s4, s20
	s_addc_u32 s9, s5, s21
	global_load_lds_dwordx4 v238, s[8:9]
.Lkl_150_s1:
	v_mfma_f32_16x16x32_bf16 v[30:33], v[222:225], v[214:217], v[30:33]
	v_mfma_f32_16x16x32_bf16 v[26:29], v[226:229], v[214:217], v[26:29]
	v_mfma_f32_16x16x32_bf16 v[22:25], v[230:233], v[214:217], v[22:25]
	v_mfma_f32_16x16x32_bf16 v[18:21], v[234:237], v[214:217], v[18:21]
	ds_read_b128 v[214:217], v149 offset:4096
	s_cmp_eq_u32 s100, 1
	s_cbranch_scc1 .Lkl_150_s2
	s_add_i32 m0, s10, 0x8000
	s_add_u32 s8, s6, s24
	s_addc_u32 s9, s7, s25
	global_load_lds_dwordx4 v239, s[8:9]
.Lkl_150_s2:
	v_mfma_f32_16x16x32_bf16 v[14:17], v[222:225], v[218:221], v[14:17]
	v_mfma_f32_16x16x32_bf16 v[10:13], v[226:229], v[218:221], v[10:13]
	v_mfma_f32_16x16x32_bf16 v[6:9], v[230:233], v[218:221], v[6:9]
	v_mfma_f32_16x16x32_bf16 v[2:5], v[234:237], v[218:221], v[2:5]
	ds_read_b128 v[218:221], v149 offset:6144
	s_cmp_eq_u32 s100, 1
	s_cbranch_scc1 .Lkl_150_s3
	s_add_i32 m0, s10, 0x2000
	s_add_u32 s8, s4, s22
	s_addc_u32 s9, s5, s23
	global_load_lds_dwordx4 v238, s[8:9]
.Lkl_150_s3:
	s_cmp_eq_u32 s100, 1
	s_cbranch_scc0 .Lkl_150
	s_nop 3
	v_readlane_b32 s4, v240, 0
	v_readlane_b32 s5, v240, 1
	v_readlane_b32 s6, v240, 2
	v_readlane_b32 s7, v240, 3
	v_readlane_b32 s8, v240, 4
	v_readlane_b32 s9, v240, 5
	v_readlane_b32 s10, v240, 6
	s_waitcnt lgkmcnt(0)
	s_xor_b32 s3, s3, 0x10000
	v_or_b32_e32 v149, s3, v147
	v_add_u32_e32 v169, v149, v148
	v_add_u32_e32 v149, v149, v146
	s_cmp_eq_u32 s100, 1
	s_cmp_eq_u64 s[10:11], 0
	s_cbranch_scc1 .LBB0_138
	v_readfirstlane_b32 s2, v140
	v_lshl_add_u64 v[132:133], s[10:11], 0, v[130:131]
	s_mov_b32 m0, s2
	v_readfirstlane_b32 s2, v145
	v_lshl_add_u64 v[130:131], s[12:13], 0, v[130:131]
	global_load_lds_dwordx4 v[132:133], off
	s_mov_b32 m0, s2
	s_mov_b64 s[12:13], 0x20000
	v_readfirstlane_b32 s2, v144
	global_load_lds_dwordx4 v[130:131], off
	v_lshl_add_u64 v[134:135], v[132:133], 0, s[12:13]
	s_mov_b32 m0, s2
	v_readfirstlane_b32 s2, v143
	global_load_lds_dwordx4 v[134:135], off
	v_lshl_add_u64 v[134:135], v[130:131], 0, s[12:13]
	s_mov_b32 m0, s2
	v_readfirstlane_b32 s2, v142
	global_load_lds_dwordx4 v[134:135], off
	v_lshl_add_u64 v[134:135], v[132:133], 0, s[96:97]
	s_mov_b32 m0, s2
	v_readfirstlane_b32 s2, v141
	global_load_lds_dwordx4 v[134:135], off
	v_lshl_add_u64 v[134:135], v[130:131], 0, s[96:97]
	s_mov_b32 m0, s2
	s_mov_b64 s[12:13], 0x60000
	v_readfirstlane_b32 s2, v139
	global_load_lds_dwordx4 v[134:135], off
	v_lshl_add_u64 v[132:133], v[132:133], 0, s[12:13]
	s_mov_b32 m0, s2
	v_readfirstlane_b32 s2, v138
	global_load_lds_dwordx4 v[132:133], off
	v_lshl_add_u64 v[130:131], v[130:131], 0, s[12:13]
	s_mov_b32 m0, s2
	s_nop 0
	global_load_lds_dwordx4 v[130:131], off
	s_branch .LBB0_138

; #define WAIT_V0() asm volatile("s_waitcnt vmcnt(0)" ::: "memory")
; #define SBAR() __builtin_amdgcn_sched_barrier(0)
; template <int EPI>
; DEVI void gemm_tile(const u16* __restrict__ Ab, long lda, const u16* __restrict__ Bb, long ldb, int K, const EpiArgs& e,
;                     bool have0 = false, const u16* __restrict__ nA = nullptr, const u16* __restrict__ nB = nullptr) {
;     ...
;   f32x4 acc[8][4];
; #pragma unroll
;   for (int m = 0; m < 8; ++m)
; #pragma unroll
;     for (int n = 0; n < 4; ++n) acc[m][n] = f32x4{0.f, 0.f, 0.f, 0.f};
;   const int nt = K / BK;
;   if (!have0) GLDS_STAGE(0, 0);
;   WAIT_V0(); __syncthreads();
;   for (int t = 0; t < nt; ++t) {
;     const int cur = t & 1;
;     if (t + 1 < nt) GLDS_STAGE(cur ^ 1, t + 1);
;     else if (nA) {
; #pragma unroll
;       for (int i = 0; i < GL; ++i) {
;         __builtin_amdgcn_global_load_lds((const unsigned*)(nA + (long)i * 64 * lda + toffA), (unsigned*)(g_shm + wid * 1024 + i * 8192), 16, 0, 0);
;         __builtin_amdgcn_global_load_lds((const unsigned*)(nB + (long)i * 64 * ldb + toffB), (unsigned*)(g_shm + TILE_B + wid * 1024 + i * 8192), 16, 0, 0);
;       }
;     }
;     const char* sb = g_shm + cur * STAGE_B;
; #pragma unroll
;     for (int ks = 0; ks < 2; ++ks) {
;       bf16x8 Bf[4];
; #pragma unroll
;       for (int n = 0; n < 4; ++n) Bf[n] = *(const bf16x8*)(sb + b_base + n * 2048 + ks * 1024);
; #pragma unroll
;       for (int mh = 0; mh < 2; ++mh) {
;         bf16x8 At[4];
; #pragma unroll
;         for (int m = 0; m < 4; ++m) At[m] = *(const bf16x8*)(sb + a_base + (mh * 4 + m) * 2048 + ks * 1024);
;         __builtin_amdgcn_s_setprio(1);
; #pragma unroll
;         for (int m = 0; m < 4; ++m)
; #pragma unroll
;           for (int n = 0; n < 4; ++n) acc[mh * 4 + m][n] = __builtin_amdgcn_mfma_f32_16x16x32_bf16(Bf[n], At[m], acc[mh * 4 + m][n], 0, 0, 0);
;         __builtin_amdgcn_s_setprio(0);
;       }
;       SBAR();
;     }
;     if (t + 1 < nt) { WAIT_V0(); __syncthreads(); }
;   }
.LBB0_184:
	s_and_b32 s22, s3, 0x10000
	v_or_b32_e32 v150, s22, v149
	v_add_u32_e32 v169, v150, v148
	v_or_b32_e32 v150, s22, v146
	v_add_u32_e32 v178, v150, v147
	ds_read_b128 v[150:153], v169 offset:32768
	ds_read_b128 v[154:157], v169 offset:34816
	ds_read_b128 v[158:161], v169 offset:36864
	ds_read_b128 v[162:165], v169 offset:38912
	ds_read_b128 v[170:173], v178
	ds_read_b128 v[174:177], v178 offset:2048
	ds_read_b128 v[214:217], v178 offset:4096
	ds_read_b128 v[218:221], v178 offset:6144
	v_writelane_b32 v240, s4, 0
	v_writelane_b32 v240, s5, 1
	v_writelane_b32 v240, s6, 2
	v_writelane_b32 v240, s7, 3
	v_writelane_b32 v240, s8, 4
	v_writelane_b32 v240, s9, 5
	v_writelane_b32 v240, s10, 6
	v_readfirstlane_b32 s4, v134
	v_readfirstlane_b32 s5, v135
	s_nop 1
	v_subrev_u32_e32 v238, s4, v134
	s_add_u32 s4, s4, s14
	s_addc_u32 s5, s5, s15
	v_readfirstlane_b32 s6, v136
	v_readfirstlane_b32 s7, v137
	s_nop 1
	v_subrev_u32_e32 v239, s6, v136
	s_add_u32 s6, s6, s14
	s_addc_u32 s7, s7, s15
	v_readfirstlane_b32 s10, v143
	s_xor_b32 s8, s22, 0x10000
	s_nop 0
	s_add_i32 s10, s10, s8
	s_add_i32 m0, s10, 0x0
	s_add_u32 s8, s4, s24
	s_addc_u32 s9, s5, s25
	global_load_lds_dwordx4 v238, s[8:9]
	s_add_i32 m0, s10, 0x8000
	s_add_u32 s8, s6, 0x1600080
	s_addc_u32 s9, s7, 0
	global_load_lds_dwordx4 v239, s[8:9]
	s_add_i32 m0, s10, 0x2000
	s_add_u32 s8, s4, s26
	s_addc_u32 s9, s5, s27
	global_load_lds_dwordx4 v238, s[8:9]
.Lkl_184:
	s_waitcnt lgkmcnt(3)
	v_mfma_f32_16x16x32_bf16 v[126:129], v[150:153], v[170:173], v[126:129]
	v_mfma_f32_16x16x32_bf16 v[122:125], v[154:157], v[170:173], v[122:125]
	v_mfma_f32_16x16x32_bf16 v[118:121], v[158:161], v[170:173], v[118:121]
	v_mfma_f32_16x16x32_bf16 v[114:117], v[162:165], v[170:173], v[114:117]
	ds_read_b128 v[170:173], v178 offset:8192
	ds_read_b128 v[222:225], v169 offset:33792
	s_add_i32 m0, s10, 0xa000
	s_add_u32 s8, s6, 0x1658080
	s_addc_u32 s9, s7, 0
	global_load_lds_dwordx4 v239, s[8:9]
	s_waitcnt lgkmcnt(4)
	v_mfma_f32_16x16x32_bf16 v[110:113], v[150:153], v[174:177], v[110:113]
	v_mfma_f32_16x16x32_bf16 v[106:109], v[154:157], v[174:177], v[106:109]
	v_mfma_f32_16x16x32_bf16 v[102:105], v[158:161], v[174:177], v[102:105]
	v_mfma_f32_16x16x32_bf16 v[98:101], v[162:165], v[174:177], v[98:101]
	ds_read_b128 v[174:177], v178 offset:10240
	ds_read_b128 v[226:229], v169 offset:35840
	s_add_i32 m0, s10, 0x4000
	s_add_u32 s8, s4, s30
	s_addc_u32 s9, s5, s31
	global_load_lds_dwordx4 v238, s[8:9]
	s_waitcnt lgkmcnt(5)
	v_mfma_f32_16x16x32_bf16 v[94:97], v[150:153], v[214:217], v[94:97]
	v_mfma_f32_16x16x32_bf16 v[90:93], v[154:157], v[214:217], v[90:93]
	v_mfma_f32_16x16x32_bf16 v[86:89], v[158:161], v[214:217], v[86:89]
	v_mfma_f32_16x16x32_bf16 v[82:85], v[162:165], v[214:217], v[82:85]
	ds_read_b128 v[214:217], v178 offset:12288
	ds_read_b128 v[230:233], v169 offset:37888
	s_add_i32 m0, s10, 0xc000
	s_add_u32 s8, s6, 0x16b0080
	s_addc_u32 s9, s7, 0
	global_load_lds_dwordx4 v239, s[8:9]
	s_waitcnt lgkmcnt(6)
	v_mfma_f32_16x16x32_bf16 v[78:81], v[150:153], v[218:221], v[78:81]
	v_mfma_f32_16x16x32_bf16 v[74:77], v[154:157], v[218:221], v[74:77]
	v_mfma_f32_16x16x32_bf16 v[70:73], v[158:161], v[218:221], v[70:73]
	v_mfma_f32_16x16x32_bf16 v[66:69], v[162:165], v[218:221], v[66:69]
	ds_read_b128 v[218:221], v178 offset:14336
	ds_read_b128 v[234:237], v169 offset:39936
	s_add_i32 m0, s10, 0x6000
	s_add_u32 s8, s4, vcc_lo
	s_addc_u32 s9, s5, vcc_hi
	global_load_lds_dwordx4 v238, s[8:9]
	s_waitcnt lgkmcnt(7)
	v_mfma_f32_16x16x32_bf16 v[62:65], v[150:153], v[170:173], v[62:65]
	v_mfma_f32_16x16x32_bf16 v[58:61], v[154:157], v[170:173], v[58:61]
	v_mfma_f32_16x16x32_bf16 v[54:57], v[158:161], v[170:173], v[54:57]
	v_mfma_f32_16x16x32_bf16 v[50:53], v[162:165], v[170:173], v[50:53]
	ds_read_b128 v[170:173], v178 offset:1024
	s_add_i32 m0, s10, 0xe000
	s_add_u32 s8, s6, 0x1708080
	s_addc_u32 s9, s7, 0
	global_load_lds_dwordx4 v239, s[8:9]
	s_waitcnt lgkmcnt(6)
	v_mfma_f32_16x16x32_bf16 v[46:49], v[150:153], v[174:177], v[46:49]
	v_mfma_f32_16x16x32_bf16 v[42:45], v[154:157], v[174:177], v[42:45]
	v_mfma_f32_16x16x32_bf16 v[38:41], v[158:161], v[174:177], v[38:41]
	v_mfma_f32_16x16x32_bf16 v[34:37], v[162:165], v[174:177], v[34:37]
	ds_read_b128 v[174:177], v178 offset:3072
	s_waitcnt lgkmcnt(5)
	v_mfma_f32_16x16x32_bf16 v[30:33], v[150:153], v[214:217], v[30:33]
	v_mfma_f32_16x16x32_bf16 v[26:29], v[154:157], v[214:217], v[26:29]
	v_mfma_f32_16x16x32_bf16 v[22:25], v[158:161], v[214:217], v[22:25]
	v_mfma_f32_16x16x32_bf16 v[18:21], v[162:165], v[214:217], v[18:21]
	ds_read_b128 v[214:217], v178 offset:5120
	s_waitcnt lgkmcnt(4)
	v_mfma_f32_16x16x32_bf16 v[14:17], v[150:153], v[218:221], v[14:17]
	v_mfma_f32_16x16x32_bf16 v[10:13], v[154:157], v[218:221], v[10:13]
	v_mfma_f32_16x16x32_bf16 v[6:9], v[158:161], v[218:221], v[6:9]
	v_mfma_f32_16x16x32_bf16 v[2:5], v[162:165], v[218:221], v[2:5]
	ds_read_b128 v[218:221], v178 offset:7168
	s_waitcnt lgkmcnt(3)
	v_mfma_f32_16x16x32_bf16 v[126:129], v[222:225], v[170:173], v[126:129]
	v_mfma_f32_16x16x32_bf16 v[122:125], v[226:229], v[170:173], v[122:125]
	v_mfma_f32_16x16x32_bf16 v[118:121], v[230:233], v[170:173], v[118:121]
	v_mfma_f32_16x16x32_bf16 v[114:117], v[234:237], v[170:173], v[114:117]
	ds_read_b128 v[170:173], v178 offset:9216
	s_waitcnt lgkmcnt(3)
; #define WAIT_V0() asm volatile("s_waitcnt vmcnt(0)" ::: "memory")
; #define SBAR() __builtin_amdgcn_sched_barrier(0)
; template <int EPI>
; DEVI void gemm_tile(const u16* __restrict__ Ab, long lda, const u16* __restrict__ Bb, long ldb, int K, const EpiArgs& e,
;                     bool have0 = false, const u16* __restrict__ nA = nullptr, const u16* __restrict__ nB = nullptr) {
;     ...
;   f32x4 acc[8][4];
; #pragma unroll
;   for (int m = 0; m < 8; ++m)
; #pragma unroll
;     for (int n = 0; n < 4; ++n) acc[m][n] = f32x4{0.f, 0.f, 0.f, 0.f};
;   const int nt = K / BK;
;   if (!have0) GLDS_STAGE(0, 0);
;   WAIT_V0(); __syncthreads();
;   for (int t = 0; t < nt; ++t) {
;     const int cur = t & 1;
;     if (t + 1 < nt) GLDS_STAGE(cur ^ 1, t + 1);
;     else if (nA) {
; #pragma unroll
;       for (int i = 0; i < GL; ++i) {
;         __builtin_amdgcn_global_load_lds((const unsigned*)(nA + (long)i * 64 * lda + toffA), (unsigned*)(g_shm + wid * 1024 + i * 8192), 16, 0, 0);
;         __builtin_amdgcn_global_load_lds((const unsigned*)(nB + (long)i * 64 * ldb + toffB), (unsigned*)(g_shm + TILE_B + wid * 1024 + i * 8192), 16, 0, 0);
;       }
;     }
;     const char* sb = g_shm + cur * STAGE_B;
; #pragma unroll
;     for (int ks = 0; ks < 2; ++ks) {
;       bf16x8 Bf[4];
; #pragma unroll
;       for (int n = 0; n < 4; ++n) Bf[n] = *(const bf16x8*)(sb + b_base + n * 2048 + ks * 1024);
; #pragma unroll
;       for (int mh = 0; mh < 2; ++mh) {
;         bf16x8 At[4];
; #pragma unroll
;         for (int m = 0; m < 4; ++m) At[m] = *(const bf16x8*)(sb + a_base + (mh * 4 + m) * 2048 + ks * 1024);
;         __builtin_amdgcn_s_setprio(1);
; #pragma unroll
;         for (int m = 0; m < 4; ++m)
; #pragma unroll
;           for (int n = 0; n < 4; ++n) acc[mh * 4 + m][n] = __builtin_amdgcn_mfma_f32_16x16x32_bf16(Bf[n], At[m], acc[mh * 4 + m][n], 0, 0, 0);
;         __builtin_amdgcn_s_setprio(0);
;       }
;       SBAR();
;     }
;     if (t + 1 < nt) { WAIT_V0(); __syncthreads(); }
;   }
	v_mfma_f32_16x16x32_bf16 v[110:113], v[222:225], v[174:177], v[110:113]
	v_mfma_f32_16x16x32_bf16 v[106:109], v[226:229], v[174:177], v[106:109]
	v_mfma_f32_16x16x32_bf16 v[102:105], v[230:233], v[174:177], v[102:105]
	v_mfma_f32_16x16x32_bf16 v[98:101], v[234:237], v[174:177], v[98:101]
	ds_read_b128 v[174:177], v178 offset:11264
	s_waitcnt lgkmcnt(3)
	v_mfma_f32_16x16x32_bf16 v[94:97], v[222:225], v[214:217], v[94:97]
	v_mfma_f32_16x16x32_bf16 v[90:93], v[226:229], v[214:217], v[90:93]
	v_mfma_f32_16x16x32_bf16 v[86:89], v[230:233], v[214:217], v[86:89]
	v_mfma_f32_16x16x32_bf16 v[82:85], v[234:237], v[214:217], v[82:85]
	ds_read_b128 v[214:217], v178 offset:13312
	s_waitcnt lgkmcnt(3)
	v_mfma_f32_16x16x32_bf16 v[78:81], v[222:225], v[218:221], v[78:81]
	v_mfma_f32_16x16x32_bf16 v[74:77], v[226:229], v[218:221], v[74:77]
	v_mfma_f32_16x16x32_bf16 v[70:73], v[230:233], v[218:221], v[70:73]
	v_mfma_f32_16x16x32_bf16 v[66:69], v[234:237], v[218:221], v[66:69]
	ds_read_b128 v[218:221], v178 offset:15360
	s_waitcnt lgkmcnt(3)
	v_mfma_f32_16x16x32_bf16 v[62:65], v[222:225], v[170:173], v[62:65]
	v_mfma_f32_16x16x32_bf16 v[58:61], v[226:229], v[170:173], v[58:61]
	v_mfma_f32_16x16x32_bf16 v[54:57], v[230:233], v[170:173], v[54:57]
	v_mfma_f32_16x16x32_bf16 v[50:53], v[234:237], v[170:173], v[50:53]
	s_waitcnt lgkmcnt(2)
	v_mfma_f32_16x16x32_bf16 v[46:49], v[222:225], v[174:177], v[46:49]
	v_mfma_f32_16x16x32_bf16 v[42:45], v[226:229], v[174:177], v[42:45]
	v_mfma_f32_16x16x32_bf16 v[38:41], v[230:233], v[174:177], v[38:41]
	v_mfma_f32_16x16x32_bf16 v[34:37], v[234:237], v[174:177], v[34:37]
	s_waitcnt lgkmcnt(0)
	s_waitcnt vmcnt(0)
	s_add_u32 s14, s14, 0x80
	s_addc_u32 s15, s15, 0
	s_add_i32 s3, s3, 0x10000
	s_cmpk_eq_i32 s14, 0x1580
	s_waitcnt vmcnt(0)
	s_barrier
	s_cselect_b32 s100, 1, 0
	s_and_b32 s22, s3, 0x10000
	v_or_b32_e32 v150, s22, v149
	v_add_u32_e32 v169, v150, v148
	v_or_b32_e32 v150, s22, v146
	v_add_u32_e32 v178, v150, v147
	ds_read_b128 v[150:153], v169 offset:32768
	ds_read_b128 v[154:157], v169 offset:34816
	ds_read_b128 v[158:161], v169 offset:36864
	ds_read_b128 v[162:165], v169 offset:38912
	ds_read_b128 v[170:173], v178
	ds_read_b128 v[174:177], v178 offset:2048
	s_add_u32 s4, s4, 0x80
	s_addc_u32 s5, s5, 0
	s_add_u32 s6, s6, 0x80
	s_addc_u32 s7, s7, 0
	s_cmp_eq_u32 s100, 1
	s_cbranch_scc1 .Lkl_184_s1
	v_readfirstlane_b32 s10, v143
	s_xor_b32 s8, s22, 0x10000
	s_nop 0
	s_add_i32 s10, s10, s8
	s_add_i32 m0, s10, 0x0
	s_add_u32 s8, s4, s24
	s_addc_u32 s9, s5, s25
	global_load_lds_dwordx4 v238, s[8:9]
.Lkl_184_s1:
	v_mfma_f32_16x16x32_bf16 v[30:33], v[222:225], v[214:217], v[30:33]
	v_mfma_f32_16x16x32_bf16 v[26:29], v[226:229], v[214:217], v[26:29]
	v_mfma_f32_16x16x32_bf16 v[22:25], v[230:233], v[214:217], v[22:25]
	v_mfma_f32_16x16x32_bf16 v[18:21], v[234:237], v[214:217], v[18:21]
	ds_read_b128 v[214:217], v178 offset:4096
	s_cmp_eq_u32 s100, 1
	s_cbranch_scc1 .Lkl_184_s2
	s_add_i32 m0, s10, 0x8000
	s_add_u32 s8, s6, 0x1600080
	s_addc_u32 s9, s7, 0
	global_load_lds_dwordx4 v239, s[8:9]
.Lkl_184_s2:
	v_mfma_f32_16x16x32_bf16 v[14:17], v[222:225], v[218:221], v[14:17]
	v_mfma_f32_16x16x32_bf16 v[10:13], v[226:229], v[218:221], v[10:13]
	v_mfma_f32_16x16x32_bf16 v[6:9], v[230:233], v[218:221], v[6:9]
	v_mfma_f32_16x16x32_bf16 v[2:5], v[234:237], v[218:221], v[2:5]
	ds_read_b128 v[218:221], v178 offset:6144
	s_cmp_eq_u32 s100, 1
	s_cbranch_scc1 .Lkl_184_s3
	s_add_i32 m0, s10, 0x2000
	s_add_u32 s8, s4, s26
	s_addc_u32 s9, s5, s27
	global_load_lds_dwordx4 v238, s[8:9]
.Lkl_184_s3:
	s_cmp_eq_u32 s100, 1
	s_cbranch_scc0 .Lkl_184
	s_nop 3
	v_readlane_b32 s4, v240, 0
	v_readlane_b32 s5, v240, 1
	v_readlane_b32 s6, v240, 2
	v_readlane_b32 s7, v240, 3
	v_readlane_b32 s8, v240, 4
	v_readlane_b32 s9, v240, 5
	v_readlane_b32 s10, v240, 6
	s_waitcnt lgkmcnt(0)
	s_xor_b32 s22, s22, 0x10000
	v_or_b32_e32 v150, s22, v149
	v_add_u32_e32 v169, v150, v148
	v_or_b32_e32 v150, s22, v146
	v_add_u32_e32 v178, v150, v147
	s_cmp_eq_u32 s100, 1
	s_cmp_eq_u64 s[8:9], 0
	s_cbranch_scc1 .LBB0_172
	v_readfirstlane_b32 s3, v143
	v_lshl_add_u64 v[134:135], s[8:9], 0, v[132:133]
	s_mov_b32 m0, s3
	v_readfirstlane_b32 s3, v145
	v_lshl_add_u64 v[132:133], s[12:13], 0, v[132:133]
	global_load_lds_dwordx4 v[134:135], off
	s_mov_b32 m0, s3
	s_mov_b64 s[12:13], 0x58000
	v_readfirstlane_b32 s3, v144
	global_load_lds_dwordx4 v[132:133], off
	v_lshl_add_u64 v[136:137], v[134:135], 0, s[12:13]
	s_mov_b32 m0, s3
	v_readfirstlane_b32 s3, v142
	global_load_lds_dwordx4 v[136:137], off
	v_lshl_add_u64 v[136:137], v[132:133], 0, s[12:13]
	s_mov_b32 m0, s3
	s_mov_b64 s[12:13], 0xb0000
	v_readfirstlane_b32 s3, v141
	global_load_lds_dwordx4 v[136:137], off
	v_lshl_add_u64 v[136:137], v[134:135], 0, s[12:13]
	s_mov_b32 m0, s3
	v_readfirstlane_b32 s3, v140
	global_load_lds_dwordx4 v[136:137], off
	v_lshl_add_u64 v[136:137], v[132:133], 0, s[12:13]
	s_mov_b32 m0, s3
	s_mov_b64 s[12:13], 0x108000
	v_readfirstlane_b32 s3, v139
	global_load_lds_dwordx4 v[136:137], off
	v_lshl_add_u64 v[134:135], v[134:135], 0, s[12:13]
	s_mov_b32 m0, s3
	v_readfirstlane_b32 s3, v138
	global_load_lds_dwordx4 v[134:135], off
	v_lshl_add_u64 v[132:133], v[132:133], 0, s[12:13]
	s_mov_b32 m0, s3
	s_nop 0
	global_load_lds_dwordx4 v[132:133], off
	s_branch .LBB0_172

; template <int EPI>
; DEVI void gemm_tile(const u16* __restrict__ Ab, long lda, const u16* __restrict__ Bb, long ldb, int K, const EpiArgs& e,
;                     bool have0 = false, const u16* __restrict__ nA = nullptr, const u16* __restrict__ nB = nullptr) {
;     ...
;   f32x4 acc[8][4];
; #pragma unroll
;   for (int m = 0; m < 8; ++m)
; #pragma unroll
;     for (int n = 0; n < 4; ++n) acc[m][n] = f32x4{0.f, 0.f, 0.f, 0.f};
;   const int nt = K / BK;
;   if (!have0) GLDS_STAGE(0, 0);
;   WAIT_V0(); __syncthreads();
;   for (int t = 0; t < nt; ++t) {
;     const int cur = t & 1;
;     if (t + 1 < nt) GLDS_STAGE(cur ^ 1, t + 1);
;     else if (nA) {
; #pragma unroll
;       for (int i = 0; i < GL; ++i) {
;         __builtin_amdgcn_global_load_lds((const unsigned*)(nA + (long)i * 64 * lda + toffA), (unsigned*)(g_shm + wid * 1024 + i * 8192), 16, 0, 0);
;         __builtin_amdgcn_global_load_lds((const unsigned*)(nB + (long)i * 64 * ldb + toffB), (unsigned*)(g_shm + TILE_B + wid * 1024 + i * 8192), 16, 0, 0);
;       }
;     }
;     const char* sb = g_shm + cur * STAGE_B;
; #pragma unroll
;     for (int ks = 0; ks < 2; ++ks) {
;       bf16x8 Bf[4];
; #pragma unroll
;       for (int n = 0; n < 4; ++n) Bf[n] = *(const bf16x8*)(sb + b_base + n * 2048 + ks * 1024);
; #pragma unroll
;       for (int mh = 0; mh < 2; ++mh) {
;         bf16x8 At[4];
; #pragma unroll
;         for (int m = 0; m < 4; ++m) At[m] = *(const bf16x8*)(sb + a_base + (mh * 4 + m) * 2048 + ks * 1024);
;         __builtin_amdgcn_s_setprio(1);
; #pragma unroll
;         for (int m = 0; m < 4; ++m)
; #pragma unroll
;           for (int n = 0; n < 4; ++n) acc[mh * 4 + m][n] = __builtin_amdgcn_mfma_f32_16x16x32_bf16(Bf[n], At[m], acc[mh * 4 + m][n], 0, 0, 0);
;         __builtin_amdgcn_s_setprio(0);
;       }
;       SBAR();
;     }
;     if (t + 1 < nt) { WAIT_V0(); __syncthreads(); }
;   }
; DEVI void mla_qkv_gemm(const Params& P, int i, int g) {
;   const u16* down = (const u16*)(P.ws + OFF_R + R_MLA_DOWN) + (long)g * TG * 768;
;   const u16* Wq = (const u16*)(P.ws + OFF_W) + WOFF_MLA + (long)i * W_MLA + W_MLA_DOWN;
;   const u16* Wkv = Wq + W_MLA_UQ;
;   u16* q = (u16*)(P.ws + OFF_R + R_MLA_Q); u16* kv = (u16*)(P.ws + OFF_R + R_MLA_KV);
;   const float* rc = (const float*)(P.ws + OFF_ROPE); const float* rs = rc + 8192 * 32;
;   const int nM = 128, nq = nM * 6, nkv = nM * 8;
;   bool have = false;
.LBB0_324:
	s_and_b32 s11, s2, 0x10000
	v_or_b32_e32 v154, s11, v153
	v_add_u32_e32 v169, v154, v152
	v_or_b32_e32 v154, s11, v150
	v_add_u32_e32 v178, v154, v151
	ds_read_b128 v[154:157], v169 offset:32768
	ds_read_b128 v[158:161], v169 offset:34816
	ds_read_b128 v[162:165], v169 offset:36864
	ds_read_b128 v[170:173], v169 offset:38912
	ds_read_b128 v[174:177], v178
	ds_read_b128 v[192:195], v178 offset:2048
	ds_read_b128 v[198:201], v178 offset:4096
	ds_read_b128 v[204:207], v178 offset:6144
	s_xor_b32 s23, s11, 0x10000
	v_add_u32_e32 v246, s23, v145
	s_lshl_b64 s[30:31], s[28:29], 1
	v_add_u32_e32 v242, 0x8000, v246
	v_readfirstlane_b32 s23, v246
	v_lshl_add_u64 v[238:239], v[136:137], 0, s[30:31]
	s_mov_b32 m0, s23
	v_readfirstlane_b32 s23, v242
	v_add_u32_e32 v244, 0x2000, v246
	v_lshl_add_u64 v[240:241], v[138:139], 0, s[30:31]
	global_load_lds_dwordx4 v[238:239], off
	s_mov_b32 m0, s23
	v_readfirstlane_b32 s23, v244
	v_add_u32_e32 v247, 0xa000, v246
	global_load_lds_dwordx4 v[240:241], off
	v_lshl_add_u64 v[242:243], v[238:239], 0, s[12:13]
	s_mov_b32 m0, s23
	v_readfirstlane_b32 s23, v247
	v_add_u32_e32 v247, 0x4000, v246
	global_load_lds_dwordx4 v[242:243], off
.Lkl_324:
	s_waitcnt lgkmcnt(3)
	v_mfma_f32_16x16x32_bf16 v[126:129], v[154:157], v[174:177], v[126:129]
	v_mfma_f32_16x16x32_bf16 v[122:125], v[158:161], v[174:177], v[122:125]
	v_mfma_f32_16x16x32_bf16 v[118:121], v[162:165], v[174:177], v[118:121]
	v_mfma_f32_16x16x32_bf16 v[114:117], v[170:173], v[174:177], v[114:117]
	ds_read_b128 v[174:177], v178 offset:8192
	ds_read_b128 v[222:225], v169 offset:33792
	v_lshl_add_u64 v[244:245], v[240:241], 0, s[6:7]
	s_mov_b32 m0, s23
	v_readfirstlane_b32 s23, v247
	global_load_lds_dwordx4 v[244:245], off
	s_waitcnt lgkmcnt(4)
	v_mfma_f32_16x16x32_bf16 v[110:113], v[154:157], v[192:195], v[110:113]
	v_mfma_f32_16x16x32_bf16 v[106:109], v[158:161], v[192:195], v[106:109]
	v_mfma_f32_16x16x32_bf16 v[102:105], v[162:165], v[192:195], v[102:105]
	v_mfma_f32_16x16x32_bf16 v[98:101], v[170:173], v[192:195], v[98:101]
	ds_read_b128 v[192:195], v178 offset:10240
	ds_read_b128 v[226:229], v169 offset:35840
	v_lshl_add_u64 v[242:243], v[242:243], 0, s[12:13]
	s_mov_b32 m0, s23
	v_lshl_add_u64 v[238:239], v[238:239], 0, s[14:15]
	global_load_lds_dwordx4 v[242:243], off
	s_waitcnt lgkmcnt(5)
	v_mfma_f32_16x16x32_bf16 v[94:97], v[154:157], v[198:201], v[94:97]
	v_mfma_f32_16x16x32_bf16 v[90:93], v[158:161], v[198:201], v[90:93]
	v_mfma_f32_16x16x32_bf16 v[86:89], v[162:165], v[198:201], v[86:89]
	v_mfma_f32_16x16x32_bf16 v[82:85], v[170:173], v[198:201], v[82:85]
	ds_read_b128 v[198:201], v178 offset:12288
	ds_read_b128 v[230:233], v169 offset:37888
	v_lshl_add_u64 v[242:243], v[244:245], 0, s[6:7]
	v_add_u32_e32 v244, 0xc000, v246
	s_add_i32 s3, s3, 1
	v_readfirstlane_b32 s23, v244
	s_mov_b32 m0, s23
	s_nop 0
	global_load_lds_dwordx4 v[242:243], off
	s_waitcnt lgkmcnt(6)
	v_mfma_f32_16x16x32_bf16 v[78:81], v[154:157], v[204:207], v[78:81]
	v_mfma_f32_16x16x32_bf16 v[74:77], v[158:161], v[204:207], v[74:77]
	v_mfma_f32_16x16x32_bf16 v[70:73], v[162:165], v[204:207], v[70:73]
	v_mfma_f32_16x16x32_bf16 v[66:69], v[170:173], v[204:207], v[66:69]
	ds_read_b128 v[204:207], v178 offset:14336
	ds_read_b128 v[234:237], v169 offset:39936
	v_add_u32_e32 v242, 0x6000, v246
	s_nop 0
	v_readfirstlane_b32 s23, v242
	s_mov_b32 m0, s23
	s_nop 0
	global_load_lds_dwordx4 v[238:239], off
	s_waitcnt lgkmcnt(7)
	v_mfma_f32_16x16x32_bf16 v[62:65], v[154:157], v[174:177], v[62:65]
	v_mfma_f32_16x16x32_bf16 v[58:61], v[158:161], v[174:177], v[58:61]
	v_mfma_f32_16x16x32_bf16 v[54:57], v[162:165], v[174:177], v[54:57]
	v_mfma_f32_16x16x32_bf16 v[50:53], v[170:173], v[174:177], v[50:53]
	ds_read_b128 v[174:177], v178 offset:1024
	v_lshl_add_u64 v[238:239], v[240:241], 0, s[16:17]
	v_add_u32_e32 v240, 0xe000, v246
	s_nop 0
	v_readfirstlane_b32 s23, v240
	s_mov_b32 m0, s23
	s_nop 0
	global_load_lds_dwordx4 v[238:239], off
	s_waitcnt lgkmcnt(6)
	v_mfma_f32_16x16x32_bf16 v[46:49], v[154:157], v[192:195], v[46:49]
	v_mfma_f32_16x16x32_bf16 v[42:45], v[158:161], v[192:195], v[42:45]
	v_mfma_f32_16x16x32_bf16 v[38:41], v[162:165], v[192:195], v[38:41]
	v_mfma_f32_16x16x32_bf16 v[34:37], v[170:173], v[192:195], v[34:37]
	ds_read_b128 v[192:195], v178 offset:3072
	s_waitcnt lgkmcnt(5)
	v_mfma_f32_16x16x32_bf16 v[30:33], v[154:157], v[198:201], v[30:33]
	v_mfma_f32_16x16x32_bf16 v[26:29], v[158:161], v[198:201], v[26:29]
	v_mfma_f32_16x16x32_bf16 v[22:25], v[162:165], v[198:201], v[22:25]
	v_mfma_f32_16x16x32_bf16 v[18:21], v[170:173], v[198:201], v[18:21]
	ds_read_b128 v[198:201], v178 offset:5120
	s_waitcnt lgkmcnt(4)
	v_mfma_f32_16x16x32_bf16 v[14:17], v[154:157], v[204:207], v[14:17]
	v_mfma_f32_16x16x32_bf16 v[10:13], v[158:161], v[204:207], v[10:13]
	v_mfma_f32_16x16x32_bf16 v[6:9], v[162:165], v[204:207], v[6:9]
	v_mfma_f32_16x16x32_bf16 v[2:5], v[170:173], v[204:207], v[2:5]
	ds_read_b128 v[204:207], v178 offset:7168
	s_waitcnt lgkmcnt(3)
	v_mfma_f32_16x16x32_bf16 v[126:129], v[222:225], v[174:177], v[126:129]
	v_mfma_f32_16x16x32_bf16 v[122:125], v[226:229], v[174:177], v[122:125]
	v_mfma_f32_16x16x32_bf16 v[118:121], v[230:233], v[174:177], v[118:121]
	v_mfma_f32_16x16x32_bf16 v[114:117], v[234:237], v[174:177], v[114:117]
	ds_read_b128 v[174:177], v178 offset:9216
	s_waitcnt lgkmcnt(3)
; #define WAIT_V0() asm volatile("s_waitcnt vmcnt(0)" ::: "memory")
; #define SBAR() __builtin_amdgcn_sched_barrier(0)
; template <int EPI>
; DEVI void gemm_tile(const u16* __restrict__ Ab, long lda, const u16* __restrict__ Bb, long ldb, int K, const EpiArgs& e,
;                     bool have0 = false, const u16* __restrict__ nA = nullptr, const u16* __restrict__ nB = nullptr) {
;     ...
;   f32x4 acc[8][4];
; #pragma unroll
;   for (int m = 0; m < 8; ++m)
; #pragma unroll
;     for (int n = 0; n < 4; ++n) acc[m][n] = f32x4{0.f, 0.f, 0.f, 0.f};
;   const int nt = K / BK;
;   if (!have0) GLDS_STAGE(0, 0);
;   WAIT_V0(); __syncthreads();
;   for (int t = 0; t < nt; ++t) {
;     const int cur = t & 1;
;     if (t + 1 < nt) GLDS_STAGE(cur ^ 1, t + 1);
;     else if (nA) {
; #pragma unroll
;       for (int i = 0; i < GL; ++i) {
;         __builtin_amdgcn_global_load_lds((const unsigned*)(nA + (long)i * 64 * lda + toffA), (unsigned*)(g_shm + wid * 1024 + i * 8192), 16, 0, 0);
;         __builtin_amdgcn_global_load_lds((const unsigned*)(nB + (long)i * 64 * ldb + toffB), (unsigned*)(g_shm + TILE_B + wid * 1024 + i * 8192), 16, 0, 0);
;       }
;     }
;     const char* sb = g_shm + cur * STAGE_B;
; #pragma unroll
;     for (int ks = 0; ks < 2; ++ks) {
;       bf16x8 Bf[4];
; #pragma unroll
;       for (int n = 0; n < 4; ++n) Bf[n] = *(const bf16x8*)(sb + b_base + n * 2048 + ks * 1024);
; #pragma unroll
;       for (int mh = 0; mh < 2; ++mh) {
;         bf16x8 At[4];
; #pragma unroll
;         for (int m = 0; m < 4; ++m) At[m] = *(const bf16x8*)(sb + a_base + (mh * 4 + m) * 2048 + ks * 1024);
;         __builtin_amdgcn_s_setprio(1);
; #pragma unroll
;         for (int m = 0; m < 4; ++m)
; #pragma unroll
;           for (int n = 0; n < 4; ++n) acc[mh * 4 + m][n] = __builtin_amdgcn_mfma_f32_16x16x32_bf16(Bf[n], At[m], acc[mh * 4 + m][n], 0, 0, 0);
;         __builtin_amdgcn_s_setprio(0);
;       }
;       SBAR();
;     }
;     if (t + 1 < nt) { WAIT_V0(); __syncthreads(); }
;   }
	v_mfma_f32_16x16x32_bf16 v[110:113], v[222:225], v[192:195], v[110:113]
	v_mfma_f32_16x16x32_bf16 v[106:109], v[226:229], v[192:195], v[106:109]
	v_mfma_f32_16x16x32_bf16 v[102:105], v[230:233], v[192:195], v[102:105]
	v_mfma_f32_16x16x32_bf16 v[98:101], v[234:237], v[192:195], v[98:101]
	ds_read_b128 v[192:195], v178 offset:11264
	s_waitcnt lgkmcnt(3)
	v_mfma_f32_16x16x32_bf16 v[94:97], v[222:225], v[198:201], v[94:97]
	v_mfma_f32_16x16x32_bf16 v[90:93], v[226:229], v[198:201], v[90:93]
	v_mfma_f32_16x16x32_bf16 v[86:89], v[230:233], v[198:201], v[86:89]
	v_mfma_f32_16x16x32_bf16 v[82:85], v[234:237], v[198:201], v[82:85]
	ds_read_b128 v[198:201], v178 offset:13312
	s_waitcnt lgkmcnt(3)
	v_mfma_f32_16x16x32_bf16 v[78:81], v[222:225], v[204:207], v[78:81]
	v_mfma_f32_16x16x32_bf16 v[74:77], v[226:229], v[204:207], v[74:77]
	v_mfma_f32_16x16x32_bf16 v[70:73], v[230:233], v[204:207], v[70:73]
	v_mfma_f32_16x16x32_bf16 v[66:69], v[234:237], v[204:207], v[66:69]
	ds_read_b128 v[204:207], v178 offset:15360
	s_waitcnt lgkmcnt(3)
	v_mfma_f32_16x16x32_bf16 v[62:65], v[222:225], v[174:177], v[62:65]
	v_mfma_f32_16x16x32_bf16 v[58:61], v[226:229], v[174:177], v[58:61]
	v_mfma_f32_16x16x32_bf16 v[54:57], v[230:233], v[174:177], v[54:57]
	v_mfma_f32_16x16x32_bf16 v[50:53], v[234:237], v[174:177], v[50:53]
	s_waitcnt lgkmcnt(2)
	v_mfma_f32_16x16x32_bf16 v[46:49], v[222:225], v[192:195], v[46:49]
	v_mfma_f32_16x16x32_bf16 v[42:45], v[226:229], v[192:195], v[42:45]
	v_mfma_f32_16x16x32_bf16 v[38:41], v[230:233], v[192:195], v[38:41]
	v_mfma_f32_16x16x32_bf16 v[34:37], v[234:237], v[192:195], v[34:37]
	s_waitcnt lgkmcnt(0)
	s_waitcnt vmcnt(0)
	s_add_i32 s2, s2, 0x10000
	s_add_i32 s28, s28, 64
	s_cmp_eq_u32 s70, s3
	s_waitcnt vmcnt(0)
	s_barrier
	s_cselect_b32 s100, 1, 0
	s_and_b32 s11, s2, 0x10000
	v_or_b32_e32 v154, s11, v153
	v_add_u32_e32 v169, v154, v152
	v_or_b32_e32 v154, s11, v150
	v_add_u32_e32 v178, v154, v151
	ds_read_b128 v[154:157], v169 offset:32768
	ds_read_b128 v[158:161], v169 offset:34816
	ds_read_b128 v[162:165], v169 offset:36864
	ds_read_b128 v[170:173], v169 offset:38912
	ds_read_b128 v[174:177], v178
	ds_read_b128 v[192:195], v178 offset:2048
	s_cmp_eq_u32 s100, 1
	s_cbranch_scc1 .Lkl_324_s1
	s_xor_b32 s23, s11, 0x10000
	v_add_u32_e32 v246, s23, v145
	s_lshl_b64 s[30:31], s[28:29], 1
	v_add_u32_e32 v242, 0x8000, v246
	v_readfirstlane_b32 s23, v246
	v_lshl_add_u64 v[238:239], v[136:137], 0, s[30:31]
	s_mov_b32 m0, s23
	v_readfirstlane_b32 s23, v242
	v_add_u32_e32 v244, 0x2000, v246
	v_lshl_add_u64 v[240:241], v[138:139], 0, s[30:31]
	global_load_lds_dwordx4 v[238:239], off
.Lkl_324_s1:
	v_mfma_f32_16x16x32_bf16 v[30:33], v[222:225], v[198:201], v[30:33]
	v_mfma_f32_16x16x32_bf16 v[26:29], v[226:229], v[198:201], v[26:29]
	v_mfma_f32_16x16x32_bf16 v[22:25], v[230:233], v[198:201], v[22:25]
	v_mfma_f32_16x16x32_bf16 v[18:21], v[234:237], v[198:201], v[18:21]
	ds_read_b128 v[198:201], v178 offset:4096
	s_cmp_eq_u32 s100, 1
	s_cbranch_scc1 .Lkl_324_s2
	s_mov_b32 m0, s23
	v_readfirstlane_b32 s23, v244
	v_add_u32_e32 v247, 0xa000, v246
	global_load_lds_dwordx4 v[240:241], off
.Lkl_324_s2:
	v_mfma_f32_16x16x32_bf16 v[14:17], v[222:225], v[204:207], v[14:17]
	v_mfma_f32_16x16x32_bf16 v[10:13], v[226:229], v[204:207], v[10:13]
	v_mfma_f32_16x16x32_bf16 v[6:9], v[230:233], v[204:207], v[6:9]
	v_mfma_f32_16x16x32_bf16 v[2:5], v[234:237], v[204:207], v[2:5]
	ds_read_b128 v[204:207], v178 offset:6144
	s_cmp_eq_u32 s100, 1
	s_cbranch_scc1 .Lkl_324_s3
	v_lshl_add_u64 v[242:243], v[238:239], 0, s[12:13]
	s_mov_b32 m0, s23
	v_readfirstlane_b32 s23, v247
	v_add_u32_e32 v247, 0x4000, v246
	global_load_lds_dwordx4 v[242:243], off
.Lkl_324_s3:
	s_cmp_eq_u32 s100, 1
	s_cbranch_scc0 .Lkl_324
	s_waitcnt lgkmcnt(0)
	s_xor_b32 s11, s11, 0x10000
	v_or_b32_e32 v154, s11, v153
	v_add_u32_e32 v169, v154, v152
	v_or_b32_e32 v154, s11, v150
	v_add_u32_e32 v178, v154, v151
	s_cmp_eq_u32 s100, 1
	s_cmp_eq_u64 s[20:21], 0
	s_cbranch_scc1 .LBB0_304
	v_readfirstlane_b32 s2, v145
	v_lshl_add_u64 v[132:133], v[132:133], 1, s[20:21]
	s_mov_b32 m0, s2
	v_readfirstlane_b32 s2, v149
	v_lshl_add_u64 v[134:135], v[134:135], 1, s[26:27]
	global_load_lds_dwordx4 v[132:133], off
	s_mov_b32 m0, s2
	v_readfirstlane_b32 s2, v148
	global_load_lds_dwordx4 v[134:135], off
	v_lshl_add_u64 v[136:137], v[132:133], 0, s[12:13]
	s_mov_b32 m0, s2
	v_readfirstlane_b32 s2, v147
	global_load_lds_dwordx4 v[136:137], off
	v_lshl_add_u64 v[138:139], v[134:135], 0, s[6:7]
	s_mov_b32 m0, s2
	v_readfirstlane_b32 s2, v146
	global_load_lds_dwordx4 v[138:139], off
	v_lshl_add_u64 v[136:137], v[136:137], 0, s[12:13]
	s_mov_b32 m0, s2
	v_readfirstlane_b32 s2, v144
	global_load_lds_dwordx4 v[136:137], off
	v_lshl_add_u64 v[136:137], v[138:139], 0, s[6:7]
	s_mov_b32 m0, s2
	v_readfirstlane_b32 s2, v143
	global_load_lds_dwordx4 v[136:137], off
	v_lshl_add_u64 v[132:133], v[132:133], 0, s[14:15]
	s_mov_b32 m0, s2
	v_readfirstlane_b32 s2, v142
	global_load_lds_dwordx4 v[132:133], off
	v_lshl_add_u64 v[132:133], v[134:135], 0, s[16:17]
	s_mov_b32 m0, s2
	s_nop 0
	global_load_lds_dwordx4 v[132:133], off
	s_branch .LBB0_304

; #define WAIT_V0() asm volatile("s_waitcnt vmcnt(0)" ::: "memory")
; #define SBAR() __builtin_amdgcn_sched_barrier(0)
; template <int EPI>
; DEVI void gemm_tile(const u16* __restrict__ Ab, long lda, const u16* __restrict__ Bb, long ldb, int K, const EpiArgs& e,
;                     bool have0 = false, const u16* __restrict__ nA = nullptr, const u16* __restrict__ nB = nullptr) {
;     ...
;   f32x4 acc[8][4];
; #pragma unroll
;   for (int m = 0; m < 8; ++m)
; #pragma unroll
;     for (int n = 0; n < 4; ++n) acc[m][n] = f32x4{0.f, 0.f, 0.f, 0.f};
;   const int nt = K / BK;
;   if (!have0) GLDS_STAGE(0, 0);
;   WAIT_V0(); __syncthreads();
;   for (int t = 0; t < nt; ++t) {
;     const int cur = t & 1;
;     if (t + 1 < nt) GLDS_STAGE(cur ^ 1, t + 1);
;     else if (nA) {
; #pragma unroll
;       for (int i = 0; i < GL; ++i) {
;         __builtin_amdgcn_global_load_lds((const unsigned*)(nA + (long)i * 64 * lda + toffA), (unsigned*)(g_shm + wid * 1024 + i * 8192), 16, 0, 0);
;         __builtin_amdgcn_global_load_lds((const unsigned*)(nB + (long)i * 64 * ldb + toffB), (unsigned*)(g_shm + TILE_B + wid * 1024 + i * 8192), 16, 0, 0);
;       }
;     }
;     const char* sb = g_shm + cur * STAGE_B;
; #pragma unroll
;     for (int ks = 0; ks < 2; ++ks) {
;       bf16x8 Bf[4];
; #pragma unroll
;       for (int n = 0; n < 4; ++n) Bf[n] = *(const bf16x8*)(sb + b_base + n * 2048 + ks * 1024);
; #pragma unroll
;       for (int mh = 0; mh < 2; ++mh) {
;         bf16x8 At[4];
; #pragma unroll
;         for (int m = 0; m < 4; ++m) At[m] = *(const bf16x8*)(sb + a_base + (mh * 4 + m) * 2048 + ks * 1024);
;         __builtin_amdgcn_s_setprio(1);
; #pragma unroll
;         for (int m = 0; m < 4; ++m)
; #pragma unroll
;           for (int n = 0; n < 4; ++n) acc[mh * 4 + m][n] = __builtin_amdgcn_mfma_f32_16x16x32_bf16(Bf[n], At[m], acc[mh * 4 + m][n], 0, 0, 0);
;         __builtin_amdgcn_s_setprio(0);
;       }
;       SBAR();
;     }
;     if (t + 1 < nt) { WAIT_V0(); __syncthreads(); }
;   }
.LBB0_359:
	s_and_b32 s3, s2, 0x10000
	v_or_b32_e32 v150, s3, v149
	v_add_u32_e32 v169, v150, v148
	v_or_b32_e32 v150, s3, v146
	v_add_u32_e32 v178, v150, v147
	ds_read_b128 v[150:153], v169 offset:32768
	ds_read_b128 v[154:157], v169 offset:34816
	ds_read_b128 v[158:161], v169 offset:36864
	ds_read_b128 v[162:165], v169 offset:38912
	ds_read_b128 v[170:173], v178
	ds_read_b128 v[174:177], v178 offset:2048
	ds_read_b128 v[192:195], v178 offset:4096
	ds_read_b128 v[198:201], v178 offset:6144
	v_writelane_b32 v240, s4, 0
	v_writelane_b32 v240, s5, 1
	v_writelane_b32 v240, s6, 2
	v_writelane_b32 v240, s7, 3
	v_writelane_b32 v240, s8, 4
	v_writelane_b32 v240, s9, 5
	v_writelane_b32 v240, s10, 6
	v_readfirstlane_b32 s4, v132
	v_readfirstlane_b32 s5, v133
	s_nop 1
	v_subrev_u32_e32 v238, s4, v132
	s_add_u32 s4, s4, s16
	s_addc_u32 s5, s5, s17
	v_readfirstlane_b32 s6, v134
	v_readfirstlane_b32 s7, v135
	s_nop 1
	v_subrev_u32_e32 v239, s6, v134
	s_add_u32 s6, s6, s16
	s_addc_u32 s7, s7, s17
	v_readfirstlane_b32 s10, v142
	s_xor_b32 s8, s3, 0x10000
	s_nop 0
	s_add_i32 s10, s10, s8
	s_add_i32 m0, s10, 0x0
	s_add_u32 s8, s4, 0x32500080
	s_addc_u32 s9, s5, 0
	global_load_lds_dwordx4 v238, s[8:9]
	s_add_i32 m0, s10, 0x8000
	s_add_u32 s8, s6, 0x99c0080
	s_addc_u32 s9, s7, 0
	global_load_lds_dwordx4 v239, s[8:9]
	s_add_i32 m0, s10, 0x2000
	s_add_u32 s8, s4, 0x32540080
	s_addc_u32 s9, s5, 0
	global_load_lds_dwordx4 v238, s[8:9]
.Lkl_359:
	s_waitcnt lgkmcnt(3)
	v_mfma_f32_16x16x32_bf16 v[126:129], v[150:153], v[170:173], v[126:129]
	v_mfma_f32_16x16x32_bf16 v[122:125], v[154:157], v[170:173], v[122:125]
	v_mfma_f32_16x16x32_bf16 v[118:121], v[158:161], v[170:173], v[118:121]
	v_mfma_f32_16x16x32_bf16 v[114:117], v[162:165], v[170:173], v[114:117]
	ds_read_b128 v[170:173], v178 offset:8192
	ds_read_b128 v[222:225], v169 offset:33792
	s_add_i32 m0, s10, 0xa000
	s_add_u32 s8, s6, 0x9a00080
	s_addc_u32 s9, s7, 0
	global_load_lds_dwordx4 v239, s[8:9]
	s_waitcnt lgkmcnt(4)
	v_mfma_f32_16x16x32_bf16 v[110:113], v[150:153], v[174:177], v[110:113]
	v_mfma_f32_16x16x32_bf16 v[106:109], v[154:157], v[174:177], v[106:109]
	v_mfma_f32_16x16x32_bf16 v[102:105], v[158:161], v[174:177], v[102:105]
	v_mfma_f32_16x16x32_bf16 v[98:101], v[162:165], v[174:177], v[98:101]
	ds_read_b128 v[174:177], v178 offset:10240
	ds_read_b128 v[226:229], v169 offset:35840
	s_add_i32 m0, s10, 0x4000
	s_add_u32 s8, s4, 0x32580080
	s_addc_u32 s9, s5, 0
	global_load_lds_dwordx4 v238, s[8:9]
	s_waitcnt lgkmcnt(5)
	v_mfma_f32_16x16x32_bf16 v[94:97], v[150:153], v[192:195], v[94:97]
	v_mfma_f32_16x16x32_bf16 v[90:93], v[154:157], v[192:195], v[90:93]
	v_mfma_f32_16x16x32_bf16 v[86:89], v[158:161], v[192:195], v[86:89]
	v_mfma_f32_16x16x32_bf16 v[82:85], v[162:165], v[192:195], v[82:85]
	ds_read_b128 v[192:195], v178 offset:12288
	ds_read_b128 v[230:233], v169 offset:37888
	s_add_i32 m0, s10, 0xc000
	s_add_u32 s8, s6, 0x9a40080
	s_addc_u32 s9, s7, 0
	global_load_lds_dwordx4 v239, s[8:9]
	s_waitcnt lgkmcnt(6)
	v_mfma_f32_16x16x32_bf16 v[78:81], v[150:153], v[198:201], v[78:81]
	v_mfma_f32_16x16x32_bf16 v[74:77], v[154:157], v[198:201], v[74:77]
	v_mfma_f32_16x16x32_bf16 v[70:73], v[158:161], v[198:201], v[70:73]
	v_mfma_f32_16x16x32_bf16 v[66:69], v[162:165], v[198:201], v[66:69]
	ds_read_b128 v[198:201], v178 offset:14336
	ds_read_b128 v[234:237], v169 offset:39936
	s_add_i32 m0, s10, 0x6000
	s_add_u32 s8, s4, 0x325c0080
	s_addc_u32 s9, s5, 0
	global_load_lds_dwordx4 v238, s[8:9]
	s_waitcnt lgkmcnt(7)
	v_mfma_f32_16x16x32_bf16 v[62:65], v[150:153], v[170:173], v[62:65]
	v_mfma_f32_16x16x32_bf16 v[58:61], v[154:157], v[170:173], v[58:61]
	v_mfma_f32_16x16x32_bf16 v[54:57], v[158:161], v[170:173], v[54:57]
	v_mfma_f32_16x16x32_bf16 v[50:53], v[162:165], v[170:173], v[50:53]
	ds_read_b128 v[170:173], v178 offset:1024
	s_add_i32 m0, s10, 0xe000
	s_add_u32 s8, s6, 0x9a80080
	s_addc_u32 s9, s7, 0
	global_load_lds_dwordx4 v239, s[8:9]
	s_waitcnt lgkmcnt(6)
	v_mfma_f32_16x16x32_bf16 v[46:49], v[150:153], v[174:177], v[46:49]
	v_mfma_f32_16x16x32_bf16 v[42:45], v[154:157], v[174:177], v[42:45]
	v_mfma_f32_16x16x32_bf16 v[38:41], v[158:161], v[174:177], v[38:41]
	v_mfma_f32_16x16x32_bf16 v[34:37], v[162:165], v[174:177], v[34:37]
	ds_read_b128 v[174:177], v178 offset:3072
	s_waitcnt lgkmcnt(5)
	v_mfma_f32_16x16x32_bf16 v[30:33], v[150:153], v[192:195], v[30:33]
	v_mfma_f32_16x16x32_bf16 v[26:29], v[154:157], v[192:195], v[26:29]
	v_mfma_f32_16x16x32_bf16 v[22:25], v[158:161], v[192:195], v[22:25]
	v_mfma_f32_16x16x32_bf16 v[18:21], v[162:165], v[192:195], v[18:21]
	ds_read_b128 v[192:195], v178 offset:5120
	s_waitcnt lgkmcnt(4)
	v_mfma_f32_16x16x32_bf16 v[14:17], v[150:153], v[198:201], v[14:17]
	v_mfma_f32_16x16x32_bf16 v[10:13], v[154:157], v[198:201], v[10:13]
	v_mfma_f32_16x16x32_bf16 v[6:9], v[158:161], v[198:201], v[6:9]
	v_mfma_f32_16x16x32_bf16 v[2:5], v[162:165], v[198:201], v[2:5]
	ds_read_b128 v[198:201], v178 offset:7168
	s_waitcnt lgkmcnt(3)
	v_mfma_f32_16x16x32_bf16 v[126:129], v[222:225], v[170:173], v[126:129]
	v_mfma_f32_16x16x32_bf16 v[122:125], v[226:229], v[170:173], v[122:125]
	v_mfma_f32_16x16x32_bf16 v[118:121], v[230:233], v[170:173], v[118:121]
	v_mfma_f32_16x16x32_bf16 v[114:117], v[234:237], v[170:173], v[114:117]
	ds_read_b128 v[170:173], v178 offset:9216
	s_waitcnt lgkmcnt(3)
; #define WAIT_V0() asm volatile("s_waitcnt vmcnt(0)" ::: "memory")
; #define SBAR() __builtin_amdgcn_sched_barrier(0)
; template <int EPI>
; DEVI void gemm_tile(const u16* __restrict__ Ab, long lda, const u16* __restrict__ Bb, long ldb, int K, const EpiArgs& e,
;                     bool have0 = false, const u16* __restrict__ nA = nullptr, const u16* __restrict__ nB = nullptr) {
;     ...
;   f32x4 acc[8][4];
; #pragma unroll
;   for (int m = 0; m < 8; ++m)
; #pragma unroll
;     for (int n = 0; n < 4; ++n) acc[m][n] = f32x4{0.f, 0.f, 0.f, 0.f};
;   const int nt = K / BK;
;   if (!have0) GLDS_STAGE(0, 0);
;   WAIT_V0(); __syncthreads();
;   for (int t = 0; t < nt; ++t) {
;     const int cur = t & 1;
;     if (t + 1 < nt) GLDS_STAGE(cur ^ 1, t + 1);
;     else if (nA) {
; #pragma unroll
;       for (int i = 0; i < GL; ++i) {
;         __builtin_amdgcn_global_load_lds((const unsigned*)(nA + (long)i * 64 * lda + toffA), (unsigned*)(g_shm + wid * 1024 + i * 8192), 16, 0, 0);
;         __builtin_amdgcn_global_load_lds((const unsigned*)(nB + (long)i * 64 * ldb + toffB), (unsigned*)(g_shm + TILE_B + wid * 1024 + i * 8192), 16, 0, 0);
;       }
;     }
;     const char* sb = g_shm + cur * STAGE_B;
; #pragma unroll
;     for (int ks = 0; ks < 2; ++ks) {
;       bf16x8 Bf[4];
; #pragma unroll
;       for (int n = 0; n < 4; ++n) Bf[n] = *(const bf16x8*)(sb + b_base + n * 2048 + ks * 1024);
; #pragma unroll
;       for (int mh = 0; mh < 2; ++mh) {
;         bf16x8 At[4];
; #pragma unroll
;         for (int m = 0; m < 4; ++m) At[m] = *(const bf16x8*)(sb + a_base + (mh * 4 + m) * 2048 + ks * 1024);
;         __builtin_amdgcn_s_setprio(1);
; #pragma unroll
;         for (int m = 0; m < 4; ++m)
; #pragma unroll
;           for (int n = 0; n < 4; ++n) acc[mh * 4 + m][n] = __builtin_amdgcn_mfma_f32_16x16x32_bf16(Bf[n], At[m], acc[mh * 4 + m][n], 0, 0, 0);
;         __builtin_amdgcn_s_setprio(0);
;       }
;       SBAR();
;     }
;     if (t + 1 < nt) { WAIT_V0(); __syncthreads(); }
;   }
	v_mfma_f32_16x16x32_bf16 v[110:113], v[222:225], v[174:177], v[110:113]
	v_mfma_f32_16x16x32_bf16 v[106:109], v[226:229], v[174:177], v[106:109]
	v_mfma_f32_16x16x32_bf16 v[102:105], v[230:233], v[174:177], v[102:105]
	v_mfma_f32_16x16x32_bf16 v[98:101], v[234:237], v[174:177], v[98:101]
	ds_read_b128 v[174:177], v178 offset:11264
	s_waitcnt lgkmcnt(3)
	v_mfma_f32_16x16x32_bf16 v[94:97], v[222:225], v[192:195], v[94:97]
	v_mfma_f32_16x16x32_bf16 v[90:93], v[226:229], v[192:195], v[90:93]
	v_mfma_f32_16x16x32_bf16 v[86:89], v[230:233], v[192:195], v[86:89]
	v_mfma_f32_16x16x32_bf16 v[82:85], v[234:237], v[192:195], v[82:85]
	ds_read_b128 v[192:195], v178 offset:13312
	s_waitcnt lgkmcnt(3)
	v_mfma_f32_16x16x32_bf16 v[78:81], v[222:225], v[198:201], v[78:81]
	v_mfma_f32_16x16x32_bf16 v[74:77], v[226:229], v[198:201], v[74:77]
	v_mfma_f32_16x16x32_bf16 v[70:73], v[230:233], v[198:201], v[70:73]
	v_mfma_f32_16x16x32_bf16 v[66:69], v[234:237], v[198:201], v[66:69]
	ds_read_b128 v[198:201], v178 offset:15360
	s_waitcnt lgkmcnt(3)
	v_mfma_f32_16x16x32_bf16 v[62:65], v[222:225], v[170:173], v[62:65]
	v_mfma_f32_16x16x32_bf16 v[58:61], v[226:229], v[170:173], v[58:61]
	v_mfma_f32_16x16x32_bf16 v[54:57], v[230:233], v[170:173], v[54:57]
	v_mfma_f32_16x16x32_bf16 v[50:53], v[234:237], v[170:173], v[50:53]
	s_waitcnt lgkmcnt(2)
	v_mfma_f32_16x16x32_bf16 v[46:49], v[222:225], v[174:177], v[46:49]
	v_mfma_f32_16x16x32_bf16 v[42:45], v[226:229], v[174:177], v[42:45]
	v_mfma_f32_16x16x32_bf16 v[38:41], v[230:233], v[174:177], v[38:41]
	v_mfma_f32_16x16x32_bf16 v[34:37], v[234:237], v[174:177], v[34:37]
	s_waitcnt lgkmcnt(0)
	s_waitcnt vmcnt(0)
	s_add_u32 s16, s16, 0x80
	s_addc_u32 s17, s17, 0
	s_add_i32 s2, s2, 0x10000
	s_cmpk_eq_i32 s16, 0xf80
	s_waitcnt vmcnt(0)
	s_barrier
	s_cselect_b32 s100, 1, 0
	s_and_b32 s3, s2, 0x10000
	v_or_b32_e32 v150, s3, v149
	v_add_u32_e32 v169, v150, v148
	v_or_b32_e32 v150, s3, v146
	v_add_u32_e32 v178, v150, v147
	ds_read_b128 v[150:153], v169 offset:32768
	ds_read_b128 v[154:157], v169 offset:34816
	ds_read_b128 v[158:161], v169 offset:36864
	ds_read_b128 v[162:165], v169 offset:38912
	ds_read_b128 v[170:173], v178
	ds_read_b128 v[174:177], v178 offset:2048
	s_add_u32 s4, s4, 0x80
	s_addc_u32 s5, s5, 0
	s_add_u32 s6, s6, 0x80
	s_addc_u32 s7, s7, 0
	s_cmp_eq_u32 s100, 1
	s_cbranch_scc1 .Lkl_359_s1
	v_readfirstlane_b32 s10, v142
	s_xor_b32 s8, s3, 0x10000
	s_nop 0
	s_add_i32 s10, s10, s8
	s_add_i32 m0, s10, 0x0
	s_add_u32 s8, s4, 0x32500080
	s_addc_u32 s9, s5, 0
	global_load_lds_dwordx4 v238, s[8:9]
.Lkl_359_s1:
	v_mfma_f32_16x16x32_bf16 v[30:33], v[222:225], v[192:195], v[30:33]
	v_mfma_f32_16x16x32_bf16 v[26:29], v[226:229], v[192:195], v[26:29]
	v_mfma_f32_16x16x32_bf16 v[22:25], v[230:233], v[192:195], v[22:25]
	v_mfma_f32_16x16x32_bf16 v[18:21], v[234:237], v[192:195], v[18:21]
	ds_read_b128 v[192:195], v178 offset:4096
	s_cmp_eq_u32 s100, 1
	s_cbranch_scc1 .Lkl_359_s2
	s_add_i32 m0, s10, 0x8000
	s_add_u32 s8, s6, 0x99c0080
	s_addc_u32 s9, s7, 0
	global_load_lds_dwordx4 v239, s[8:9]
.Lkl_359_s2:
	v_mfma_f32_16x16x32_bf16 v[14:17], v[222:225], v[198:201], v[14:17]
	v_mfma_f32_16x16x32_bf16 v[10:13], v[226:229], v[198:201], v[10:13]
	v_mfma_f32_16x16x32_bf16 v[6:9], v[230:233], v[198:201], v[6:9]
	v_mfma_f32_16x16x32_bf16 v[2:5], v[234:237], v[198:201], v[2:5]
	ds_read_b128 v[198:201], v178 offset:6144
	s_cmp_eq_u32 s100, 1
	s_cbranch_scc1 .Lkl_359_s3
	s_add_i32 m0, s10, 0x2000
	s_add_u32 s8, s4, 0x32540080
	s_addc_u32 s9, s5, 0
	global_load_lds_dwordx4 v238, s[8:9]
.Lkl_359_s3:
	s_cmp_eq_u32 s100, 1
	s_cbranch_scc0 .Lkl_359
	s_nop 3
	v_readlane_b32 s4, v240, 0
	v_readlane_b32 s5, v240, 1
	v_readlane_b32 s6, v240, 2
	v_readlane_b32 s7, v240, 3
	v_readlane_b32 s8, v240, 4
	v_readlane_b32 s9, v240, 5
	v_readlane_b32 s10, v240, 6
	s_waitcnt lgkmcnt(0)
	s_xor_b32 s3, s3, 0x10000
	v_or_b32_e32 v150, s3, v149
	v_add_u32_e32 v169, v150, v148
	v_or_b32_e32 v150, s3, v146
	v_add_u32_e32 v178, v150, v147
	s_cmp_eq_u32 s100, 1
	s_cmp_eq_u64 s[8:9], 0
	s_cbranch_scc1 .LBB0_362
	v_readfirstlane_b32 s2, v142
	v_lshl_add_u64 v[132:133], s[8:9], 0, v[130:131]
	s_mov_b32 m0, s2
	v_readfirstlane_b32 s2, v145
	v_lshl_add_u64 v[130:131], s[12:13], 0, v[130:131]
	global_load_lds_dwordx4 v[132:133], off
	s_mov_b32 m0, s2
	v_readfirstlane_b32 s2, v144
	global_load_lds_dwordx4 v[130:131], off
	v_lshl_add_u64 v[134:135], v[132:133], 0, s[96:97]
	s_mov_b32 m0, s2
	v_readfirstlane_b32 s2, v143
	global_load_lds_dwordx4 v[134:135], off
	v_lshl_add_u64 v[134:135], v[130:131], 0, s[96:97]
	s_mov_b32 m0, s2
	s_mov_b64 s[12:13], 0x80000
	v_readfirstlane_b32 s2, v141
	global_load_lds_dwordx4 v[134:135], off
	v_lshl_add_u64 v[134:135], v[132:133], 0, s[12:13]
	s_mov_b32 m0, s2
	v_readfirstlane_b32 s2, v140
	global_load_lds_dwordx4 v[134:135], off
	v_lshl_add_u64 v[134:135], v[130:131], 0, s[12:13]
	s_mov_b32 m0, s2
	s_mov_b64 s[12:13], 0xc0000
	v_readfirstlane_b32 s2, v139
	global_load_lds_dwordx4 v[134:135], off
	v_lshl_add_u64 v[132:133], v[132:133], 0, s[12:13]
	s_mov_b32 m0, s2
	v_readfirstlane_b32 s2, v138
	global_load_lds_dwordx4 v[132:133], off
	v_lshl_add_u64 v[130:131], v[130:131], 0, s[12:13]
	s_mov_b32 m0, s2
	s_nop 0
	global_load_lds_dwordx4 v[130:131], off

; #define WAIT_V0() asm volatile("s_waitcnt vmcnt(0)" ::: "memory")
; #define SBAR() __builtin_amdgcn_sched_barrier(0)
; template <int EPI>
; DEVI void gemm_tile(const u16* __restrict__ Ab, long lda, const u16* __restrict__ Bb, long ldb, int K, const EpiArgs& e,
;                     bool have0 = false, const u16* __restrict__ nA = nullptr, const u16* __restrict__ nB = nullptr) {
;     ...
;   f32x4 acc[8][4];
; #pragma unroll
;   for (int m = 0; m < 8; ++m)
; #pragma unroll
;     for (int n = 0; n < 4; ++n) acc[m][n] = f32x4{0.f, 0.f, 0.f, 0.f};
;   const int nt = K / BK;
;   if (!have0) GLDS_STAGE(0, 0);
;   WAIT_V0(); __syncthreads();
;   for (int t = 0; t < nt; ++t) {
;     const int cur = t & 1;
;     if (t + 1 < nt) GLDS_STAGE(cur ^ 1, t + 1);
;     else if (nA) {
; #pragma unroll
;       for (int i = 0; i < GL; ++i) {
;         __builtin_amdgcn_global_load_lds((const unsigned*)(nA + (long)i * 64 * lda + toffA), (unsigned*)(g_shm + wid * 1024 + i * 8192), 16, 0, 0);
;         __builtin_amdgcn_global_load_lds((const unsigned*)(nB + (long)i * 64 * ldb + toffB), (unsigned*)(g_shm + TILE_B + wid * 1024 + i * 8192), 16, 0, 0);
;       }
;     }
;     const char* sb = g_shm + cur * STAGE_B;
; #pragma unroll
;     for (int ks = 0; ks < 2; ++ks) {
;       bf16x8 Bf[4];
; #pragma unroll
;       for (int n = 0; n < 4; ++n) Bf[n] = *(const bf16x8*)(sb + b_base + n * 2048 + ks * 1024);
; #pragma unroll
;       for (int mh = 0; mh < 2; ++mh) {
;         bf16x8 At[4];
; #pragma unroll
;         for (int m = 0; m < 4; ++m) At[m] = *(const bf16x8*)(sb + a_base + (mh * 4 + m) * 2048 + ks * 1024);
;         __builtin_amdgcn_s_setprio(1);
; #pragma unroll
;         for (int m = 0; m < 4; ++m)
; #pragma unroll
;           for (int n = 0; n < 4; ++n) acc[mh * 4 + m][n] = __builtin_amdgcn_mfma_f32_16x16x32_bf16(Bf[n], At[m], acc[mh * 4 + m][n], 0, 0, 0);
;         __builtin_amdgcn_s_setprio(0);
;       }
;       SBAR();
;     }
;     if (t + 1 < nt) { WAIT_V0(); __syncthreads(); }
;   }
.LBB0_459:
	s_and_b32 s3, s2, 0x10000
	v_or_b32_e32 v150, s3, v149
	v_add_u32_e32 v169, v150, v148
	v_or_b32_e32 v150, s3, v146
	v_add_u32_e32 v178, v150, v147
	ds_read_b128 v[150:153], v169 offset:32768
	ds_read_b128 v[154:157], v169 offset:34816
	ds_read_b128 v[158:161], v169 offset:36864
	ds_read_b128 v[162:165], v169 offset:38912
	ds_read_b128 v[170:173], v178
	ds_read_b128 v[174:177], v178 offset:2048
	ds_read_b128 v[192:195], v178 offset:4096
	ds_read_b128 v[198:201], v178 offset:6144
	v_writelane_b32 v240, s4, 0
	v_writelane_b32 v240, s5, 1
	v_writelane_b32 v240, s6, 2
	v_writelane_b32 v240, s7, 3
	v_writelane_b32 v240, s8, 4
	v_writelane_b32 v240, s9, 5
	v_writelane_b32 v240, s10, 6
	v_readfirstlane_b32 s4, v132
	v_readfirstlane_b32 s5, v133
	s_nop 1
	v_subrev_u32_e32 v238, s4, v132
	s_add_u32 s4, s4, s14
	s_addc_u32 s5, s5, s15
	v_readfirstlane_b32 s6, v134
	v_readfirstlane_b32 s7, v135
	s_nop 1
	v_subrev_u32_e32 v239, s6, v134
	s_add_u32 s6, s6, s14
	s_addc_u32 s7, s7, s15
	v_readfirstlane_b32 s10, v142
	s_xor_b32 s8, s3, 0x10000
	s_nop 0
	s_add_i32 s10, s10, s8
	s_add_i32 m0, s10, 0x0
	s_add_u32 s8, s4, s30
	s_addc_u32 s9, s5, s31
	global_load_lds_dwordx4 v238, s[8:9]
	s_add_i32 m0, s10, 0x8000
	s_add_u32 s8, s6, s20
	s_addc_u32 s9, s7, s21
	global_load_lds_dwordx4 v239, s[8:9]
	s_add_i32 m0, s10, 0x2000
	s_add_u32 s8, s4, s40
	s_addc_u32 s9, s5, s41
	global_load_lds_dwordx4 v238, s[8:9]
.Lkl_459:
	s_waitcnt lgkmcnt(3)
	v_mfma_f32_16x16x32_bf16 v[126:129], v[150:153], v[170:173], v[126:129]
	v_mfma_f32_16x16x32_bf16 v[122:125], v[154:157], v[170:173], v[122:125]
	v_mfma_f32_16x16x32_bf16 v[118:121], v[158:161], v[170:173], v[118:121]
	v_mfma_f32_16x16x32_bf16 v[114:117], v[162:165], v[170:173], v[114:117]
	ds_read_b128 v[170:173], v178 offset:8192
	ds_read_b128 v[222:225], v169 offset:33792
	s_add_i32 m0, s10, 0xa000
	s_add_u32 s8, s6, s22
	s_addc_u32 s9, s7, s23
	global_load_lds_dwordx4 v239, s[8:9]
	s_waitcnt lgkmcnt(4)
	v_mfma_f32_16x16x32_bf16 v[110:113], v[150:153], v[174:177], v[110:113]
	v_mfma_f32_16x16x32_bf16 v[106:109], v[154:157], v[174:177], v[106:109]
	v_mfma_f32_16x16x32_bf16 v[102:105], v[158:161], v[174:177], v[102:105]
	v_mfma_f32_16x16x32_bf16 v[98:101], v[162:165], v[174:177], v[98:101]
	ds_read_b128 v[174:177], v178 offset:10240
	ds_read_b128 v[226:229], v169 offset:35840
	s_add_i32 m0, s10, 0x4000
	s_add_u32 s8, s4, s42
	s_addc_u32 s9, s5, s43
	global_load_lds_dwordx4 v238, s[8:9]
	s_waitcnt lgkmcnt(5)
	v_mfma_f32_16x16x32_bf16 v[94:97], v[150:153], v[192:195], v[94:97]
	v_mfma_f32_16x16x32_bf16 v[90:93], v[154:157], v[192:195], v[90:93]
	v_mfma_f32_16x16x32_bf16 v[86:89], v[158:161], v[192:195], v[86:89]
	v_mfma_f32_16x16x32_bf16 v[82:85], v[162:165], v[192:195], v[82:85]
	ds_read_b128 v[192:195], v178 offset:12288
	ds_read_b128 v[230:233], v169 offset:37888
	s_add_i32 m0, s10, 0xc000
	s_add_u32 s8, s6, s24
	s_addc_u32 s9, s7, s25
	global_load_lds_dwordx4 v239, s[8:9]
	s_waitcnt lgkmcnt(6)
	v_mfma_f32_16x16x32_bf16 v[78:81], v[150:153], v[198:201], v[78:81]
	v_mfma_f32_16x16x32_bf16 v[74:77], v[154:157], v[198:201], v[74:77]
	v_mfma_f32_16x16x32_bf16 v[70:73], v[158:161], v[198:201], v[70:73]
	v_mfma_f32_16x16x32_bf16 v[66:69], v[162:165], v[198:201], v[66:69]
	ds_read_b128 v[198:201], v178 offset:14336
	ds_read_b128 v[234:237], v169 offset:39936
	s_add_i32 m0, s10, 0x6000
	s_add_u32 s8, s4, s44
	s_addc_u32 s9, s5, s45
	global_load_lds_dwordx4 v238, s[8:9]
	s_waitcnt lgkmcnt(7)
	v_mfma_f32_16x16x32_bf16 v[62:65], v[150:153], v[170:173], v[62:65]
	v_mfma_f32_16x16x32_bf16 v[58:61], v[154:157], v[170:173], v[58:61]
	v_mfma_f32_16x16x32_bf16 v[54:57], v[158:161], v[170:173], v[54:57]
	v_mfma_f32_16x16x32_bf16 v[50:53], v[162:165], v[170:173], v[50:53]
	ds_read_b128 v[170:173], v178 offset:1024
	s_add_i32 m0, s10, 0xe000
	s_add_u32 s8, s6, s26
	s_addc_u32 s9, s7, s27
	global_load_lds_dwordx4 v239, s[8:9]
	s_waitcnt lgkmcnt(6)
	v_mfma_f32_16x16x32_bf16 v[46:49], v[150:153], v[174:177], v[46:49]
	v_mfma_f32_16x16x32_bf16 v[42:45], v[154:157], v[174:177], v[42:45]
	v_mfma_f32_16x16x32_bf16 v[38:41], v[158:161], v[174:177], v[38:41]
	v_mfma_f32_16x16x32_bf16 v[34:37], v[162:165], v[174:177], v[34:37]
	ds_read_b128 v[174:177], v178 offset:3072
	s_waitcnt lgkmcnt(5)
	v_mfma_f32_16x16x32_bf16 v[30:33], v[150:153], v[192:195], v[30:33]
	v_mfma_f32_16x16x32_bf16 v[26:29], v[154:157], v[192:195], v[26:29]
	v_mfma_f32_16x16x32_bf16 v[22:25], v[158:161], v[192:195], v[22:25]
	v_mfma_f32_16x16x32_bf16 v[18:21], v[162:165], v[192:195], v[18:21]
	ds_read_b128 v[192:195], v178 offset:5120
	s_waitcnt lgkmcnt(4)
	v_mfma_f32_16x16x32_bf16 v[14:17], v[150:153], v[198:201], v[14:17]
	v_mfma_f32_16x16x32_bf16 v[10:13], v[154:157], v[198:201], v[10:13]
	v_mfma_f32_16x16x32_bf16 v[6:9], v[158:161], v[198:201], v[6:9]
	v_mfma_f32_16x16x32_bf16 v[2:5], v[162:165], v[198:201], v[2:5]
	ds_read_b128 v[198:201], v178 offset:7168
	s_waitcnt lgkmcnt(3)
	v_mfma_f32_16x16x32_bf16 v[126:129], v[222:225], v[170:173], v[126:129]
	v_mfma_f32_16x16x32_bf16 v[122:125], v[226:229], v[170:173], v[122:125]
	v_mfma_f32_16x16x32_bf16 v[118:121], v[230:233], v[170:173], v[118:121]
	v_mfma_f32_16x16x32_bf16 v[114:117], v[234:237], v[170:173], v[114:117]
	ds_read_b128 v[170:173], v178 offset:9216
	s_waitcnt lgkmcnt(3)
; #define WAIT_V0() asm volatile("s_waitcnt vmcnt(0)" ::: "memory")
; #define SBAR() __builtin_amdgcn_sched_barrier(0)
; template <int EPI>
; DEVI void gemm_tile(const u16* __restrict__ Ab, long lda, const u16* __restrict__ Bb, long ldb, int K, const EpiArgs& e,
;                     bool have0 = false, const u16* __restrict__ nA = nullptr, const u16* __restrict__ nB = nullptr) {
;     ...
;   f32x4 acc[8][4];
; #pragma unroll
;   for (int m = 0; m < 8; ++m)
; #pragma unroll
;     for (int n = 0; n < 4; ++n) acc[m][n] = f32x4{0.f, 0.f, 0.f, 0.f};
;   const int nt = K / BK;
;   if (!have0) GLDS_STAGE(0, 0);
;   WAIT_V0(); __syncthreads();
;   for (int t = 0; t < nt; ++t) {
;     const int cur = t & 1;
;     if (t + 1 < nt) GLDS_STAGE(cur ^ 1, t + 1);
;     else if (nA) {
; #pragma unroll
;       for (int i = 0; i < GL; ++i) {
;         __builtin_amdgcn_global_load_lds((const unsigned*)(nA + (long)i * 64 * lda + toffA), (unsigned*)(g_shm + wid * 1024 + i * 8192), 16, 0, 0);
;         __builtin_amdgcn_global_load_lds((const unsigned*)(nB + (long)i * 64 * ldb + toffB), (unsigned*)(g_shm + TILE_B + wid * 1024 + i * 8192), 16, 0, 0);
;       }
;     }
;     const char* sb = g_shm + cur * STAGE_B;
; #pragma unroll
;     for (int ks = 0; ks < 2; ++ks) {
;       bf16x8 Bf[4];
; #pragma unroll
;       for (int n = 0; n < 4; ++n) Bf[n] = *(const bf16x8*)(sb + b_base + n * 2048 + ks * 1024);
; #pragma unroll
;       for (int mh = 0; mh < 2; ++mh) {
;         bf16x8 At[4];
; #pragma unroll
;         for (int m = 0; m < 4; ++m) At[m] = *(const bf16x8*)(sb + a_base + (mh * 4 + m) * 2048 + ks * 1024);
;         __builtin_amdgcn_s_setprio(1);
; #pragma unroll
;         for (int m = 0; m < 4; ++m)
; #pragma unroll
;           for (int n = 0; n < 4; ++n) acc[mh * 4 + m][n] = __builtin_amdgcn_mfma_f32_16x16x32_bf16(Bf[n], At[m], acc[mh * 4 + m][n], 0, 0, 0);
;         __builtin_amdgcn_s_setprio(0);
;       }
;       SBAR();
;     }
;     if (t + 1 < nt) { WAIT_V0(); __syncthreads(); }
;   }
	v_mfma_f32_16x16x32_bf16 v[110:113], v[222:225], v[174:177], v[110:113]
	v_mfma_f32_16x16x32_bf16 v[106:109], v[226:229], v[174:177], v[106:109]
	v_mfma_f32_16x16x32_bf16 v[102:105], v[230:233], v[174:177], v[102:105]
	v_mfma_f32_16x16x32_bf16 v[98:101], v[234:237], v[174:177], v[98:101]
	ds_read_b128 v[174:177], v178 offset:11264
	s_waitcnt lgkmcnt(3)
	v_mfma_f32_16x16x32_bf16 v[94:97], v[222:225], v[192:195], v[94:97]
	v_mfma_f32_16x16x32_bf16 v[90:93], v[226:229], v[192:195], v[90:93]
	v_mfma_f32_16x16x32_bf16 v[86:89], v[230:233], v[192:195], v[86:89]
	v_mfma_f32_16x16x32_bf16 v[82:85], v[234:237], v[192:195], v[82:85]
	ds_read_b128 v[192:195], v178 offset:13312
	s_waitcnt lgkmcnt(3)
	v_mfma_f32_16x16x32_bf16 v[78:81], v[222:225], v[198:201], v[78:81]
	v_mfma_f32_16x16x32_bf16 v[74:77], v[226:229], v[198:201], v[74:77]
	v_mfma_f32_16x16x32_bf16 v[70:73], v[230:233], v[198:201], v[70:73]
	v_mfma_f32_16x16x32_bf16 v[66:69], v[234:237], v[198:201], v[66:69]
	ds_read_b128 v[198:201], v178 offset:15360
	s_waitcnt lgkmcnt(3)
	v_mfma_f32_16x16x32_bf16 v[62:65], v[222:225], v[170:173], v[62:65]
	v_mfma_f32_16x16x32_bf16 v[58:61], v[226:229], v[170:173], v[58:61]
	v_mfma_f32_16x16x32_bf16 v[54:57], v[230:233], v[170:173], v[54:57]
	v_mfma_f32_16x16x32_bf16 v[50:53], v[234:237], v[170:173], v[50:53]
	s_waitcnt lgkmcnt(2)
	v_mfma_f32_16x16x32_bf16 v[46:49], v[222:225], v[174:177], v[46:49]
	v_mfma_f32_16x16x32_bf16 v[42:45], v[226:229], v[174:177], v[42:45]
	v_mfma_f32_16x16x32_bf16 v[38:41], v[230:233], v[174:177], v[38:41]
	v_mfma_f32_16x16x32_bf16 v[34:37], v[234:237], v[174:177], v[34:37]
	s_waitcnt lgkmcnt(0)
	s_waitcnt vmcnt(0)
	s_add_u32 s14, s14, 0x80
	s_addc_u32 s15, s15, 0
	s_add_i32 s2, s2, 0x10000
	s_cmpk_eq_i32 s14, 0x780
	s_waitcnt vmcnt(0)
	s_barrier
	s_cselect_b32 s100, 1, 0
	s_and_b32 s3, s2, 0x10000
	v_or_b32_e32 v150, s3, v149
	v_add_u32_e32 v169, v150, v148
	v_or_b32_e32 v150, s3, v146
	v_add_u32_e32 v178, v150, v147
	ds_read_b128 v[150:153], v169 offset:32768
	ds_read_b128 v[154:157], v169 offset:34816
	ds_read_b128 v[158:161], v169 offset:36864
	ds_read_b128 v[162:165], v169 offset:38912
	ds_read_b128 v[170:173], v178
	ds_read_b128 v[174:177], v178 offset:2048
	s_add_u32 s4, s4, 0x80
	s_addc_u32 s5, s5, 0
	s_add_u32 s6, s6, 0x80
	s_addc_u32 s7, s7, 0
	s_cmp_eq_u32 s100, 1
	s_cbranch_scc1 .Lkl_459_s1
	v_readfirstlane_b32 s10, v142
	s_xor_b32 s8, s3, 0x10000
	s_nop 0
	s_add_i32 s10, s10, s8
	s_add_i32 m0, s10, 0x0
	s_add_u32 s8, s4, s30
	s_addc_u32 s9, s5, s31
	global_load_lds_dwordx4 v238, s[8:9]
.Lkl_459_s1:
	v_mfma_f32_16x16x32_bf16 v[30:33], v[222:225], v[192:195], v[30:33]
	v_mfma_f32_16x16x32_bf16 v[26:29], v[226:229], v[192:195], v[26:29]
	v_mfma_f32_16x16x32_bf16 v[22:25], v[230:233], v[192:195], v[22:25]
	v_mfma_f32_16x16x32_bf16 v[18:21], v[234:237], v[192:195], v[18:21]
	ds_read_b128 v[192:195], v178 offset:4096
	s_cmp_eq_u32 s100, 1
	s_cbranch_scc1 .Lkl_459_s2
	s_add_i32 m0, s10, 0x8000
	s_add_u32 s8, s6, s20
	s_addc_u32 s9, s7, s21
	global_load_lds_dwordx4 v239, s[8:9]
.Lkl_459_s2:
	v_mfma_f32_16x16x32_bf16 v[14:17], v[222:225], v[198:201], v[14:17]
	v_mfma_f32_16x16x32_bf16 v[10:13], v[226:229], v[198:201], v[10:13]
	v_mfma_f32_16x16x32_bf16 v[6:9], v[230:233], v[198:201], v[6:9]
	v_mfma_f32_16x16x32_bf16 v[2:5], v[234:237], v[198:201], v[2:5]
	ds_read_b128 v[198:201], v178 offset:6144
	s_cmp_eq_u32 s100, 1
	s_cbranch_scc1 .Lkl_459_s3
	s_add_i32 m0, s10, 0x2000
	s_add_u32 s8, s4, s40
	s_addc_u32 s9, s5, s41
	global_load_lds_dwordx4 v238, s[8:9]
.Lkl_459_s3:
	s_cmp_eq_u32 s100, 1
	s_cbranch_scc0 .Lkl_459
	s_nop 3
	v_readlane_b32 s4, v240, 0
	v_readlane_b32 s5, v240, 1
	v_readlane_b32 s6, v240, 2
	v_readlane_b32 s7, v240, 3
	v_readlane_b32 s8, v240, 4
	v_readlane_b32 s9, v240, 5
	v_readlane_b32 s10, v240, 6
	s_waitcnt lgkmcnt(0)
	s_xor_b32 s3, s3, 0x10000
	v_or_b32_e32 v150, s3, v149
	v_add_u32_e32 v169, v150, v148
	v_or_b32_e32 v150, s3, v146
	v_add_u32_e32 v178, v150, v147
	s_cmp_eq_u32 s100, 1
	s_cmp_eq_u64 s[8:9], 0
	s_cbranch_scc1 .LBB0_447
	v_readfirstlane_b32 s2, v142
	v_lshl_add_u64 v[132:133], s[8:9], 0, v[130:131]
	s_mov_b32 m0, s2
	v_readfirstlane_b32 s2, v145
	v_lshl_add_u64 v[130:131], s[12:13], 0, v[130:131]
	global_load_lds_dwordx4 v[132:133], off
	s_mov_b32 m0, s2
	s_mov_b64 s[12:13], 0x20000
	v_readfirstlane_b32 s2, v144
	global_load_lds_dwordx4 v[130:131], off
	v_lshl_add_u64 v[134:135], v[132:133], 0, s[12:13]
	s_mov_b32 m0, s2
	v_readfirstlane_b32 s2, v143
	global_load_lds_dwordx4 v[134:135], off
	v_lshl_add_u64 v[134:135], v[130:131], 0, s[12:13]
	s_mov_b32 m0, s2
	v_readfirstlane_b32 s2, v141
	global_load_lds_dwordx4 v[134:135], off
	v_lshl_add_u64 v[134:135], v[132:133], 0, s[96:97]
	s_mov_b32 m0, s2
	v_readfirstlane_b32 s2, v140
	global_load_lds_dwordx4 v[134:135], off
	v_lshl_add_u64 v[134:135], v[130:131], 0, s[96:97]
	s_mov_b32 m0, s2
	s_mov_b64 s[12:13], 0x60000
	v_readfirstlane_b32 s2, v139
	global_load_lds_dwordx4 v[134:135], off
	v_lshl_add_u64 v[132:133], v[132:133], 0, s[12:13]
	s_mov_b32 m0, s2
	v_readfirstlane_b32 s2, v138
	global_load_lds_dwordx4 v[132:133], off
	v_lshl_add_u64 v[130:131], v[130:131], 0, s[12:13]
	s_mov_b32 m0, s2
	s_nop 0
	global_load_lds_dwordx4 v[130:131], off
	s_branch .LBB0_447

; #define WAIT_V0() asm volatile("s_waitcnt vmcnt(0)" ::: "memory")
; template <int EPI>
; DEVI void gemm_tile(const u16* __restrict__ Ab, long lda, const u16* __restrict__ Bb, long ldb, int K, const EpiArgs& e,
;                     bool have0 = false, const u16* __restrict__ nA = nullptr, const u16* __restrict__ nB = nullptr) {
;     ...
;   f32x4 acc[8][4];
; #pragma unroll
;   for (int m = 0; m < 8; ++m)
; #pragma unroll
;     for (int n = 0; n < 4; ++n) acc[m][n] = f32x4{0.f, 0.f, 0.f, 0.f};
;   const int nt = K / BK;
;   if (!have0) GLDS_STAGE(0, 0);
;   WAIT_V0(); __syncthreads();
;   for (int t = 0; t < nt; ++t) {
;     const int cur = t & 1;
;     if (t + 1 < nt) GLDS_STAGE(cur ^ 1, t + 1);
.LBB0_710:
	s_and_b32 s3, s2, 0x10000
	v_or_b32_e32 v150, s3, v149
	v_add_u32_e32 v169, v150, v148
	v_or_b32_e32 v150, s3, v146
	v_add_u32_e32 v178, v150, v147
	ds_read_b128 v[150:153], v169 offset:32768
	ds_read_b128 v[154:157], v169 offset:34816
	ds_read_b128 v[158:161], v169 offset:36864
	ds_read_b128 v[162:165], v169 offset:38912
	ds_read_b128 v[170:173], v178
	ds_read_b128 v[174:177], v178 offset:2048
	ds_read_b128 v[192:195], v178 offset:4096
	ds_read_b128 v[198:201], v178 offset:6144
	v_writelane_b32 v240, s4, 0
	v_writelane_b32 v240, s5, 1
	v_writelane_b32 v240, s6, 2
	v_writelane_b32 v240, s7, 3
	v_writelane_b32 v240, s8, 4
	v_writelane_b32 v240, s9, 5
	v_writelane_b32 v240, s10, 6
	v_readfirstlane_b32 s4, v132
	v_readfirstlane_b32 s5, v133
	s_nop 1
	v_subrev_u32_e32 v238, s4, v132
	s_add_u32 s4, s4, s14
	s_addc_u32 s5, s5, s15
	v_readfirstlane_b32 s6, v134
	v_readfirstlane_b32 s7, v135
	s_nop 1
	v_subrev_u32_e32 v239, s6, v134
	s_add_u32 s6, s6, s14
	s_addc_u32 s7, s7, s15
	v_readfirstlane_b32 s10, v142
	s_xor_b32 s8, s3, 0x10000
	s_nop 0
	s_add_i32 s10, s10, s8
	s_add_i32 m0, s10, 0x0
	s_add_u32 s8, s4, 0xe500080
	s_addc_u32 s9, s5, 0
	global_load_lds_dwordx4 v238, s[8:9]
	s_add_i32 m0, s10, 0x8000
	s_add_u32 s8, s6, s20
	s_addc_u32 s9, s7, s21
	global_load_lds_dwordx4 v239, s[8:9]
	s_add_i32 m0, s10, 0x2000
	s_add_u32 s8, s4, 0xe520080
	s_addc_u32 s9, s5, 0
	global_load_lds_dwordx4 v238, s[8:9]
; #define WAIT_V0() asm volatile("s_waitcnt vmcnt(0)" ::: "memory")
; #define SBAR() __builtin_amdgcn_sched_barrier(0)
; template <int EPI>
; DEVI void gemm_tile(const u16* __restrict__ Ab, long lda, const u16* __restrict__ Bb, long ldb, int K, const EpiArgs& e,
;                     bool have0 = false, const u16* __restrict__ nA = nullptr, const u16* __restrict__ nB = nullptr) {
;     ...
;   for (int t = 0; t < nt; ++t) {
;     const int cur = t & 1;
;     if (t + 1 < nt) GLDS_STAGE(cur ^ 1, t + 1);
;     else if (nA) {
; #pragma unroll
;       for (int i = 0; i < GL; ++i) {
;         __builtin_amdgcn_global_load_lds((const unsigned*)(nA + (long)i * 64 * lda + toffA), (unsigned*)(g_shm + wid * 1024 + i * 8192), 16, 0, 0);
;         __builtin_amdgcn_global_load_lds((const unsigned*)(nB + (long)i * 64 * ldb + toffB), (unsigned*)(g_shm + TILE_B + wid * 1024 + i * 8192), 16, 0, 0);
;       }
;     }
;     const char* sb = g_shm + cur * STAGE_B;
; #pragma unroll
;     for (int ks = 0; ks < 2; ++ks) {
;       bf16x8 Bf[4];
; #pragma unroll
;       for (int n = 0; n < 4; ++n) Bf[n] = *(const bf16x8*)(sb + b_base + n * 2048 + ks * 1024);
; #pragma unroll
;       for (int mh = 0; mh < 2; ++mh) {
;         bf16x8 At[4];
; #pragma unroll
;         for (int m = 0; m < 4; ++m) At[m] = *(const bf16x8*)(sb + a_base + (mh * 4 + m) * 2048 + ks * 1024);
;         __builtin_amdgcn_s_setprio(1);
; #pragma unroll
;         for (int m = 0; m < 4; ++m)
; #pragma unroll
;           for (int n = 0; n < 4; ++n) acc[mh * 4 + m][n] = __builtin_amdgcn_mfma_f32_16x16x32_bf16(Bf[n], At[m], acc[mh * 4 + m][n], 0, 0, 0);
;         __builtin_amdgcn_s_setprio(0);
;       }
;       SBAR();
;     }
;     if (t + 1 < nt) { WAIT_V0(); __syncthreads(); }
;   }
.Lkl_710:
	s_waitcnt lgkmcnt(3)
	v_mfma_f32_16x16x32_bf16 v[126:129], v[150:153], v[170:173], v[126:129]
	v_mfma_f32_16x16x32_bf16 v[122:125], v[154:157], v[170:173], v[122:125]
	v_mfma_f32_16x16x32_bf16 v[118:121], v[158:161], v[170:173], v[118:121]
	v_mfma_f32_16x16x32_bf16 v[114:117], v[162:165], v[170:173], v[114:117]
	ds_read_b128 v[170:173], v178 offset:8192
	ds_read_b128 v[222:225], v169 offset:33792
	s_add_i32 m0, s10, 0xa000
	s_add_u32 s8, s6, s22
	s_addc_u32 s9, s7, s23
	global_load_lds_dwordx4 v239, s[8:9]
	s_waitcnt lgkmcnt(4)
	v_mfma_f32_16x16x32_bf16 v[110:113], v[150:153], v[174:177], v[110:113]
	v_mfma_f32_16x16x32_bf16 v[106:109], v[154:157], v[174:177], v[106:109]
	v_mfma_f32_16x16x32_bf16 v[102:105], v[158:161], v[174:177], v[102:105]
	v_mfma_f32_16x16x32_bf16 v[98:101], v[162:165], v[174:177], v[98:101]
	ds_read_b128 v[174:177], v178 offset:10240
	ds_read_b128 v[226:229], v169 offset:35840
	s_add_i32 m0, s10, 0x4000
	s_add_u32 s8, s4, 0xe540080
	s_addc_u32 s9, s5, 0
	global_load_lds_dwordx4 v238, s[8:9]
	s_waitcnt lgkmcnt(5)
	v_mfma_f32_16x16x32_bf16 v[94:97], v[150:153], v[192:195], v[94:97]
	v_mfma_f32_16x16x32_bf16 v[90:93], v[154:157], v[192:195], v[90:93]
	v_mfma_f32_16x16x32_bf16 v[86:89], v[158:161], v[192:195], v[86:89]
	v_mfma_f32_16x16x32_bf16 v[82:85], v[162:165], v[192:195], v[82:85]
	ds_read_b128 v[192:195], v178 offset:12288
	ds_read_b128 v[230:233], v169 offset:37888
	s_add_i32 m0, s10, 0xc000
	s_add_u32 s8, s6, s24
	s_addc_u32 s9, s7, s25
	global_load_lds_dwordx4 v239, s[8:9]
	s_waitcnt lgkmcnt(6)
	v_mfma_f32_16x16x32_bf16 v[78:81], v[150:153], v[198:201], v[78:81]
	v_mfma_f32_16x16x32_bf16 v[74:77], v[154:157], v[198:201], v[74:77]
	v_mfma_f32_16x16x32_bf16 v[70:73], v[158:161], v[198:201], v[70:73]
	v_mfma_f32_16x16x32_bf16 v[66:69], v[162:165], v[198:201], v[66:69]
	ds_read_b128 v[198:201], v178 offset:14336
	ds_read_b128 v[234:237], v169 offset:39936
	s_add_i32 m0, s10, 0x6000
	s_add_u32 s8, s4, 0xe560080
	s_addc_u32 s9, s5, 0
	global_load_lds_dwordx4 v238, s[8:9]
	s_waitcnt lgkmcnt(7)
	v_mfma_f32_16x16x32_bf16 v[62:65], v[150:153], v[170:173], v[62:65]
	v_mfma_f32_16x16x32_bf16 v[58:61], v[154:157], v[170:173], v[58:61]
	v_mfma_f32_16x16x32_bf16 v[54:57], v[158:161], v[170:173], v[54:57]
	v_mfma_f32_16x16x32_bf16 v[50:53], v[162:165], v[170:173], v[50:53]
	ds_read_b128 v[170:173], v178 offset:1024
	s_add_i32 m0, s10, 0xe000
	s_add_u32 s8, s6, s26
	s_addc_u32 s9, s7, s27
	global_load_lds_dwordx4 v239, s[8:9]
	s_waitcnt lgkmcnt(6)
	v_mfma_f32_16x16x32_bf16 v[46:49], v[150:153], v[174:177], v[46:49]
	v_mfma_f32_16x16x32_bf16 v[42:45], v[154:157], v[174:177], v[42:45]
	v_mfma_f32_16x16x32_bf16 v[38:41], v[158:161], v[174:177], v[38:41]
	v_mfma_f32_16x16x32_bf16 v[34:37], v[162:165], v[174:177], v[34:37]
	ds_read_b128 v[174:177], v178 offset:3072
	s_waitcnt lgkmcnt(5)
	v_mfma_f32_16x16x32_bf16 v[30:33], v[150:153], v[192:195], v[30:33]
	v_mfma_f32_16x16x32_bf16 v[26:29], v[154:157], v[192:195], v[26:29]
	v_mfma_f32_16x16x32_bf16 v[22:25], v[158:161], v[192:195], v[22:25]
	v_mfma_f32_16x16x32_bf16 v[18:21], v[162:165], v[192:195], v[18:21]
	ds_read_b128 v[192:195], v178 offset:5120
	s_waitcnt lgkmcnt(4)
	v_mfma_f32_16x16x32_bf16 v[14:17], v[150:153], v[198:201], v[14:17]
	v_mfma_f32_16x16x32_bf16 v[10:13], v[154:157], v[198:201], v[10:13]
	v_mfma_f32_16x16x32_bf16 v[6:9], v[158:161], v[198:201], v[6:9]
	v_mfma_f32_16x16x32_bf16 v[2:5], v[162:165], v[198:201], v[2:5]
	ds_read_b128 v[198:201], v178 offset:7168
	s_waitcnt lgkmcnt(3)
	v_mfma_f32_16x16x32_bf16 v[126:129], v[222:225], v[170:173], v[126:129]
	v_mfma_f32_16x16x32_bf16 v[122:125], v[226:229], v[170:173], v[122:125]
	v_mfma_f32_16x16x32_bf16 v[118:121], v[230:233], v[170:173], v[118:121]
	v_mfma_f32_16x16x32_bf16 v[114:117], v[234:237], v[170:173], v[114:117]
	ds_read_b128 v[170:173], v178 offset:9216
	s_waitcnt lgkmcnt(3)
	v_mfma_f32_16x16x32_bf16 v[110:113], v[222:225], v[174:177], v[110:113]
	v_mfma_f32_16x16x32_bf16 v[106:109], v[226:229], v[174:177], v[106:109]
	v_mfma_f32_16x16x32_bf16 v[102:105], v[230:233], v[174:177], v[102:105]
	v_mfma_f32_16x16x32_bf16 v[98:101], v[234:237], v[174:177], v[98:101]
	ds_read_b128 v[174:177], v178 offset:11264
	s_waitcnt lgkmcnt(3)
	v_mfma_f32_16x16x32_bf16 v[94:97], v[222:225], v[192:195], v[94:97]
	v_mfma_f32_16x16x32_bf16 v[90:93], v[226:229], v[192:195], v[90:93]
	v_mfma_f32_16x16x32_bf16 v[86:89], v[230:233], v[192:195], v[86:89]
	v_mfma_f32_16x16x32_bf16 v[82:85], v[234:237], v[192:195], v[82:85]
	ds_read_b128 v[192:195], v178 offset:13312
	s_waitcnt lgkmcnt(3)
	v_mfma_f32_16x16x32_bf16 v[78:81], v[222:225], v[198:201], v[78:81]
	v_mfma_f32_16x16x32_bf16 v[74:77], v[226:229], v[198:201], v[74:77]
	v_mfma_f32_16x16x32_bf16 v[70:73], v[230:233], v[198:201], v[70:73]
	v_mfma_f32_16x16x32_bf16 v[66:69], v[234:237], v[198:201], v[66:69]
	ds_read_b128 v[198:201], v178 offset:15360
	s_waitcnt lgkmcnt(3)
	v_mfma_f32_16x16x32_bf16 v[62:65], v[222:225], v[170:173], v[62:65]
	v_mfma_f32_16x16x32_bf16 v[58:61], v[226:229], v[170:173], v[58:61]
	v_mfma_f32_16x16x32_bf16 v[54:57], v[230:233], v[170:173], v[54:57]
	v_mfma_f32_16x16x32_bf16 v[50:53], v[234:237], v[170:173], v[50:53]
	s_waitcnt lgkmcnt(2)
	v_mfma_f32_16x16x32_bf16 v[46:49], v[222:225], v[174:177], v[46:49]
	v_mfma_f32_16x16x32_bf16 v[42:45], v[226:229], v[174:177], v[42:45]
	v_mfma_f32_16x16x32_bf16 v[38:41], v[230:233], v[174:177], v[38:41]
	v_mfma_f32_16x16x32_bf16 v[34:37], v[234:237], v[174:177], v[34:37]
	s_waitcnt lgkmcnt(0)
	s_waitcnt vmcnt(0)
	s_add_u32 s14, s14, 0x80
	s_addc_u32 s15, s15, 0
	s_add_i32 s2, s2, 0x10000
	s_cmpk_eq_i32 s14, 0x780
	s_waitcnt vmcnt(0)
	s_barrier
	s_cselect_b32 s100, 1, 0
	s_and_b32 s3, s2, 0x10000
	v_or_b32_e32 v150, s3, v149
	v_add_u32_e32 v169, v150, v148
	v_or_b32_e32 v150, s3, v146
	v_add_u32_e32 v178, v150, v147
	ds_read_b128 v[150:153], v169 offset:32768
	ds_read_b128 v[154:157], v169 offset:34816
	ds_read_b128 v[158:161], v169 offset:36864
	ds_read_b128 v[162:165], v169 offset:38912
	ds_read_b128 v[170:173], v178
	ds_read_b128 v[174:177], v178 offset:2048
	s_add_u32 s4, s4, 0x80
	s_addc_u32 s5, s5, 0
	s_add_u32 s6, s6, 0x80
	s_addc_u32 s7, s7, 0
	s_cmp_eq_u32 s100, 1
	s_cbranch_scc1 .Lkl_710_s1
	v_readfirstlane_b32 s10, v142
	s_xor_b32 s8, s3, 0x10000
	s_nop 0
	s_add_i32 s10, s10, s8
	s_add_i32 m0, s10, 0x0
	s_add_u32 s8, s4, 0xe500080
	s_addc_u32 s9, s5, 0
	global_load_lds_dwordx4 v238, s[8:9]

; #define WAIT_V0() asm volatile("s_waitcnt vmcnt(0)" ::: "memory")
; #define SBAR() __builtin_amdgcn_sched_barrier(0)
; template <int EPI>
; DEVI void gemm_tile(const u16* __restrict__ Ab, long lda, const u16* __restrict__ Bb, long ldb, int K, const EpiArgs& e,
;                     bool have0 = false, const u16* __restrict__ nA = nullptr, const u16* __restrict__ nB = nullptr) {
;     ...
;   for (int t = 0; t < nt; ++t) {
;     const int cur = t & 1;
;     if (t + 1 < nt) GLDS_STAGE(cur ^ 1, t + 1);
;     else if (nA) {
; #pragma unroll
;       for (int i = 0; i < GL; ++i) {
;         __builtin_amdgcn_global_load_lds((const unsigned*)(nA + (long)i * 64 * lda + toffA), (unsigned*)(g_shm + wid * 1024 + i * 8192), 16, 0, 0);
;         __builtin_amdgcn_global_load_lds((const unsigned*)(nB + (long)i * 64 * ldb + toffB), (unsigned*)(g_shm + TILE_B + wid * 1024 + i * 8192), 16, 0, 0);
;       }
;     }
;     const char* sb = g_shm + cur * STAGE_B;
; #pragma unroll
;     for (int ks = 0; ks < 2; ++ks) {
;       bf16x8 Bf[4];
; #pragma unroll
;       for (int n = 0; n < 4; ++n) Bf[n] = *(const bf16x8*)(sb + b_base + n * 2048 + ks * 1024);
; #pragma unroll
;       for (int mh = 0; mh < 2; ++mh) {
;         bf16x8 At[4];
; #pragma unroll
;         for (int m = 0; m < 4; ++m) At[m] = *(const bf16x8*)(sb + a_base + (mh * 4 + m) * 2048 + ks * 1024);
;         __builtin_amdgcn_s_setprio(1);
; #pragma unroll
;         for (int m = 0; m < 4; ++m)
; #pragma unroll
;           for (int n = 0; n < 4; ++n) acc[mh * 4 + m][n] = __builtin_amdgcn_mfma_f32_16x16x32_bf16(Bf[n], At[m], acc[mh * 4 + m][n], 0, 0, 0);
;         __builtin_amdgcn_s_setprio(0);
;       }
;       SBAR();
;     }
;     if (t + 1 < nt) { WAIT_V0(); __syncthreads(); }
;   }
.Lkl_710_s2:
	v_mfma_f32_16x16x32_bf16 v[14:17], v[222:225], v[198:201], v[14:17]
	v_mfma_f32_16x16x32_bf16 v[10:13], v[226:229], v[198:201], v[10:13]
	v_mfma_f32_16x16x32_bf16 v[6:9], v[230:233], v[198:201], v[6:9]
	v_mfma_f32_16x16x32_bf16 v[2:5], v[234:237], v[198:201], v[2:5]
	ds_read_b128 v[198:201], v178 offset:6144
	s_cmp_eq_u32 s100, 1
	s_cbranch_scc1 .Lkl_710_s3
	s_add_i32 m0, s10, 0x2000
	s_add_u32 s8, s4, 0xe520080
	s_addc_u32 s9, s5, 0
	global_load_lds_dwordx4 v238, s[8:9]
.Lkl_710_s3:
	s_cmp_eq_u32 s100, 1
	s_cbranch_scc0 .Lkl_710
	s_nop 3
	v_readlane_b32 s4, v240, 0
	v_readlane_b32 s5, v240, 1
	v_readlane_b32 s6, v240, 2
	v_readlane_b32 s7, v240, 3
	v_readlane_b32 s8, v240, 4
	v_readlane_b32 s9, v240, 5
	v_readlane_b32 s10, v240, 6
	s_waitcnt lgkmcnt(0)
	s_xor_b32 s3, s3, 0x10000
	v_or_b32_e32 v150, s3, v149
	v_add_u32_e32 v169, v150, v148
	v_or_b32_e32 v150, s3, v146
	v_add_u32_e32 v178, v150, v147
	s_cmp_eq_u32 s100, 1
	s_cmp_eq_u64 s[8:9], 0
	s_cbranch_scc1 .LBB0_698
	v_readfirstlane_b32 s2, v142
	v_lshl_add_u64 v[132:133], s[8:9], 0, v[130:131]
	s_mov_b32 m0, s2
	v_readfirstlane_b32 s2, v145
	v_lshl_add_u64 v[130:131], s[10:11], 0, v[130:131]
	global_load_lds_dwordx4 v[132:133], off
	s_mov_b32 m0, s2
	s_mov_b64 s[10:11], 0x20000
	v_readfirstlane_b32 s2, v144
	global_load_lds_dwordx4 v[130:131], off
	v_lshl_add_u64 v[134:135], v[132:133], 0, s[10:11]
	s_mov_b32 m0, s2
	v_readfirstlane_b32 s2, v143
	global_load_lds_dwordx4 v[134:135], off
	v_lshl_add_u64 v[134:135], v[130:131], 0, s[10:11]
	s_mov_b32 m0, s2
	v_readfirstlane_b32 s2, v141
	global_load_lds_dwordx4 v[134:135], off
	v_lshl_add_u64 v[134:135], v[132:133], 0, s[96:97]
	s_mov_b32 m0, s2
	v_readfirstlane_b32 s2, v140
	global_load_lds_dwordx4 v[134:135], off
	v_lshl_add_u64 v[134:135], v[130:131], 0, s[96:97]
	s_mov_b32 m0, s2
	s_mov_b64 s[10:11], 0x60000
	v_readfirstlane_b32 s2, v139
	global_load_lds_dwordx4 v[134:135], off
	v_lshl_add_u64 v[132:133], v[132:133], 0, s[10:11]
	s_mov_b32 m0, s2
	v_readfirstlane_b32 s2, v138
	global_load_lds_dwordx4 v[132:133], off
	v_lshl_add_u64 v[130:131], v[130:131], 0, s[10:11]
	s_mov_b32 m0, s2
	s_nop 0
	global_load_lds_dwordx4 v[130:131], off
	s_branch .LBB0_698

; #define WAIT_V0() asm volatile("s_waitcnt vmcnt(0)" ::: "memory")
; template <int EPI>
; DEVI void gemm_tile(const u16* __restrict__ Ab, long lda, const u16* __restrict__ Bb, long ldb, int K, const EpiArgs& e,
;                     bool have0 = false, const u16* __restrict__ nA = nullptr, const u16* __restrict__ nB = nullptr) {
;     ...
;   f32x4 acc[8][4];
; #pragma unroll
;   for (int m = 0; m < 8; ++m)
; #pragma unroll
;     for (int n = 0; n < 4; ++n) acc[m][n] = f32x4{0.f, 0.f, 0.f, 0.f};
;   const int nt = K / BK;
;   if (!have0) GLDS_STAGE(0, 0);
;   WAIT_V0(); __syncthreads();
;   for (int t = 0; t < nt; ++t) {
;     const int cur = t & 1;
;     if (t + 1 < nt) GLDS_STAGE(cur ^ 1, t + 1);
.LBB0_795:
	s_and_b32 s3, s2, 0x10000
	v_or_b32_e32 v150, s3, v149
	v_add_u32_e32 v169, v150, v148
	v_or_b32_e32 v150, s3, v146
	v_add_u32_e32 v178, v150, v147
	ds_read_b128 v[150:153], v169 offset:32768
	ds_read_b128 v[154:157], v169 offset:34816
	ds_read_b128 v[158:161], v169 offset:36864
	ds_read_b128 v[162:165], v169 offset:38912
	ds_read_b128 v[170:173], v178
	ds_read_b128 v[174:177], v178 offset:2048
	ds_read_b128 v[192:195], v178 offset:4096
	ds_read_b128 v[198:201], v178 offset:6144
	v_writelane_b32 v240, s4, 0
	v_writelane_b32 v240, s5, 1
	v_writelane_b32 v240, s6, 2
	v_writelane_b32 v240, s7, 3
	v_writelane_b32 v240, s8, 4
	v_writelane_b32 v240, s9, 5
	v_writelane_b32 v240, s10, 6
	v_readfirstlane_b32 s4, v132
	v_readfirstlane_b32 s5, v133
	s_nop 1
	v_subrev_u32_e32 v238, s4, v132
	s_add_u32 s4, s4, s14
	s_addc_u32 s5, s5, s15
	v_readfirstlane_b32 s6, v134
	v_readfirstlane_b32 s7, v135
	s_nop 1
	v_subrev_u32_e32 v239, s6, v134
	s_add_u32 s6, s6, s14
	s_addc_u32 s7, s7, s15
	v_readfirstlane_b32 s10, v142
	s_xor_b32 s8, s3, 0x10000
	s_nop 0
	s_add_i32 s10, s10, s8
	s_add_i32 m0, s10, 0x0
	s_add_u32 s8, s4, 0x12500080
	s_addc_u32 s9, s5, 0
	global_load_lds_dwordx4 v238, s[8:9]
	s_add_i32 m0, s10, 0x8000
	s_add_u32 s8, s6, s20
	s_addc_u32 s9, s7, s21
	global_load_lds_dwordx4 v239, s[8:9]
	s_add_i32 m0, s10, 0x2000
	s_add_u32 s8, s4, 0x12520080
	s_addc_u32 s9, s5, 0
	global_load_lds_dwordx4 v238, s[8:9]
; #define WAIT_V0() asm volatile("s_waitcnt vmcnt(0)" ::: "memory")
; #define SBAR() __builtin_amdgcn_sched_barrier(0)
; template <int EPI>
; DEVI void gemm_tile(const u16* __restrict__ Ab, long lda, const u16* __restrict__ Bb, long ldb, int K, const EpiArgs& e,
;                     bool have0 = false, const u16* __restrict__ nA = nullptr, const u16* __restrict__ nB = nullptr) {
;     ...
;   for (int t = 0; t < nt; ++t) {
;     const int cur = t & 1;
;     if (t + 1 < nt) GLDS_STAGE(cur ^ 1, t + 1);
;     else if (nA) {
; #pragma unroll
;       for (int i = 0; i < GL; ++i) {
;         __builtin_amdgcn_global_load_lds((const unsigned*)(nA + (long)i * 64 * lda + toffA), (unsigned*)(g_shm + wid * 1024 + i * 8192), 16, 0, 0);
;         __builtin_amdgcn_global_load_lds((const unsigned*)(nB + (long)i * 64 * ldb + toffB), (unsigned*)(g_shm + TILE_B + wid * 1024 + i * 8192), 16, 0, 0);
;       }
;     }
;     const char* sb = g_shm + cur * STAGE_B;
; #pragma unroll
;     for (int ks = 0; ks < 2; ++ks) {
;       bf16x8 Bf[4];
; #pragma unroll
;       for (int n = 0; n < 4; ++n) Bf[n] = *(const bf16x8*)(sb + b_base + n * 2048 + ks * 1024);
; #pragma unroll
;       for (int mh = 0; mh < 2; ++mh) {
;         bf16x8 At[4];
; #pragma unroll
;         for (int m = 0; m < 4; ++m) At[m] = *(const bf16x8*)(sb + a_base + (mh * 4 + m) * 2048 + ks * 1024);
;         __builtin_amdgcn_s_setprio(1);
; #pragma unroll
;         for (int m = 0; m < 4; ++m)
; #pragma unroll
;           for (int n = 0; n < 4; ++n) acc[mh * 4 + m][n] = __builtin_amdgcn_mfma_f32_16x16x32_bf16(Bf[n], At[m], acc[mh * 4 + m][n], 0, 0, 0);
;         __builtin_amdgcn_s_setprio(0);
;       }
;       SBAR();
;     }
;     if (t + 1 < nt) { WAIT_V0(); __syncthreads(); }
;   }
.Lkl_795:
	s_waitcnt lgkmcnt(3)
	v_mfma_f32_16x16x32_bf16 v[126:129], v[150:153], v[170:173], v[126:129]
	v_mfma_f32_16x16x32_bf16 v[122:125], v[154:157], v[170:173], v[122:125]
	v_mfma_f32_16x16x32_bf16 v[118:121], v[158:161], v[170:173], v[118:121]
	v_mfma_f32_16x16x32_bf16 v[114:117], v[162:165], v[170:173], v[114:117]
	ds_read_b128 v[170:173], v178 offset:8192
	ds_read_b128 v[222:225], v169 offset:33792
	s_add_i32 m0, s10, 0xa000
	s_add_u32 s8, s6, s22
	s_addc_u32 s9, s7, s23
	global_load_lds_dwordx4 v239, s[8:9]
	s_waitcnt lgkmcnt(4)
	v_mfma_f32_16x16x32_bf16 v[110:113], v[150:153], v[174:177], v[110:113]
	v_mfma_f32_16x16x32_bf16 v[106:109], v[154:157], v[174:177], v[106:109]
	v_mfma_f32_16x16x32_bf16 v[102:105], v[158:161], v[174:177], v[102:105]
	v_mfma_f32_16x16x32_bf16 v[98:101], v[162:165], v[174:177], v[98:101]
	ds_read_b128 v[174:177], v178 offset:10240
	ds_read_b128 v[226:229], v169 offset:35840
	s_add_i32 m0, s10, 0x4000
	s_add_u32 s8, s4, 0x12540080
	s_addc_u32 s9, s5, 0
	global_load_lds_dwordx4 v238, s[8:9]
	s_waitcnt lgkmcnt(5)
	v_mfma_f32_16x16x32_bf16 v[94:97], v[150:153], v[192:195], v[94:97]
	v_mfma_f32_16x16x32_bf16 v[90:93], v[154:157], v[192:195], v[90:93]
	v_mfma_f32_16x16x32_bf16 v[86:89], v[158:161], v[192:195], v[86:89]
	v_mfma_f32_16x16x32_bf16 v[82:85], v[162:165], v[192:195], v[82:85]
	ds_read_b128 v[192:195], v178 offset:12288
	ds_read_b128 v[230:233], v169 offset:37888
	s_add_i32 m0, s10, 0xc000
	s_add_u32 s8, s6, s24
	s_addc_u32 s9, s7, s25
	global_load_lds_dwordx4 v239, s[8:9]
	s_waitcnt lgkmcnt(6)
	v_mfma_f32_16x16x32_bf16 v[78:81], v[150:153], v[198:201], v[78:81]
	v_mfma_f32_16x16x32_bf16 v[74:77], v[154:157], v[198:201], v[74:77]
	v_mfma_f32_16x16x32_bf16 v[70:73], v[158:161], v[198:201], v[70:73]
	v_mfma_f32_16x16x32_bf16 v[66:69], v[162:165], v[198:201], v[66:69]
	ds_read_b128 v[198:201], v178 offset:14336
	ds_read_b128 v[234:237], v169 offset:39936
	s_add_i32 m0, s10, 0x6000
	s_add_u32 s8, s4, 0x12560080
	s_addc_u32 s9, s5, 0
	global_load_lds_dwordx4 v238, s[8:9]
	s_waitcnt lgkmcnt(7)
	v_mfma_f32_16x16x32_bf16 v[62:65], v[150:153], v[170:173], v[62:65]
	v_mfma_f32_16x16x32_bf16 v[58:61], v[154:157], v[170:173], v[58:61]
	v_mfma_f32_16x16x32_bf16 v[54:57], v[158:161], v[170:173], v[54:57]
	v_mfma_f32_16x16x32_bf16 v[50:53], v[162:165], v[170:173], v[50:53]
	ds_read_b128 v[170:173], v178 offset:1024
	s_add_i32 m0, s10, 0xe000
	s_add_u32 s8, s6, s26
	s_addc_u32 s9, s7, s27
	global_load_lds_dwordx4 v239, s[8:9]
	s_waitcnt lgkmcnt(6)
	v_mfma_f32_16x16x32_bf16 v[46:49], v[150:153], v[174:177], v[46:49]
	v_mfma_f32_16x16x32_bf16 v[42:45], v[154:157], v[174:177], v[42:45]
	v_mfma_f32_16x16x32_bf16 v[38:41], v[158:161], v[174:177], v[38:41]
	v_mfma_f32_16x16x32_bf16 v[34:37], v[162:165], v[174:177], v[34:37]
	ds_read_b128 v[174:177], v178 offset:3072
	s_waitcnt lgkmcnt(5)
	v_mfma_f32_16x16x32_bf16 v[30:33], v[150:153], v[192:195], v[30:33]
	v_mfma_f32_16x16x32_bf16 v[26:29], v[154:157], v[192:195], v[26:29]
	v_mfma_f32_16x16x32_bf16 v[22:25], v[158:161], v[192:195], v[22:25]
	v_mfma_f32_16x16x32_bf16 v[18:21], v[162:165], v[192:195], v[18:21]
	ds_read_b128 v[192:195], v178 offset:5120
	s_waitcnt lgkmcnt(4)
	v_mfma_f32_16x16x32_bf16 v[14:17], v[150:153], v[198:201], v[14:17]
	v_mfma_f32_16x16x32_bf16 v[10:13], v[154:157], v[198:201], v[10:13]
	v_mfma_f32_16x16x32_bf16 v[6:9], v[158:161], v[198:201], v[6:9]
	v_mfma_f32_16x16x32_bf16 v[2:5], v[162:165], v[198:201], v[2:5]
	ds_read_b128 v[198:201], v178 offset:7168
	s_waitcnt lgkmcnt(3)
	v_mfma_f32_16x16x32_bf16 v[126:129], v[222:225], v[170:173], v[126:129]
	v_mfma_f32_16x16x32_bf16 v[122:125], v[226:229], v[170:173], v[122:125]
	v_mfma_f32_16x16x32_bf16 v[118:121], v[230:233], v[170:173], v[118:121]
	v_mfma_f32_16x16x32_bf16 v[114:117], v[234:237], v[170:173], v[114:117]
	ds_read_b128 v[170:173], v178 offset:9216
	s_waitcnt lgkmcnt(3)
	v_mfma_f32_16x16x32_bf16 v[110:113], v[222:225], v[174:177], v[110:113]
	v_mfma_f32_16x16x32_bf16 v[106:109], v[226:229], v[174:177], v[106:109]
	v_mfma_f32_16x16x32_bf16 v[102:105], v[230:233], v[174:177], v[102:105]
	v_mfma_f32_16x16x32_bf16 v[98:101], v[234:237], v[174:177], v[98:101]
	ds_read_b128 v[174:177], v178 offset:11264
	s_waitcnt lgkmcnt(3)
	v_mfma_f32_16x16x32_bf16 v[94:97], v[222:225], v[192:195], v[94:97]
	v_mfma_f32_16x16x32_bf16 v[90:93], v[226:229], v[192:195], v[90:93]
	v_mfma_f32_16x16x32_bf16 v[86:89], v[230:233], v[192:195], v[86:89]
	v_mfma_f32_16x16x32_bf16 v[82:85], v[234:237], v[192:195], v[82:85]
	ds_read_b128 v[192:195], v178 offset:13312
	s_waitcnt lgkmcnt(3)
	v_mfma_f32_16x16x32_bf16 v[78:81], v[222:225], v[198:201], v[78:81]
	v_mfma_f32_16x16x32_bf16 v[74:77], v[226:229], v[198:201], v[74:77]
	v_mfma_f32_16x16x32_bf16 v[70:73], v[230:233], v[198:201], v[70:73]
	v_mfma_f32_16x16x32_bf16 v[66:69], v[234:237], v[198:201], v[66:69]
	ds_read_b128 v[198:201], v178 offset:15360
	s_waitcnt lgkmcnt(3)
	v_mfma_f32_16x16x32_bf16 v[62:65], v[222:225], v[170:173], v[62:65]
	v_mfma_f32_16x16x32_bf16 v[58:61], v[226:229], v[170:173], v[58:61]
	v_mfma_f32_16x16x32_bf16 v[54:57], v[230:233], v[170:173], v[54:57]
	v_mfma_f32_16x16x32_bf16 v[50:53], v[234:237], v[170:173], v[50:53]
	s_waitcnt lgkmcnt(2)
	v_mfma_f32_16x16x32_bf16 v[46:49], v[222:225], v[174:177], v[46:49]
	v_mfma_f32_16x16x32_bf16 v[42:45], v[226:229], v[174:177], v[42:45]
	v_mfma_f32_16x16x32_bf16 v[38:41], v[230:233], v[174:177], v[38:41]
	v_mfma_f32_16x16x32_bf16 v[34:37], v[234:237], v[174:177], v[34:37]
	s_waitcnt lgkmcnt(0)
	s_waitcnt vmcnt(0)
	s_add_u32 s14, s14, 0x80
	s_addc_u32 s15, s15, 0
	s_add_i32 s2, s2, 0x10000
	s_cmpk_eq_i32 s14, 0x780
	s_waitcnt vmcnt(0)
	s_barrier
	s_cselect_b32 s100, 1, 0
	s_and_b32 s3, s2, 0x10000
	v_or_b32_e32 v150, s3, v149
	v_add_u32_e32 v169, v150, v148
	v_or_b32_e32 v150, s3, v146
	v_add_u32_e32 v178, v150, v147
	ds_read_b128 v[150:153], v169 offset:32768
	ds_read_b128 v[154:157], v169 offset:34816
	ds_read_b128 v[158:161], v169 offset:36864
	ds_read_b128 v[162:165], v169 offset:38912
	ds_read_b128 v[170:173], v178
	ds_read_b128 v[174:177], v178 offset:2048
	s_add_u32 s4, s4, 0x80
	s_addc_u32 s5, s5, 0
	s_add_u32 s6, s6, 0x80
	s_addc_u32 s7, s7, 0
	s_cmp_eq_u32 s100, 1
	s_cbranch_scc1 .Lkl_795_s1
	v_readfirstlane_b32 s10, v142
	s_xor_b32 s8, s3, 0x10000
	s_nop 0
	s_add_i32 s10, s10, s8
	s_add_i32 m0, s10, 0x0
	s_add_u32 s8, s4, 0x12500080
	s_addc_u32 s9, s5, 0
	global_load_lds_dwordx4 v238, s[8:9]

; #define WAIT_V0() asm volatile("s_waitcnt vmcnt(0)" ::: "memory")
; #define SBAR() __builtin_amdgcn_sched_barrier(0)
; template <int EPI>
; DEVI void gemm_tile(const u16* __restrict__ Ab, long lda, const u16* __restrict__ Bb, long ldb, int K, const EpiArgs& e,
;                     bool have0 = false, const u16* __restrict__ nA = nullptr, const u16* __restrict__ nB = nullptr) {
;     ...
;   for (int t = 0; t < nt; ++t) {
;     const int cur = t & 1;
;     if (t + 1 < nt) GLDS_STAGE(cur ^ 1, t + 1);
;     else if (nA) {
; #pragma unroll
;       for (int i = 0; i < GL; ++i) {
;         __builtin_amdgcn_global_load_lds((const unsigned*)(nA + (long)i * 64 * lda + toffA), (unsigned*)(g_shm + wid * 1024 + i * 8192), 16, 0, 0);
;         __builtin_amdgcn_global_load_lds((const unsigned*)(nB + (long)i * 64 * ldb + toffB), (unsigned*)(g_shm + TILE_B + wid * 1024 + i * 8192), 16, 0, 0);
;       }
;     }
;     const char* sb = g_shm + cur * STAGE_B;
; #pragma unroll
;     for (int ks = 0; ks < 2; ++ks) {
;       bf16x8 Bf[4];
; #pragma unroll
;       for (int n = 0; n < 4; ++n) Bf[n] = *(const bf16x8*)(sb + b_base + n * 2048 + ks * 1024);
; #pragma unroll
;       for (int mh = 0; mh < 2; ++mh) {
;         bf16x8 At[4];
; #pragma unroll
;         for (int m = 0; m < 4; ++m) At[m] = *(const bf16x8*)(sb + a_base + (mh * 4 + m) * 2048 + ks * 1024);
;         __builtin_amdgcn_s_setprio(1);
; #pragma unroll
;         for (int m = 0; m < 4; ++m)
; #pragma unroll
;           for (int n = 0; n < 4; ++n) acc[mh * 4 + m][n] = __builtin_amdgcn_mfma_f32_16x16x32_bf16(Bf[n], At[m], acc[mh * 4 + m][n], 0, 0, 0);
;         __builtin_amdgcn_s_setprio(0);
;       }
;       SBAR();
;     }
;     if (t + 1 < nt) { WAIT_V0(); __syncthreads(); }
;   }
.Lkl_795_s2:
	v_mfma_f32_16x16x32_bf16 v[14:17], v[222:225], v[198:201], v[14:17]
	v_mfma_f32_16x16x32_bf16 v[10:13], v[226:229], v[198:201], v[10:13]
	v_mfma_f32_16x16x32_bf16 v[6:9], v[230:233], v[198:201], v[6:9]
	v_mfma_f32_16x16x32_bf16 v[2:5], v[234:237], v[198:201], v[2:5]
	ds_read_b128 v[198:201], v178 offset:6144
	s_cmp_eq_u32 s100, 1
	s_cbranch_scc1 .Lkl_795_s3
	s_add_i32 m0, s10, 0x2000
	s_add_u32 s8, s4, 0x12520080
	s_addc_u32 s9, s5, 0
	global_load_lds_dwordx4 v238, s[8:9]

; #define WAIT_V0() asm volatile("s_waitcnt vmcnt(0)" ::: "memory")
; #define SBAR() __builtin_amdgcn_sched_barrier(0)
; template <int EPI>
; DEVI void gemm_tile(const u16* __restrict__ Ab, long lda, const u16* __restrict__ Bb, long ldb, int K, const EpiArgs& e,
;                     bool have0 = false, const u16* __restrict__ nA = nullptr, const u16* __restrict__ nB = nullptr) {
;     ...
;   f32x4 acc[8][4];
; #pragma unroll
;   for (int m = 0; m < 8; ++m)
; #pragma unroll
;     for (int n = 0; n < 4; ++n) acc[m][n] = f32x4{0.f, 0.f, 0.f, 0.f};
;   const int nt = K / BK;
;   if (!have0) GLDS_STAGE(0, 0);
;   WAIT_V0(); __syncthreads();
;   for (int t = 0; t < nt; ++t) {
;     const int cur = t & 1;
;     if (t + 1 < nt) GLDS_STAGE(cur ^ 1, t + 1);
;     else if (nA) {
; #pragma unroll
;       for (int i = 0; i < GL; ++i) {
;         __builtin_amdgcn_global_load_lds((const unsigned*)(nA + (long)i * 64 * lda + toffA), (unsigned*)(g_shm + wid * 1024 + i * 8192), 16, 0, 0);
;         __builtin_amdgcn_global_load_lds((const unsigned*)(nB + (long)i * 64 * ldb + toffB), (unsigned*)(g_shm + TILE_B + wid * 1024 + i * 8192), 16, 0, 0);
;       }
;     }
;     const char* sb = g_shm + cur * STAGE_B;
; #pragma unroll
;     for (int ks = 0; ks < 2; ++ks) {
;       bf16x8 Bf[4];
; #pragma unroll
;       for (int n = 0; n < 4; ++n) Bf[n] = *(const bf16x8*)(sb + b_base + n * 2048 + ks * 1024);
; #pragma unroll
;       for (int mh = 0; mh < 2; ++mh) {
;         bf16x8 At[4];
; #pragma unroll
;         for (int m = 0; m < 4; ++m) At[m] = *(const bf16x8*)(sb + a_base + (mh * 4 + m) * 2048 + ks * 1024);
;         __builtin_amdgcn_s_setprio(1);
; #pragma unroll
;         for (int m = 0; m < 4; ++m)
; #pragma unroll
;           for (int n = 0; n < 4; ++n) acc[mh * 4 + m][n] = __builtin_amdgcn_mfma_f32_16x16x32_bf16(Bf[n], At[m], acc[mh * 4 + m][n], 0, 0, 0);
;         __builtin_amdgcn_s_setprio(0);
;       }
;       SBAR();
;     }
;     if (t + 1 < nt) { WAIT_V0(); __syncthreads(); }
;   }
.LBB0_1085:
	s_and_b32 s3, s2, 0x10000
	v_or_b32_e32 v150, s3, v149
	v_add_u32_e32 v169, v150, v148
	v_or_b32_e32 v150, s3, v146
	v_add_u32_e32 v178, v150, v147
	ds_read_b128 v[150:153], v169 offset:32768
	ds_read_b128 v[154:157], v169 offset:34816
	ds_read_b128 v[158:161], v169 offset:36864
	ds_read_b128 v[162:165], v169 offset:38912
	ds_read_b128 v[170:173], v178
	ds_read_b128 v[174:177], v178 offset:2048
	ds_read_b128 v[192:195], v178 offset:4096
	ds_read_b128 v[198:201], v178 offset:6144
	v_writelane_b32 v240, s4, 0
	v_writelane_b32 v240, s5, 1
	v_writelane_b32 v240, s6, 2
	v_writelane_b32 v240, s7, 3
	v_writelane_b32 v240, s8, 4
	v_writelane_b32 v240, s9, 5
	v_writelane_b32 v240, s10, 6
	v_readfirstlane_b32 s4, v134
	v_readfirstlane_b32 s5, v135
	s_nop 1
	v_subrev_u32_e32 v238, s4, v134
	s_add_u32 s4, s4, s16
	s_addc_u32 s5, s5, s17
	v_readfirstlane_b32 s6, v136
	v_readfirstlane_b32 s7, v137
	s_nop 1
	v_subrev_u32_e32 v239, s6, v136
	s_add_u32 s6, s6, s16
	s_addc_u32 s7, s7, s17
	v_readfirstlane_b32 s10, v142
	s_xor_b32 s8, s3, 0x10000
	s_nop 0
	s_add_i32 s10, s10, s8
	s_add_i32 m0, s10, 0x0
	s_add_u32 s8, s4, s22
	s_addc_u32 s9, s5, s23
	global_load_lds_dwordx4 v238, s[8:9]
	s_add_i32 m0, s10, 0x8000
	s_add_u32 s8, s6, 0x97c0080
	s_addc_u32 s9, s7, 0
	global_load_lds_dwordx4 v239, s[8:9]
	s_add_i32 m0, s10, 0x2000
	s_add_u32 s8, s4, s24
	s_addc_u32 s9, s5, s25
	global_load_lds_dwordx4 v238, s[8:9]
.Lkl_1085:
	s_waitcnt lgkmcnt(3)
	v_mfma_f32_16x16x32_bf16 v[126:129], v[150:153], v[170:173], v[126:129]
	v_mfma_f32_16x16x32_bf16 v[122:125], v[154:157], v[170:173], v[122:125]
	v_mfma_f32_16x16x32_bf16 v[118:121], v[158:161], v[170:173], v[118:121]
	v_mfma_f32_16x16x32_bf16 v[114:117], v[162:165], v[170:173], v[114:117]
	ds_read_b128 v[170:173], v178 offset:8192
	ds_read_b128 v[222:225], v169 offset:33792
	s_add_i32 m0, s10, 0xa000
	s_add_u32 s8, s6, 0x97e0080
	s_addc_u32 s9, s7, 0
	global_load_lds_dwordx4 v239, s[8:9]
	s_waitcnt lgkmcnt(4)
	v_mfma_f32_16x16x32_bf16 v[110:113], v[150:153], v[174:177], v[110:113]
	v_mfma_f32_16x16x32_bf16 v[106:109], v[154:157], v[174:177], v[106:109]
	v_mfma_f32_16x16x32_bf16 v[102:105], v[158:161], v[174:177], v[102:105]
	v_mfma_f32_16x16x32_bf16 v[98:101], v[162:165], v[174:177], v[98:101]
	ds_read_b128 v[174:177], v178 offset:10240
	ds_read_b128 v[226:229], v169 offset:35840
	s_add_i32 m0, s10, 0x4000
	s_add_u32 s8, s4, s26
	s_addc_u32 s9, s5, s27
	global_load_lds_dwordx4 v238, s[8:9]
	s_waitcnt lgkmcnt(5)
	v_mfma_f32_16x16x32_bf16 v[94:97], v[150:153], v[192:195], v[94:97]
	v_mfma_f32_16x16x32_bf16 v[90:93], v[154:157], v[192:195], v[90:93]
	v_mfma_f32_16x16x32_bf16 v[86:89], v[158:161], v[192:195], v[86:89]
	v_mfma_f32_16x16x32_bf16 v[82:85], v[162:165], v[192:195], v[82:85]
	ds_read_b128 v[192:195], v178 offset:12288
	ds_read_b128 v[230:233], v169 offset:37888
	s_add_i32 m0, s10, 0xc000
	s_add_u32 s8, s6, 0x9800080
	s_addc_u32 s9, s7, 0
	global_load_lds_dwordx4 v239, s[8:9]
	s_waitcnt lgkmcnt(6)
	v_mfma_f32_16x16x32_bf16 v[78:81], v[150:153], v[198:201], v[78:81]
	v_mfma_f32_16x16x32_bf16 v[74:77], v[154:157], v[198:201], v[74:77]
	v_mfma_f32_16x16x32_bf16 v[70:73], v[158:161], v[198:201], v[70:73]
	v_mfma_f32_16x16x32_bf16 v[66:69], v[162:165], v[198:201], v[66:69]
	ds_read_b128 v[198:201], v178 offset:14336
	ds_read_b128 v[234:237], v169 offset:39936
	s_add_i32 m0, s10, 0x6000
	s_add_u32 s8, s4, s30
	s_addc_u32 s9, s5, s31
	global_load_lds_dwordx4 v238, s[8:9]
	s_waitcnt lgkmcnt(7)
	v_mfma_f32_16x16x32_bf16 v[62:65], v[150:153], v[170:173], v[62:65]
	v_mfma_f32_16x16x32_bf16 v[58:61], v[154:157], v[170:173], v[58:61]
	v_mfma_f32_16x16x32_bf16 v[54:57], v[158:161], v[170:173], v[54:57]
	v_mfma_f32_16x16x32_bf16 v[50:53], v[162:165], v[170:173], v[50:53]
	ds_read_b128 v[170:173], v178 offset:1024
	s_add_i32 m0, s10, 0xe000
	s_add_u32 s8, s6, 0x9820080
	s_addc_u32 s9, s7, 0
	global_load_lds_dwordx4 v239, s[8:9]
	s_waitcnt lgkmcnt(6)
	v_mfma_f32_16x16x32_bf16 v[46:49], v[150:153], v[174:177], v[46:49]
	v_mfma_f32_16x16x32_bf16 v[42:45], v[154:157], v[174:177], v[42:45]
	v_mfma_f32_16x16x32_bf16 v[38:41], v[158:161], v[174:177], v[38:41]
	v_mfma_f32_16x16x32_bf16 v[34:37], v[162:165], v[174:177], v[34:37]
	ds_read_b128 v[174:177], v178 offset:3072
	s_waitcnt lgkmcnt(5)
	v_mfma_f32_16x16x32_bf16 v[30:33], v[150:153], v[192:195], v[30:33]
	v_mfma_f32_16x16x32_bf16 v[26:29], v[154:157], v[192:195], v[26:29]
	v_mfma_f32_16x16x32_bf16 v[22:25], v[158:161], v[192:195], v[22:25]
	v_mfma_f32_16x16x32_bf16 v[18:21], v[162:165], v[192:195], v[18:21]
	ds_read_b128 v[192:195], v178 offset:5120
	s_waitcnt lgkmcnt(4)
	v_mfma_f32_16x16x32_bf16 v[14:17], v[150:153], v[198:201], v[14:17]
	v_mfma_f32_16x16x32_bf16 v[10:13], v[154:157], v[198:201], v[10:13]
	v_mfma_f32_16x16x32_bf16 v[6:9], v[158:161], v[198:201], v[6:9]
	v_mfma_f32_16x16x32_bf16 v[2:5], v[162:165], v[198:201], v[2:5]
	ds_read_b128 v[198:201], v178 offset:7168
	s_waitcnt lgkmcnt(3)
	v_mfma_f32_16x16x32_bf16 v[126:129], v[222:225], v[170:173], v[126:129]
	v_mfma_f32_16x16x32_bf16 v[122:125], v[226:229], v[170:173], v[122:125]
	v_mfma_f32_16x16x32_bf16 v[118:121], v[230:233], v[170:173], v[118:121]
	v_mfma_f32_16x16x32_bf16 v[114:117], v[234:237], v[170:173], v[114:117]
	ds_read_b128 v[170:173], v178 offset:9216
	s_waitcnt lgkmcnt(3)
; #define WAIT_V0() asm volatile("s_waitcnt vmcnt(0)" ::: "memory")
; #define SBAR() __builtin_amdgcn_sched_barrier(0)
; template <int EPI>
; DEVI void gemm_tile(const u16* __restrict__ Ab, long lda, const u16* __restrict__ Bb, long ldb, int K, const EpiArgs& e,
;                     bool have0 = false, const u16* __restrict__ nA = nullptr, const u16* __restrict__ nB = nullptr) {
;     ...
;   f32x4 acc[8][4];
; #pragma unroll
;   for (int m = 0; m < 8; ++m)
; #pragma unroll
;     for (int n = 0; n < 4; ++n) acc[m][n] = f32x4{0.f, 0.f, 0.f, 0.f};
;   const int nt = K / BK;
;   if (!have0) GLDS_STAGE(0, 0);
;   WAIT_V0(); __syncthreads();
;   for (int t = 0; t < nt; ++t) {
;     const int cur = t & 1;
;     if (t + 1 < nt) GLDS_STAGE(cur ^ 1, t + 1);
;     else if (nA) {
; #pragma unroll
;       for (int i = 0; i < GL; ++i) {
;         __builtin_amdgcn_global_load_lds((const unsigned*)(nA + (long)i * 64 * lda + toffA), (unsigned*)(g_shm + wid * 1024 + i * 8192), 16, 0, 0);
;         __builtin_amdgcn_global_load_lds((const unsigned*)(nB + (long)i * 64 * ldb + toffB), (unsigned*)(g_shm + TILE_B + wid * 1024 + i * 8192), 16, 0, 0);
;       }
;     }
;     const char* sb = g_shm + cur * STAGE_B;
; #pragma unroll
;     for (int ks = 0; ks < 2; ++ks) {
;       bf16x8 Bf[4];
; #pragma unroll
;       for (int n = 0; n < 4; ++n) Bf[n] = *(const bf16x8*)(sb + b_base + n * 2048 + ks * 1024);
; #pragma unroll
;       for (int mh = 0; mh < 2; ++mh) {
;         bf16x8 At[4];
; #pragma unroll
;         for (int m = 0; m < 4; ++m) At[m] = *(const bf16x8*)(sb + a_base + (mh * 4 + m) * 2048 + ks * 1024);
;         __builtin_amdgcn_s_setprio(1);
; #pragma unroll
;         for (int m = 0; m < 4; ++m)
; #pragma unroll
;           for (int n = 0; n < 4; ++n) acc[mh * 4 + m][n] = __builtin_amdgcn_mfma_f32_16x16x32_bf16(Bf[n], At[m], acc[mh * 4 + m][n], 0, 0, 0);
;         __builtin_amdgcn_s_setprio(0);
;       }
;       SBAR();
;     }
;     if (t + 1 < nt) { WAIT_V0(); __syncthreads(); }
;   }
	v_mfma_f32_16x16x32_bf16 v[110:113], v[222:225], v[174:177], v[110:113]
	v_mfma_f32_16x16x32_bf16 v[106:109], v[226:229], v[174:177], v[106:109]
	v_mfma_f32_16x16x32_bf16 v[102:105], v[230:233], v[174:177], v[102:105]
	v_mfma_f32_16x16x32_bf16 v[98:101], v[234:237], v[174:177], v[98:101]
	ds_read_b128 v[174:177], v178 offset:11264
	s_waitcnt lgkmcnt(3)
	v_mfma_f32_16x16x32_bf16 v[94:97], v[222:225], v[192:195], v[94:97]
	v_mfma_f32_16x16x32_bf16 v[90:93], v[226:229], v[192:195], v[90:93]
	v_mfma_f32_16x16x32_bf16 v[86:89], v[230:233], v[192:195], v[86:89]
	v_mfma_f32_16x16x32_bf16 v[82:85], v[234:237], v[192:195], v[82:85]
	ds_read_b128 v[192:195], v178 offset:13312
	s_waitcnt lgkmcnt(3)
	v_mfma_f32_16x16x32_bf16 v[78:81], v[222:225], v[198:201], v[78:81]
	v_mfma_f32_16x16x32_bf16 v[74:77], v[226:229], v[198:201], v[74:77]
	v_mfma_f32_16x16x32_bf16 v[70:73], v[230:233], v[198:201], v[70:73]
	v_mfma_f32_16x16x32_bf16 v[66:69], v[234:237], v[198:201], v[66:69]
	ds_read_b128 v[198:201], v178 offset:15360
	s_waitcnt lgkmcnt(3)
	v_mfma_f32_16x16x32_bf16 v[62:65], v[222:225], v[170:173], v[62:65]
	v_mfma_f32_16x16x32_bf16 v[58:61], v[226:229], v[170:173], v[58:61]
	v_mfma_f32_16x16x32_bf16 v[54:57], v[230:233], v[170:173], v[54:57]
	v_mfma_f32_16x16x32_bf16 v[50:53], v[234:237], v[170:173], v[50:53]
	s_waitcnt lgkmcnt(2)
	v_mfma_f32_16x16x32_bf16 v[46:49], v[222:225], v[174:177], v[46:49]
	v_mfma_f32_16x16x32_bf16 v[42:45], v[226:229], v[174:177], v[42:45]
	v_mfma_f32_16x16x32_bf16 v[38:41], v[230:233], v[174:177], v[38:41]
	v_mfma_f32_16x16x32_bf16 v[34:37], v[234:237], v[174:177], v[34:37]
	s_waitcnt lgkmcnt(0)
	s_waitcnt vmcnt(0)
	s_add_u32 s16, s16, 0x80
	s_addc_u32 s17, s17, 0
	s_add_i32 s2, s2, 0x10000
	s_cmpk_eq_i32 s16, 0x780
	s_waitcnt vmcnt(0)
	s_barrier
	s_cselect_b32 s100, 1, 0
	s_and_b32 s3, s2, 0x10000
	v_or_b32_e32 v150, s3, v149
	v_add_u32_e32 v169, v150, v148
	v_or_b32_e32 v150, s3, v146
	v_add_u32_e32 v178, v150, v147
	ds_read_b128 v[150:153], v169 offset:32768
	ds_read_b128 v[154:157], v169 offset:34816
	ds_read_b128 v[158:161], v169 offset:36864
	ds_read_b128 v[162:165], v169 offset:38912
	ds_read_b128 v[170:173], v178
	ds_read_b128 v[174:177], v178 offset:2048
	s_add_u32 s4, s4, 0x80
	s_addc_u32 s5, s5, 0
	s_add_u32 s6, s6, 0x80
	s_addc_u32 s7, s7, 0
	s_cmp_eq_u32 s100, 1
	s_cbranch_scc1 .Lkl_1085_s1
	v_readfirstlane_b32 s10, v142
	s_xor_b32 s8, s3, 0x10000
	s_nop 0
	s_add_i32 s10, s10, s8
	s_add_i32 m0, s10, 0x0
	s_add_u32 s8, s4, s22
	s_addc_u32 s9, s5, s23
	global_load_lds_dwordx4 v238, s[8:9]
.Lkl_1085_s1:
	v_mfma_f32_16x16x32_bf16 v[30:33], v[222:225], v[192:195], v[30:33]
	v_mfma_f32_16x16x32_bf16 v[26:29], v[226:229], v[192:195], v[26:29]
	v_mfma_f32_16x16x32_bf16 v[22:25], v[230:233], v[192:195], v[22:25]
	v_mfma_f32_16x16x32_bf16 v[18:21], v[234:237], v[192:195], v[18:21]
	ds_read_b128 v[192:195], v178 offset:4096
	s_cmp_eq_u32 s100, 1
	s_cbranch_scc1 .Lkl_1085_s2
	s_add_i32 m0, s10, 0x8000
	s_add_u32 s8, s6, 0x97c0080
	s_addc_u32 s9, s7, 0
	global_load_lds_dwordx4 v239, s[8:9]
.Lkl_1085_s2:
	v_mfma_f32_16x16x32_bf16 v[14:17], v[222:225], v[198:201], v[14:17]
	v_mfma_f32_16x16x32_bf16 v[10:13], v[226:229], v[198:201], v[10:13]
	v_mfma_f32_16x16x32_bf16 v[6:9], v[230:233], v[198:201], v[6:9]
	v_mfma_f32_16x16x32_bf16 v[2:5], v[234:237], v[198:201], v[2:5]
	ds_read_b128 v[198:201], v178 offset:6144
	s_cmp_eq_u32 s100, 1
	s_cbranch_scc1 .Lkl_1085_s3
	s_add_i32 m0, s10, 0x2000
	s_add_u32 s8, s4, s24
	s_addc_u32 s9, s5, s25
	global_load_lds_dwordx4 v238, s[8:9]
.Lkl_1085_s3:
	s_cmp_eq_u32 s100, 1
	s_cbranch_scc0 .Lkl_1085
	s_nop 3
	v_readlane_b32 s4, v240, 0
	v_readlane_b32 s5, v240, 1
	v_readlane_b32 s6, v240, 2
	v_readlane_b32 s7, v240, 3
	v_readlane_b32 s8, v240, 4
	v_readlane_b32 s9, v240, 5
	v_readlane_b32 s10, v240, 6
	s_waitcnt lgkmcnt(0)
	s_xor_b32 s3, s3, 0x10000
	v_or_b32_e32 v150, s3, v149
	v_add_u32_e32 v169, v150, v148
	v_or_b32_e32 v150, s3, v146
	v_add_u32_e32 v178, v150, v147
	s_cmp_eq_u32 s100, 1
	s_cmp_eq_u64 s[8:9], 0
	s_cbranch_scc1 .LBB0_1073
	v_readfirstlane_b32 s2, v142
	v_lshl_add_u64 v[134:135], s[8:9], 0, v[132:133]
	s_mov_b32 m0, s2
	v_readfirstlane_b32 s2, v145
	v_lshl_add_u64 v[132:133], s[12:13], 0, v[132:133]
	global_load_lds_dwordx4 v[134:135], off
	s_mov_b32 m0, s2
	s_mov_b64 s[12:13], 0x20000
	v_readfirstlane_b32 s2, v144
	global_load_lds_dwordx4 v[132:133], off
	v_lshl_add_u64 v[136:137], v[134:135], 0, s[12:13]
	s_mov_b32 m0, s2
	v_readfirstlane_b32 s2, v143
	global_load_lds_dwordx4 v[136:137], off
	v_lshl_add_u64 v[136:137], v[132:133], 0, s[12:13]
	s_mov_b32 m0, s2
	v_readfirstlane_b32 s2, v141
	global_load_lds_dwordx4 v[136:137], off
	v_lshl_add_u64 v[136:137], v[134:135], 0, s[96:97]
	s_mov_b32 m0, s2
	v_readfirstlane_b32 s2, v140
	global_load_lds_dwordx4 v[136:137], off
	v_lshl_add_u64 v[136:137], v[132:133], 0, s[96:97]
	s_mov_b32 m0, s2
	s_mov_b64 s[12:13], 0x60000
	v_readfirstlane_b32 s2, v139
	global_load_lds_dwordx4 v[136:137], off
	v_lshl_add_u64 v[134:135], v[134:135], 0, s[12:13]
	s_mov_b32 m0, s2
	v_readfirstlane_b32 s2, v138
	global_load_lds_dwordx4 v[134:135], off
	v_lshl_add_u64 v[132:133], v[132:133], 0, s[12:13]
	s_mov_b32 m0, s2
	s_nop 0
	global_load_lds_dwordx4 v[132:133], off
	s_branch .LBB0_1073

; #define WAIT_V0() asm volatile("s_waitcnt vmcnt(0)" ::: "memory")
; #define SBAR() __builtin_amdgcn_sched_barrier(0)
; template <int EPI>
; DEVI void gemm_tile(const u16* __restrict__ Ab, long lda, const u16* __restrict__ Bb, long ldb, int K, const EpiArgs& e,
;                     bool have0 = false, const u16* __restrict__ nA = nullptr, const u16* __restrict__ nB = nullptr) {
;     ...
;   f32x4 acc[8][4];
; #pragma unroll
;   for (int m = 0; m < 8; ++m)
; #pragma unroll
;     for (int n = 0; n < 4; ++n) acc[m][n] = f32x4{0.f, 0.f, 0.f, 0.f};
;   const int nt = K / BK;
;   if (!have0) GLDS_STAGE(0, 0);
;   WAIT_V0(); __syncthreads();
;   for (int t = 0; t < nt; ++t) {
;     const int cur = t & 1;
;     if (t + 1 < nt) GLDS_STAGE(cur ^ 1, t + 1);
;     else if (nA) {
; #pragma unroll
;       for (int i = 0; i < GL; ++i) {
;         __builtin_amdgcn_global_load_lds((const unsigned*)(nA + (long)i * 64 * lda + toffA), (unsigned*)(g_shm + wid * 1024 + i * 8192), 16, 0, 0);
;         __builtin_amdgcn_global_load_lds((const unsigned*)(nB + (long)i * 64 * ldb + toffB), (unsigned*)(g_shm + TILE_B + wid * 1024 + i * 8192), 16, 0, 0);
;       }
;     }
;     const char* sb = g_shm + cur * STAGE_B;
; #pragma unroll
;     for (int ks = 0; ks < 2; ++ks) {
;       bf16x8 Bf[4];
; #pragma unroll
;       for (int n = 0; n < 4; ++n) Bf[n] = *(const bf16x8*)(sb + b_base + n * 2048 + ks * 1024);
; #pragma unroll
;       for (int mh = 0; mh < 2; ++mh) {
;         bf16x8 At[4];
; #pragma unroll
;         for (int m = 0; m < 4; ++m) At[m] = *(const bf16x8*)(sb + a_base + (mh * 4 + m) * 2048 + ks * 1024);
;         __builtin_amdgcn_s_setprio(1);
; #pragma unroll
;         for (int m = 0; m < 4; ++m)
; #pragma unroll
;           for (int n = 0; n < 4; ++n) acc[mh * 4 + m][n] = __builtin_amdgcn_mfma_f32_16x16x32_bf16(Bf[n], At[m], acc[mh * 4 + m][n], 0, 0, 0);
;         __builtin_amdgcn_s_setprio(0);
;       }
;       SBAR();
;     }
;     if (t + 1 < nt) { WAIT_V0(); __syncthreads(); }
;   }
.LBB0_1121:
	s_and_b32 s3, s2, 0x10000
	v_or_b32_e32 v150, s3, v149
	v_add_u32_e32 v169, v150, v148
	v_or_b32_e32 v150, s3, v146
	v_add_u32_e32 v178, v150, v147
	ds_read_b128 v[150:153], v169 offset:32768
	ds_read_b128 v[154:157], v169 offset:34816
	ds_read_b128 v[158:161], v169 offset:36864
	ds_read_b128 v[162:165], v169 offset:38912
	ds_read_b128 v[170:173], v178
	ds_read_b128 v[174:177], v178 offset:2048
	ds_read_b128 v[214:217], v178 offset:4096
	ds_read_b128 v[218:221], v178 offset:6144
	v_writelane_b32 v240, s4, 0
	v_writelane_b32 v240, s5, 1
	v_writelane_b32 v240, s6, 2
	v_writelane_b32 v240, s7, 3
	v_writelane_b32 v240, s8, 4
	v_writelane_b32 v240, s9, 5
	v_writelane_b32 v240, s10, 6
	v_readfirstlane_b32 s4, v132
	v_readfirstlane_b32 s5, v133
	s_nop 1
	v_subrev_u32_e32 v238, s4, v132
	s_add_u32 s4, s4, s16
	s_addc_u32 s5, s5, s17
	v_readfirstlane_b32 s6, v134
	v_readfirstlane_b32 s7, v135
	s_nop 1
	v_subrev_u32_e32 v239, s6, v134
	s_add_u32 s6, s6, s16
	s_addc_u32 s7, s7, s17
	v_readfirstlane_b32 s10, v142
	s_xor_b32 s8, s3, 0x10000
	s_nop 0
	s_add_i32 s10, s10, s8
	s_add_i32 m0, s10, 0x0
	s_add_u32 s8, s4, s30
	s_addc_u32 s9, s5, s31
	global_load_lds_dwordx4 v238, s[8:9]
	s_add_i32 m0, s10, 0x8000
	s_add_u32 s8, s6, 0x8400080
	s_addc_u32 s9, s7, 0
	global_load_lds_dwordx4 v239, s[8:9]
	s_add_i32 m0, s10, 0x2000
	s_add_u32 s8, s4, s40
	s_addc_u32 s9, s5, s41
	global_load_lds_dwordx4 v238, s[8:9]
.Lkl_1121:
	s_waitcnt lgkmcnt(3)
	v_mfma_f32_16x16x32_bf16 v[126:129], v[150:153], v[170:173], v[126:129]
	v_mfma_f32_16x16x32_bf16 v[122:125], v[154:157], v[170:173], v[122:125]
	v_mfma_f32_16x16x32_bf16 v[118:121], v[158:161], v[170:173], v[118:121]
	v_mfma_f32_16x16x32_bf16 v[114:117], v[162:165], v[170:173], v[114:117]
	ds_read_b128 v[170:173], v178 offset:8192
	ds_read_b128 v[222:225], v169 offset:33792
	s_add_i32 m0, s10, 0xa000
	s_add_u32 s8, s6, 0x8420080
	s_addc_u32 s9, s7, 0
	global_load_lds_dwordx4 v239, s[8:9]
	s_waitcnt lgkmcnt(4)
	v_mfma_f32_16x16x32_bf16 v[110:113], v[150:153], v[174:177], v[110:113]
	v_mfma_f32_16x16x32_bf16 v[106:109], v[154:157], v[174:177], v[106:109]
	v_mfma_f32_16x16x32_bf16 v[102:105], v[158:161], v[174:177], v[102:105]
	v_mfma_f32_16x16x32_bf16 v[98:101], v[162:165], v[174:177], v[98:101]
	ds_read_b128 v[174:177], v178 offset:10240
	ds_read_b128 v[226:229], v169 offset:35840
	s_add_i32 m0, s10, 0x4000
	s_add_u32 s8, s4, s42
	s_addc_u32 s9, s5, s43
	global_load_lds_dwordx4 v238, s[8:9]
	s_waitcnt lgkmcnt(5)
	v_mfma_f32_16x16x32_bf16 v[94:97], v[150:153], v[214:217], v[94:97]
	v_mfma_f32_16x16x32_bf16 v[90:93], v[154:157], v[214:217], v[90:93]
	v_mfma_f32_16x16x32_bf16 v[86:89], v[158:161], v[214:217], v[86:89]
	v_mfma_f32_16x16x32_bf16 v[82:85], v[162:165], v[214:217], v[82:85]
	ds_read_b128 v[214:217], v178 offset:12288
	ds_read_b128 v[230:233], v169 offset:37888
	s_add_i32 m0, s10, 0xc000
	s_add_u32 s8, s6, 0x8440080
	s_addc_u32 s9, s7, 0
	global_load_lds_dwordx4 v239, s[8:9]
	s_waitcnt lgkmcnt(6)
	v_mfma_f32_16x16x32_bf16 v[78:81], v[150:153], v[218:221], v[78:81]
	v_mfma_f32_16x16x32_bf16 v[74:77], v[154:157], v[218:221], v[74:77]
	v_mfma_f32_16x16x32_bf16 v[70:73], v[158:161], v[218:221], v[70:73]
	v_mfma_f32_16x16x32_bf16 v[66:69], v[162:165], v[218:221], v[66:69]
	ds_read_b128 v[218:221], v178 offset:14336
	ds_read_b128 v[234:237], v169 offset:39936
	s_add_i32 m0, s10, 0x6000
	s_add_u32 s8, s4, s44
	s_addc_u32 s9, s5, s45
	global_load_lds_dwordx4 v238, s[8:9]
	s_waitcnt lgkmcnt(7)
	v_mfma_f32_16x16x32_bf16 v[62:65], v[150:153], v[170:173], v[62:65]
	v_mfma_f32_16x16x32_bf16 v[58:61], v[154:157], v[170:173], v[58:61]
	v_mfma_f32_16x16x32_bf16 v[54:57], v[158:161], v[170:173], v[54:57]
	v_mfma_f32_16x16x32_bf16 v[50:53], v[162:165], v[170:173], v[50:53]
	ds_read_b128 v[170:173], v178 offset:1024
	s_add_i32 m0, s10, 0xe000
	s_add_u32 s8, s6, 0x8460080
	s_addc_u32 s9, s7, 0
	global_load_lds_dwordx4 v239, s[8:9]
	s_waitcnt lgkmcnt(6)
	v_mfma_f32_16x16x32_bf16 v[46:49], v[150:153], v[174:177], v[46:49]
	v_mfma_f32_16x16x32_bf16 v[42:45], v[154:157], v[174:177], v[42:45]
	v_mfma_f32_16x16x32_bf16 v[38:41], v[158:161], v[174:177], v[38:41]
	v_mfma_f32_16x16x32_bf16 v[34:37], v[162:165], v[174:177], v[34:37]
	ds_read_b128 v[174:177], v178 offset:3072
	s_waitcnt lgkmcnt(5)
; #define WAIT_V0() asm volatile("s_waitcnt vmcnt(0)" ::: "memory")
; #define SBAR() __builtin_amdgcn_sched_barrier(0)
; template <int EPI>
; DEVI void gemm_tile(const u16* __restrict__ Ab, long lda, const u16* __restrict__ Bb, long ldb, int K, const EpiArgs& e,
;                     bool have0 = false, const u16* __restrict__ nA = nullptr, const u16* __restrict__ nB = nullptr) {
;     ...
;   for (int t = 0; t < nt; ++t) {
;     const int cur = t & 1;
;     if (t + 1 < nt) GLDS_STAGE(cur ^ 1, t + 1);
;     else if (nA) {
; #pragma unroll
;       for (int i = 0; i < GL; ++i) {
;         __builtin_amdgcn_global_load_lds((const unsigned*)(nA + (long)i * 64 * lda + toffA), (unsigned*)(g_shm + wid * 1024 + i * 8192), 16, 0, 0);
;         __builtin_amdgcn_global_load_lds((const unsigned*)(nB + (long)i * 64 * ldb + toffB), (unsigned*)(g_shm + TILE_B + wid * 1024 + i * 8192), 16, 0, 0);
;       }
;     }
;     const char* sb = g_shm + cur * STAGE_B;
; #pragma unroll
;     for (int ks = 0; ks < 2; ++ks) {
;       bf16x8 Bf[4];
; #pragma unroll
;       for (int n = 0; n < 4; ++n) Bf[n] = *(const bf16x8*)(sb + b_base + n * 2048 + ks * 1024);
; #pragma unroll
;       for (int mh = 0; mh < 2; ++mh) {
;         bf16x8 At[4];
; #pragma unroll
;         for (int m = 0; m < 4; ++m) At[m] = *(const bf16x8*)(sb + a_base + (mh * 4 + m) * 2048 + ks * 1024);
;         __builtin_amdgcn_s_setprio(1);
; #pragma unroll
;         for (int m = 0; m < 4; ++m)
; #pragma unroll
;           for (int n = 0; n < 4; ++n) acc[mh * 4 + m][n] = __builtin_amdgcn_mfma_f32_16x16x32_bf16(Bf[n], At[m], acc[mh * 4 + m][n], 0, 0, 0);
;         __builtin_amdgcn_s_setprio(0);
;       }
;       SBAR();
;     }
;     if (t + 1 < nt) { WAIT_V0(); __syncthreads(); }
;   }
	v_mfma_f32_16x16x32_bf16 v[30:33], v[150:153], v[214:217], v[30:33]
	v_mfma_f32_16x16x32_bf16 v[26:29], v[154:157], v[214:217], v[26:29]
	v_mfma_f32_16x16x32_bf16 v[22:25], v[158:161], v[214:217], v[22:25]
	v_mfma_f32_16x16x32_bf16 v[18:21], v[162:165], v[214:217], v[18:21]
	ds_read_b128 v[214:217], v178 offset:5120
	s_waitcnt lgkmcnt(4)
	v_mfma_f32_16x16x32_bf16 v[14:17], v[150:153], v[218:221], v[14:17]
	v_mfma_f32_16x16x32_bf16 v[10:13], v[154:157], v[218:221], v[10:13]
	v_mfma_f32_16x16x32_bf16 v[6:9], v[158:161], v[218:221], v[6:9]
	v_mfma_f32_16x16x32_bf16 v[2:5], v[162:165], v[218:221], v[2:5]
	ds_read_b128 v[218:221], v178 offset:7168
	s_waitcnt lgkmcnt(3)
	v_mfma_f32_16x16x32_bf16 v[126:129], v[222:225], v[170:173], v[126:129]
	v_mfma_f32_16x16x32_bf16 v[122:125], v[226:229], v[170:173], v[122:125]
	v_mfma_f32_16x16x32_bf16 v[118:121], v[230:233], v[170:173], v[118:121]
	v_mfma_f32_16x16x32_bf16 v[114:117], v[234:237], v[170:173], v[114:117]
	ds_read_b128 v[170:173], v178 offset:9216
	s_waitcnt lgkmcnt(3)
	v_mfma_f32_16x16x32_bf16 v[110:113], v[222:225], v[174:177], v[110:113]
	v_mfma_f32_16x16x32_bf16 v[106:109], v[226:229], v[174:177], v[106:109]
	v_mfma_f32_16x16x32_bf16 v[102:105], v[230:233], v[174:177], v[102:105]
	v_mfma_f32_16x16x32_bf16 v[98:101], v[234:237], v[174:177], v[98:101]
	ds_read_b128 v[174:177], v178 offset:11264
	s_waitcnt lgkmcnt(3)
	v_mfma_f32_16x16x32_bf16 v[94:97], v[222:225], v[214:217], v[94:97]
	v_mfma_f32_16x16x32_bf16 v[90:93], v[226:229], v[214:217], v[90:93]
	v_mfma_f32_16x16x32_bf16 v[86:89], v[230:233], v[214:217], v[86:89]
	v_mfma_f32_16x16x32_bf16 v[82:85], v[234:237], v[214:217], v[82:85]
	ds_read_b128 v[214:217], v178 offset:13312
	s_waitcnt lgkmcnt(3)
	v_mfma_f32_16x16x32_bf16 v[78:81], v[222:225], v[218:221], v[78:81]
	v_mfma_f32_16x16x32_bf16 v[74:77], v[226:229], v[218:221], v[74:77]
	v_mfma_f32_16x16x32_bf16 v[70:73], v[230:233], v[218:221], v[70:73]
	v_mfma_f32_16x16x32_bf16 v[66:69], v[234:237], v[218:221], v[66:69]
	ds_read_b128 v[218:221], v178 offset:15360
	s_waitcnt lgkmcnt(3)
	v_mfma_f32_16x16x32_bf16 v[62:65], v[222:225], v[170:173], v[62:65]
	v_mfma_f32_16x16x32_bf16 v[58:61], v[226:229], v[170:173], v[58:61]
	v_mfma_f32_16x16x32_bf16 v[54:57], v[230:233], v[170:173], v[54:57]
	v_mfma_f32_16x16x32_bf16 v[50:53], v[234:237], v[170:173], v[50:53]
	s_waitcnt lgkmcnt(2)
	v_mfma_f32_16x16x32_bf16 v[46:49], v[222:225], v[174:177], v[46:49]
	v_mfma_f32_16x16x32_bf16 v[42:45], v[226:229], v[174:177], v[42:45]
	v_mfma_f32_16x16x32_bf16 v[38:41], v[230:233], v[174:177], v[38:41]
	v_mfma_f32_16x16x32_bf16 v[34:37], v[234:237], v[174:177], v[34:37]
	s_waitcnt lgkmcnt(0)
	s_waitcnt vmcnt(0)
	s_add_u32 s16, s16, 0x80
	s_addc_u32 s17, s17, 0
	s_add_i32 s2, s2, 0x10000
	s_cmpk_eq_i32 s16, 0x780
	s_waitcnt vmcnt(0)
	s_barrier
	s_cselect_b32 s100, 1, 0
	s_and_b32 s3, s2, 0x10000
	v_or_b32_e32 v150, s3, v149
	v_add_u32_e32 v169, v150, v148
	v_or_b32_e32 v150, s3, v146
	v_add_u32_e32 v178, v150, v147
	ds_read_b128 v[150:153], v169 offset:32768
	ds_read_b128 v[154:157], v169 offset:34816
	ds_read_b128 v[158:161], v169 offset:36864
	ds_read_b128 v[162:165], v169 offset:38912
	ds_read_b128 v[170:173], v178
	ds_read_b128 v[174:177], v178 offset:2048
	s_add_u32 s4, s4, 0x80
	s_addc_u32 s5, s5, 0
	s_add_u32 s6, s6, 0x80
	s_addc_u32 s7, s7, 0
	s_cmp_eq_u32 s100, 1
	s_cbranch_scc1 .Lkl_1121_s1
	v_readfirstlane_b32 s10, v142
	s_xor_b32 s8, s3, 0x10000
	s_nop 0
	s_add_i32 s10, s10, s8
	s_add_i32 m0, s10, 0x0
	s_add_u32 s8, s4, s30
	s_addc_u32 s9, s5, s31
	global_load_lds_dwordx4 v238, s[8:9]
.Lkl_1121_s1:
	v_mfma_f32_16x16x32_bf16 v[30:33], v[222:225], v[214:217], v[30:33]
	v_mfma_f32_16x16x32_bf16 v[26:29], v[226:229], v[214:217], v[26:29]
	v_mfma_f32_16x16x32_bf16 v[22:25], v[230:233], v[214:217], v[22:25]
	v_mfma_f32_16x16x32_bf16 v[18:21], v[234:237], v[214:217], v[18:21]
	ds_read_b128 v[214:217], v178 offset:4096
	s_cmp_eq_u32 s100, 1
	s_cbranch_scc1 .Lkl_1121_s2
	s_add_i32 m0, s10, 0x8000
	s_add_u32 s8, s6, 0x8400080
	s_addc_u32 s9, s7, 0
	global_load_lds_dwordx4 v239, s[8:9]
.Lkl_1121_s2:
	v_mfma_f32_16x16x32_bf16 v[14:17], v[222:225], v[218:221], v[14:17]
	v_mfma_f32_16x16x32_bf16 v[10:13], v[226:229], v[218:221], v[10:13]
	v_mfma_f32_16x16x32_bf16 v[6:9], v[230:233], v[218:221], v[6:9]
	v_mfma_f32_16x16x32_bf16 v[2:5], v[234:237], v[218:221], v[2:5]
	ds_read_b128 v[218:221], v178 offset:6144
	s_cmp_eq_u32 s100, 1
	s_cbranch_scc1 .Lkl_1121_s3
	s_add_i32 m0, s10, 0x2000
	s_add_u32 s8, s4, s40
	s_addc_u32 s9, s5, s41
	global_load_lds_dwordx4 v238, s[8:9]

; DEVI int opq_tid() { int t = threadIdx.x; asm volatile("" : "+v"(t)); return t; }
; #define WAIT_V0() asm volatile("s_waitcnt vmcnt(0)" ::: "memory")
; DEVI int v_st(int k, int c) { const int kk = (k & ~0xC) | ((k & 4) << 1) | ((k & 8) >> 1); return ((kk >> 3) * 4 + (c >> 5)) * 512 + ((kk & 7) * 32 + (c & 31)) * 2; }
; DEVI int v_rd_base(int lane) { return ((lane & 3) << 3) | (((lane >> 2) & 3) << 6) | (((lane >> 4) & 1) << 5) | (((lane >> 5) & 1) << 8); }
; DEVI void attn_item(const u16* __restrict__ Qb, const u16* __restrict__ Kn, const u16* __restrict__ Kr, const u16* __restrict__ Vh, u16* __restrict__ Ob, int seq) {
;   const int tid = opq_tid(), wid = tid >> 6, lane = tid & 63, r32 = lane & 31, hi = lane >> 5;
;   char* V_lds = g_shm; char* K_lds = g_shm + 2 * SHM_V;
;   float* wsl = (float*)(g_shm + 2 * SHM_V + 2 * SHM_K) + wid * 64; float* li_l = wsl; float* al_l = wsl + 32;
;   float m_reg = -1e30f, l_reg = 0.f;
;   f32x16 o[4];
; #pragma unroll
;   for (int d = 0; d < 4; ++d)
; #pragma unroll
;     for (int r = 0; r < 16; ++r) o[d][r] = 0.f;
;   bf16x8 qr[12];
;   const u16* Qw = Qb + (long)(wid * 32 + r32) * 1536 + hi * 8;
; #pragma unroll
;   for (int d0 = 0; d0 < 12; ++d0) qr[d0] = *(const bf16x8*)(Qw + d0 * 16);
;   const int krow = tid >> 3, c8 = tid & 7;
;   const u16* knp = Kn + (long)krow * 2048 + c8 * 8;
;   const u16* krp = Kr + (long)krow * 768 + c8 * 8;
;   const int kwr = krow * KROW + c8 * 16;
;   const int sr = tid >> 4, sc = (tid & 15) * 8, vst0 = v_st(sr, sc), vst1 = v_st(32 + sr, sc);
;   const u16* vp = Vh + (long)sr * 2048 + sc;
;   const int vb0 = (int)(uintptr_t)V_lds + v_rd_base(lane);
;   bf16x8 ks[3], vs0, vs1;
;     ...
;   const int NTk = seq / 64;
;   SLOAD(0); WAIT_V0(); SWRITE(0); __syncthreads();
; DEVI void mla_attn(const Params& P, int g) {
;     ...
;   for (int it0 = blockIdx.x; it0 < nitems; it0 += gridDim.x) {
;     int it = it0;
;     { const int nb = gridDim.x;
;       if ((nb & 7) == 0) { const int w = it0 / nb, b = it0 - w * nb; if ((w + 1) * nb <= nitems) it = w * nb + (b & 7) * (nb >> 3) + (b >> 3); } }
;     const int qb = it % nqb, hh = (it / nqb) & 7, sq = it / (nqb * 8);
;     const long r0 = (long)sq * S;
;     attn_item(q + (r0 + qb * 256) * 1536 + hh * 192, kv + r0 * 2048 + hh * 256, down + r0 * 768 + 640, kv + r0 * 2048 + hh * 256 + 128,
;               o + (r0 + qb * 256) * 1024 + hh * 128, S);
.LBB0_1259:
	s_abs_i32 s6, s2
	s_mul_hi_u32 s7, s6, s33
	s_mul_i32 s10, s7, s15
	s_sub_i32 s10, s6, s10
	s_ashr_i32 s3, s2, 31
	s_add_i32 s11, s7, 1
	s_sub_i32 s12, s10, s15
	s_cmp_ge_u32 s10, s15
	s_cselect_b32 s7, s11, s7
	s_cselect_b32 s10, s12, s10
	s_add_i32 s11, s7, 1
	s_cmp_ge_u32 s10, s15
	s_cselect_b32 s7, s11, s7
	s_xor_b32 s7, s7, s3
	s_sub_i32 s7, s7, s3
	s_mul_i32 s10, s7, s15
	s_sub_i32 s10, s2, s10
	s_mul_hi_u32 s2, s6, s68
	s_and_b32 s40, s7, 7
	s_mul_i32 s7, s2, s21
	s_sub_i32 s6, s6, s7
	s_add_i32 s7, s2, 1
	s_sub_i32 s11, s6, s21
	s_cmp_ge_u32 s6, s21
	s_cselect_b32 s2, s7, s2
	s_cselect_b32 s6, s11, s6
	s_add_i32 s7, s2, 1
	s_cmp_ge_u32 s6, s21
	s_cselect_b32 s2, s7, s2
	s_xor_b32 s2, s2, s3
	s_sub_i32 s2, s2, s3
	s_ashr_i32 s3, s2, 31
	s_lshl_b64 s[12:13], s[2:3], s31
	s_lshl_b32 s2, s10, 8
	s_ashr_i32 s3, s2, 31
	s_add_u32 s6, s12, s2
	s_addc_u32 s7, s13, s3
	s_mul_i32 s2, s7, 0xc00
	s_mul_hi_u32 s3, s6, 0xc00
	s_add_i32 s3, s3, s2
	s_mul_i32 s2, s6, 0xc00
	v_readlane_b32 s10, v253, 48
	s_add_u32 s2, s10, s2
	v_readlane_b32 s10, v253, 49
	s_addc_u32 s3, s10, s3
	s_mul_i32 s10, s40, 0x180
	s_add_u32 s10, s2, s10
	s_addc_u32 s11, s3, 0
	s_lshl_b64 s[2:3], s[12:13], 12
	v_readlane_b32 s41, v253, 50
	s_add_u32 s41, s41, s2
	v_readlane_b32 s42, v253, 51
	s_addc_u32 s43, s42, s3
	s_lshl_b32 s48, s40, 9
	v_mov_b32_e32 v34, v167
	s_add_u32 s42, s41, s48
	s_mulk_i32 s13, 0x600
	s_mul_hi_u32 s41, s12, 0x600
	s_addc_u32 s43, s43, 0
	v_ashrrev_i32_e32 v22, 3, v34
	s_add_i32 s49, s41, s13
	s_mul_i32 s58, s12, 0x600
	v_ashrrev_i32_e32 v23, 31, v22
	s_add_u32 s12, s17, s58
	v_lshlrev_b64 v[24:25], 12, v[22:23]
	v_lshlrev_b32_e32 v23, 4, v34
	s_addc_u32 s13, s18, s49
	v_lshl_add_u64 v[2:3], s[42:43], 0, v[24:25]
	v_and_b32_e32 v26, 0x70, v23
	v_mov_b32_e32 v27, v1
	v_lshl_add_u64 v[6:7], v[2:3], 0, v[26:27]
	v_mov_b64_e32 v[2:3], s[12:13]
	s_movk_i32 s64, 0x600
	v_ashrrev_i32_e32 v28, 4, v34
	v_mad_i64_i32 v[2:3], s[12:13], v22, s64, v[2:3]
	v_lshlrev_b32_e32 v35, 3, v34
	v_ashrrev_i32_e32 v29, 31, v28
	v_lshl_add_u64 v[10:11], v[2:3], 0, v[26:27]
	v_and_b32_e32 v0, 0x78, v35
	v_lshlrev_b64 v[30:31], 12, v[28:29]
	s_mov_b32 s12, 0x16500000
	v_lshl_add_u64 v[2:3], s[42:43], 0, v[30:31]
	v_lshlrev_b32_e32 v4, 1, v0
	v_mov_b32_e32 v5, v1
	v_add_co_u32_e32 v10, vcc, s12, v10
	v_lshl_add_u64 v[18:19], v[2:3], 0, v[4:5]
	s_nop 0
	v_addc_co_u32_e32 v11, vcc, 0, v11, vcc
	s_mov_b32 s12, 0x20000
	global_load_dwordx4 v[2:5], v[6:7], off
	s_nop 0
	global_load_dwordx4 v[6:9], v[6:7], off offset:128
	s_nop 0
	global_load_dwordx4 v[10:13], v[10:11], off offset:1280
	s_nop 0
	global_load_dwordx4 v[14:17], v[18:19], off offset:256
	v_add_co_u32_e32 v18, vcc, s12, v18
	v_ashrrev_i32_e32 v29, 1, v34
	s_movk_i32 s12, 0xffe0
	v_bfe_u32 v213, v34, 5, 1
	v_bfi_b32 v0, s12, v29, v34
	v_mov_b64_e32 v[32:33], s[10:11]
	v_mad_i64_i32 v[32:33], s[10:11], v0, s63, v[32:33]
	v_lshlrev_b32_e32 v0, 4, v213
	v_addc_co_u32_e32 v19, vcc, 0, v19, vcc
	v_lshl_add_u64 v[32:33], v[32:33], 0, v[0:1]
	global_load_dwordx4 v[18:21], v[18:19], off offset:256
	s_nop 0
	global_load_dwordx4 v[142:145], v[32:33], off
	global_load_dwordx4 v[138:141], v[32:33], off offset:32
	global_load_dwordx4 v[134:137], v[32:33], off offset:64
	global_load_dwordx4 v[130:133], v[32:33], off offset:96
	global_load_dwordx4 v[126:129], v[32:33], off offset:128
	global_load_dwordx4 v[122:125], v[32:33], off offset:160
	global_load_dwordx4 v[118:121], v[32:33], off offset:192
	global_load_dwordx4 v[114:117], v[32:33], off offset:224
	global_load_dwordx4 v[110:113], v[32:33], off offset:256
	global_load_dwordx4 v[106:109], v[32:33], off offset:288
	global_load_dwordx4 v[102:105], v[32:33], off offset:320
	global_load_dwordx4 v[98:101], v[32:33], off offset:352
	v_and_b32_e32 v170, 0xffffffe0, v29
	v_and_b32_e32 v29, 0xfffff0, v28
	v_lshlrev_b32_e32 v33, 1, v28
	v_and_or_b32 v29, v33, 8, v29
	v_lshrrev_b32_e32 v33, 1, v28
	v_lshrrev_b32_e32 v29, 1, v29
	v_bfe_u32 v36, v35, 5, 2
	v_and_b32_e32 v37, 3, v28
	v_or_b32_e32 v29, v29, v36
	v_and_or_b32 v33, v33, 4, v37
	v_lshlrev_b32_e32 v29, 9, v29
	v_lshlrev_b32_e32 v33, 6, v33
	v_and_b32_e32 v37, 48, v23
	v_add_u32_e32 v28, 32, v28
	v_or3_b32 v216, v29, v33, v37
	v_and_b32_e32 v29, 0xfffff0, v28
	v_lshlrev_b32_e32 v28, 1, v28
	v_and_or_b32 v28, v28, 8, v29
	v_lshrrev_b32_e32 v28, 1, v28
	v_or_b32_e32 v28, v28, v36
	v_lshlrev_b32_e32 v28, 9, v28
	v_mad_u64_u32 v[172:173], s[10:11], v22, s65, v[26:27]
	v_or3_b32 v217, v28, v33, v37
	s_waitcnt vmcnt(0)
	s_waitcnt vmcnt(16)
	ds_write_b128 v172, v[2:5] offset:32768
	s_waitcnt vmcnt(15)
	ds_write_b128 v172, v[6:9] offset:32896
	s_waitcnt vmcnt(14)
	ds_write_b128 v172, v[10:13] offset:33024
	s_waitcnt vmcnt(13)
	ds_write_b128 v216, v[14:17]
	s_waitcnt vmcnt(12)
	ds_write_b128 v217, v[18:21]
	v_lshlrev_b32_e32 v2, 1, v34
	v_and_b32_e32 v2, 32, v2
	s_movk_i32 s10, 0x118
	v_and_or_b32 v2, v35, s10, v2
	s_movk_i32 s12, 0xc0
	v_and_or_b32 v214, v23, s12, v2
	v_and_b32_e32 v2, 15, v34
	s_add_u32 s12, s8, s58
	v_lshl_add_u64 v[174:175], s[2:3], 0, v[30:31]
	v_lshlrev_b32_e32 v2, 4, v2
	s_addc_u32 s13, s9, s49
	v_and_b32_e32 v32, 0x3fffffc0, v34
	v_or3_b32 v174, v174, s48, v2
	v_mov_b64_e32 v[2:3], s[12:13]
	v_lshl_add_u32 v171, v32, 2, v212
	v_and_b32_e32 v32, 63, v34
	v_mad_i64_i32 v[2:3], s[12:13], v22, s64, v[2:3]
	v_lshl_add_u64 v[178:179], s[2:3], 0, v[24:25]
	v_mov_b32_e32 v16, v1
	v_mov_b32_e32 v17, v1
	v_and_b32_e32 v169, 31, v34
	v_cmp_gt_u32_e64 s[10:11], 32, v32
	v_lshl_add_u64 v[176:177], v[2:3], 0, v[26:27]
	v_or3_b32 v178, v178, s48, v26
	v_mov_b32_e32 v2, v1
	v_mov_b32_e32 v3, v1
	v_mov_b32_e32 v4, v1
	v_mov_b32_e32 v5, v1
	v_mov_b32_e32 v6, v1
	v_mov_b32_e32 v7, v1
	v_mov_b32_e32 v8, v1
	v_mov_b32_e32 v9, v1
	v_mov_b32_e32 v10, v1
	v_mov_b32_e32 v11, v1
	v_mov_b32_e32 v12, v1
	v_mov_b32_e32 v13, v1
	v_mov_b32_e32 v14, v1
	v_mov_b32_e32 v15, v1
	v_mov_b64_e32 v[64:65], v[16:17]
	v_mov_b64_e32 v[48:49], v[16:17]
	v_mov_b64_e32 v[32:33], v[16:17]
	s_mov_b32 s41, 0
	v_mul_u32_u24_e32 v218, 0x190, v169
	v_lshl_or_b32 v173, v169, 2, v171
	v_mad_u32_u24 v219, v169, s65, v0
	v_mov_b32_e32 v221, 0
	v_mov_b32_e32 v215, 0xf149f2ca
	v_mov_b64_e32 v[62:63], v[14:15]
	v_mov_b64_e32 v[60:61], v[12:13]
	v_mov_b64_e32 v[58:59], v[10:11]
	v_mov_b64_e32 v[56:57], v[8:9]
	v_mov_b64_e32 v[54:55], v[6:7]
	v_mov_b64_e32 v[52:53], v[4:5]
	v_mov_b64_e32 v[50:51], v[2:3]
	v_mov_b64_e32 v[46:47], v[14:15]
	v_mov_b64_e32 v[44:45], v[12:13]
	v_mov_b64_e32 v[42:43], v[10:11]
	v_mov_b64_e32 v[40:41], v[8:9]
	v_mov_b64_e32 v[38:39], v[6:7]
	v_mov_b64_e32 v[36:37], v[4:5]
	v_mov_b64_e32 v[34:35], v[2:3]
	v_mov_b64_e32 v[30:31], v[14:15]
	v_mov_b64_e32 v[28:29], v[12:13]
	v_mov_b64_e32 v[26:27], v[10:11]
	v_mov_b64_e32 v[24:25], v[8:9]
	v_mov_b64_e32 v[22:23], v[6:7]
	v_mov_b64_e32 v[20:21], v[4:5]
	v_mov_b64_e32 v[18:19], v[2:3]
	s_waitcnt lgkmcnt(0)
	s_barrier
	s_cmp_eq_u32 s101, 1
	s_cbranch_scc0 .Latt_pp_x0
	s_barrier
; #define SLOAD(k0) do { ks[0] = *(const bf16x8*)(knp + (long)(k0) * 2048); ks[1] = *(const bf16x8*)(knp + (long)(k0) * 2048 + 64);          \
;     ks[2] = *(const bf16x8*)(krp + (long)(k0) * 768);                                                                           \
;     vs0 = *(const bf16x8*)(vp + (long)(k0) * 2048); vs1 = *(const bf16x8*)(vp + (long)((k0) + 32) * 2048); } while (0)
; DEVI void attn_item(const u16* __restrict__ Qb, const u16* __restrict__ Kn, const u16* __restrict__ Kr, const u16* __restrict__ Vh, u16* __restrict__ Ob, int seq) {
;     ...
;   for (int j = 0; j < NTk; ++j) {
;     const int cur = j & 1;
;     if (j + 1 < NTk) SLOAD((j + 1) * 64);
;     f32x16 p0, p1;
; #pragma unroll
;     for (int r = 0; r < 16; ++r) { p0[r] = 0.f; p1[r] = 0.f; }
;     const char* Ks = K_lds + cur * SHM_K;
; #pragma unroll
;     for (int d0 = 0; d0 < 12; ++d0) {
;       const int cb = (d0 * 16 + hi * 8) * 2;
;       const bf16x8 b0 = *(const bf16x8*)(Ks + r32 * KROW + cb);
;       const bf16x8 b1 = *(const bf16x8*)(Ks + (32 + r32) * KROW + cb);
;       p0 = __builtin_amdgcn_mfma_f32_32x32x16_bf16(b0, qr[d0], p0, 0, 0, 0);
;       p1 = __builtin_amdgcn_mfma_f32_32x32x16_bf16(b1, qr[d0], p1, 0, 0, 0);
;     }
;     float mn, alpha;
;     partialSM(p0, p1, m_reg, mn, alpha);
.Latt_pp_x0:
.LBB0_1260:
	v_lshl_add_u64 v[66:67], s[34:35], 0, v[178:179]
	v_add_co_u32_e32 v66, vcc, 0x31540000, v66
	s_mov_b32 s2, 0x31540000
	s_nop 0
	v_addc_co_u32_e32 v67, vcc, 0, v67, vcc
	global_load_dwordx4 v[146:149], v[66:67], off
	global_load_dwordx4 v[150:153], v[66:67], off offset:128
	v_lshl_add_u64 v[66:67], s[34:35], 0, v[176:177]
	v_add_co_u32_e32 v66, vcc, 0x16518000, v66
	s_and_b32 s42, s41, 1
	s_nop 0
	v_addc_co_u32_e32 v67, vcc, 0, v67, vcc
	global_load_dwordx4 v[154:157], v[66:67], off offset:1280
	v_lshl_add_u64 v[66:67], s[34:35], 0, v[174:175]
	v_add_co_u32_e32 v68, vcc, s2, v66
	s_mul_i32 s2, s42, 0x6400
	s_nop 0
	v_addc_co_u32_e32 v69, vcc, 0, v67, vcc
	v_add_co_u32_e32 v66, vcc, 0x31560000, v66
	v_add_u32_e32 v204, s2, v219
	s_nop 0
	v_addc_co_u32_e32 v67, vcc, 0, v67, vcc
	global_load_dwordx4 v[158:161], v[68:69], off offset:256
	global_load_dwordx4 v[162:165], v[66:67], off offset:256
	ds_read_b128 v[66:69], v204 offset:45568
	ds_read_b128 v[70:73], v204 offset:32768
	ds_read_b128 v[192:195], v204 offset:32800
	ds_read_b128 v[198:201], v204 offset:45600
	ds_read_b128 v[228:231], v204 offset:32832
	ds_read_b128 v[232:235], v204 offset:45632
	ds_read_b128 v[236:239], v204 offset:32864
	ds_read_b128 v[240:243], v204 offset:45664
	s_waitcnt vmcnt(16) lgkmcnt(6)
	v_mfma_f32_32x32x16_bf16 v[82:97], v[70:73], v[142:145], 0
	v_mfma_f32_32x32x16_bf16 v[66:81], v[66:69], v[142:145], 0
	s_waitcnt vmcnt(15) lgkmcnt(4)
	v_mfma_f32_32x32x16_bf16 v[82:97], v[192:195], v[138:141], v[82:97]
	v_mfma_f32_32x32x16_bf16 v[66:81], v[198:201], v[138:141], v[66:81]
	ds_read_b128 v[192:195], v204 offset:32896
	ds_read_b128 v[198:201], v204 offset:45696
	s_waitcnt vmcnt(14) lgkmcnt(4)
	v_mfma_f32_32x32x16_bf16 v[82:97], v[228:231], v[134:137], v[82:97]
	v_mfma_f32_32x32x16_bf16 v[66:81], v[232:235], v[134:137], v[66:81]
	ds_read_b128 v[228:231], v204 offset:32928
	ds_read_b128 v[232:235], v204 offset:45728
	s_waitcnt vmcnt(13) lgkmcnt(4)
	v_mfma_f32_32x32x16_bf16 v[82:97], v[236:239], v[130:133], v[82:97]
	v_mfma_f32_32x32x16_bf16 v[66:81], v[240:243], v[130:133], v[66:81]
	ds_read_b128 v[236:239], v204 offset:32960
	ds_read_b128 v[240:243], v204 offset:45760
	s_waitcnt vmcnt(12) lgkmcnt(4)
	v_mfma_f32_32x32x16_bf16 v[82:97], v[192:195], v[126:129], v[82:97]
	v_mfma_f32_32x32x16_bf16 v[66:81], v[198:201], v[126:129], v[66:81]
	ds_read_b128 v[192:195], v204 offset:32992
	ds_read_b128 v[198:201], v204 offset:45792
	s_waitcnt vmcnt(11) lgkmcnt(4)
	v_mfma_f32_32x32x16_bf16 v[82:97], v[228:231], v[122:125], v[82:97]
	v_mfma_f32_32x32x16_bf16 v[66:81], v[232:235], v[122:125], v[66:81]
	ds_read_b128 v[228:231], v204 offset:33024
	ds_read_b128 v[232:235], v204 offset:45824
	s_waitcnt vmcnt(10) lgkmcnt(4)
	v_mfma_f32_32x32x16_bf16 v[82:97], v[236:239], v[118:121], v[82:97]
	v_mfma_f32_32x32x16_bf16 v[66:81], v[240:243], v[118:121], v[66:81]
	ds_read_b128 v[236:239], v204 offset:33056
	ds_read_b128 v[240:243], v204 offset:45856
	s_waitcnt vmcnt(9) lgkmcnt(4)
	v_mfma_f32_32x32x16_bf16 v[82:97], v[192:195], v[114:117], v[82:97]
	v_mfma_f32_32x32x16_bf16 v[66:81], v[198:201], v[114:117], v[66:81]
	ds_read_b128 v[192:195], v204 offset:33088
	ds_read_b128 v[198:201], v204 offset:45888
	s_waitcnt vmcnt(8) lgkmcnt(4)
	v_mfma_f32_32x32x16_bf16 v[82:97], v[228:231], v[110:113], v[82:97]
	v_mfma_f32_32x32x16_bf16 v[66:81], v[232:235], v[110:113], v[66:81]
	ds_read_b128 v[228:231], v204 offset:33120
	ds_read_b128 v[232:235], v204 offset:45920
	s_waitcnt vmcnt(7) lgkmcnt(4)
	v_mfma_f32_32x32x16_bf16 v[82:97], v[236:239], v[106:109], v[82:97]
	v_mfma_f32_32x32x16_bf16 v[66:81], v[240:243], v[106:109], v[66:81]
	s_waitcnt vmcnt(6) lgkmcnt(2)
	v_mfma_f32_32x32x16_bf16 v[82:97], v[192:195], v[102:105], v[82:97]
	v_mfma_f32_32x32x16_bf16 v[66:81], v[198:201], v[102:105], v[66:81]
	s_waitcnt vmcnt(5) lgkmcnt(0)
	v_mfma_f32_32x32x16_bf16 v[82:97], v[228:231], v[98:101], v[82:97]
	v_mfma_f32_32x32x16_bf16 v[66:81], v[232:235], v[98:101], v[66:81]
	s_xor_b32 s2, s42, 1
	s_mul_i32 s3, s2, 0x6400
	v_add_u32_e32 v244, s3, v172
	s_waitcnt vmcnt(4)
	ds_write_b128 v244, v[146:149] offset:32768
	s_waitcnt vmcnt(3)
	ds_write_b128 v244, v[150:153] offset:32896
	s_waitcnt vmcnt(2)
	ds_write_b128 v244, v[154:157] offset:33024
	s_waitcnt lgkmcnt(0)
	s_barrier
	s_nop 9
	v_max_f32_e32 v192, v83, v83
	v_max_f32_e32 v193, v82, v82
	v_max_f32_e32 v192, v193, v192
	v_max3_f32 v192, v192, v84, v85
	v_max3_f32 v192, v192, v86, v87
	v_max3_f32 v192, v192, v88, v89
	v_max3_f32 v192, v192, v90, v91
	v_max3_f32 v192, v192, v92, v93
	v_max3_f32 v192, v192, v94, v95
	v_max3_f32 v192, v192, v96, v97
	v_max3_f32 v192, v192, v66, v67
	v_max3_f32 v192, v192, v68, v69
	v_max3_f32 v192, v192, v70, v71
	v_max3_f32 v192, v192, v72, v73
	v_max3_f32 v192, v192, v74, v75
	v_max3_f32 v192, v192, v76, v77
	v_max3_f32 v192, v192, v78, v79
	v_max3_f32 v192, v192, v80, v81
	v_mov_b32_e32 v193, v192
	s_nop 1
	v_permlane32_swap_b32_e32 v192, v193
	v_max_f32_e32 v193, v193, v193
	v_max_f32_e32 v192, v192, v192
	v_max_f32_e32 v192, v192, v193
	v_sub_f32_e32 v193, v192, v215
	v_cmp_ge_f32_e32 vcc, s90, v193
	v_max_f32_e32 v193, v215, v215
	v_max_f32_e32 v220, v193, v192
	v_sub_f32_e32 v192, v215, v220
	v_mul_f32_e32 v192, 0x3dd53b94, v192
	v_exp_f32_e32 v192, v192
	s_cmp_eq_u64 vcc, exec
	s_cselect_b64 s[12:13], -1, 0
	v_cndmask_b32_e64 v222, v192, 1.0, s[12:13]
	v_cmp_gt_f32_e32 vcc, 1.0, v222
	s_cbranch_vccz .LBB0_1264
; #define WAIT_L0() asm volatile("s_waitcnt lgkmcnt(0)" ::: "memory")
; #define SBAR() __builtin_amdgcn_sched_barrier(0)
; DEVI int crow(int r, int hi) { return (r & 3) + 8 * (r >> 2) + 4 * hi; }
; DEVI void partialSM(f32x16& p0, f32x16& p1, float& m_reg, float& mn, float& alpha) {
;     ...
;   const float mnC = -mn * C;
; #pragma unroll
;   for (int r = 0; r < 16; ++r) p0[r] = __builtin_amdgcn_exp2f(fmaf(p0[r], C, mnC));
; #pragma unroll
;   for (int r = 0; r < 16; ++r) p1[r] = __builtin_amdgcn_exp2f(fmaf(p1[r], C, mnC));
; }
; DEVI void finishSM(f32x16& p0, f32x16& p1, float alpha, float& l_reg, bf16x8& pa0, bf16x8& pa1, bf16x8& pa2, bf16x8& pa3) {
;   float ps = 0;
; #pragma unroll
;   for (int r = 0; r < 16; ++r) ps += p0[r];
; #pragma unroll
;   for (int r = 0; r < 16; ++r) ps += p1[r];
;   { auto rr = __builtin_amdgcn_permlane32_swap(__float_as_uint(ps), __float_as_uint(ps), false, false);
;     ps = __uint_as_float(rr[0]) + __uint_as_float(rr[1]); }
;   l_reg = l_reg * alpha + ps;
;     ...
;   PK4(p0, 0, pa0); PK4(p0, 8, pa1); PK4(p1, 0, pa2); PK4(p1, 8, pa3);
; DEVI void attn_item(const u16* __restrict__ Qb, const u16* __restrict__ Kn, const u16* __restrict__ Kr, const u16* __restrict__ Vh, u16* __restrict__ Ob, int seq) {
;     ...
;     if (__any(alpha < 1.f)) {
;       if (hi == 0) al_l[r32] = alpha;
;       WAIT_L0();
; #pragma unroll
;       for (int d = 0; d < 4; ++d)
; #pragma unroll
;         for (int r = 0; r < 16; ++r) o[d][r] *= al_l[crow(r, hi)];
;     }
;     bf16x8 pa0, pa1, pa2, pa3;
;     finishSM(p0, p1, alpha, l_reg, pa0, pa1, pa2, pa3);
;     SBAR();
;     const int vb = vb0 + cur * SHM_V;
;     pv_pipe(o, vb, pa0, pa1, pa2, pa3);
	s_and_saveexec_b64 s[2:3], s[10:11]
	ds_write_b32 v173, v222 offset:128
	s_or_b64 exec, exec, s[2:3]
	s_waitcnt lgkmcnt(0)
	v_add_u32_e32 v223, v171, v0
	ds_read_b128 v[192:195], v223 offset:224
	ds_read_b128 v[198:201], v223 offset:192
	ds_read_b128 v[204:207], v223 offset:160
	ds_read_b128 v[224:227], v223 offset:128
	s_waitcnt lgkmcnt(3)
	v_pk_mul_f32 v[14:15], v[14:15], v[192:193]
	s_waitcnt lgkmcnt(2)
	v_pk_mul_f32 v[10:11], v[10:11], v[198:199]
	s_waitcnt lgkmcnt(1)
	v_pk_mul_f32 v[6:7], v[6:7], v[204:205]
	v_pk_mul_f32 v[16:17], v[16:17], v[194:195]
	v_pk_mul_f32 v[12:13], v[12:13], v[200:201]
	v_pk_mul_f32 v[8:9], v[8:9], v[206:207]
	s_waitcnt lgkmcnt(0)
	v_pk_mul_f32 v[4:5], v[4:5], v[226:227]
	v_pk_mul_f32 v[2:3], v[2:3], v[224:225]
	v_pk_mul_f32 v[62:63], v[62:63], v[192:193]
	v_pk_mul_f32 v[58:59], v[58:59], v[198:199]
	v_pk_mul_f32 v[54:55], v[54:55], v[204:205]
	v_pk_mul_f32 v[64:65], v[64:65], v[194:195]
	v_pk_mul_f32 v[60:61], v[60:61], v[200:201]
	v_pk_mul_f32 v[56:57], v[56:57], v[206:207]
	v_pk_mul_f32 v[52:53], v[52:53], v[226:227]
	v_pk_mul_f32 v[50:51], v[50:51], v[224:225]
	v_pk_mul_f32 v[46:47], v[46:47], v[192:193]
	v_pk_mul_f32 v[42:43], v[42:43], v[198:199]
	v_pk_mul_f32 v[38:39], v[38:39], v[204:205]
	v_pk_mul_f32 v[48:49], v[48:49], v[194:195]
	v_pk_mul_f32 v[44:45], v[44:45], v[200:201]
	v_pk_mul_f32 v[40:41], v[40:41], v[206:207]
	v_pk_mul_f32 v[36:37], v[36:37], v[226:227]
	v_pk_mul_f32 v[34:35], v[34:35], v[224:225]
	v_pk_mul_f32 v[30:31], v[30:31], v[192:193]
	v_pk_mul_f32 v[26:27], v[26:27], v[198:199]
	v_pk_mul_f32 v[22:23], v[22:23], v[204:205]
	v_pk_mul_f32 v[32:33], v[32:33], v[194:195]
	v_pk_mul_f32 v[28:29], v[28:29], v[200:201]
	v_pk_mul_f32 v[24:25], v[24:25], v[206:207]
	v_pk_mul_f32 v[20:21], v[20:21], v[226:227]
	v_pk_mul_f32 v[18:19], v[18:19], v[224:225]
.LBB0_1264:
	v_cndmask_b32_e64 v215, v220, v215, s[12:13]
	v_mul_f32_e32 v192, 0xbdd53b94, v215
	v_fmamk_f32 v66, v66, 0x3dd53b94, v192
	v_exp_f32_e32 v193, v66
	v_fmamk_f32 v66, v67, 0x3dd53b94, v192
	v_exp_f32_e32 v194, v66
	v_fmamk_f32 v66, v68, 0x3dd53b94, v192
	v_exp_f32_e32 v195, v66
	v_fmamk_f32 v66, v69, 0x3dd53b94, v192
	v_exp_f32_e32 v198, v66
	v_fmamk_f32 v66, v70, 0x3dd53b94, v192
	v_exp_f32_e32 v199, v66
	v_fmamk_f32 v66, v71, 0x3dd53b94, v192
	v_exp_f32_e32 v200, v66
	v_fmamk_f32 v66, v72, 0x3dd53b94, v192
	v_exp_f32_e32 v201, v66
	v_fmamk_f32 v66, v73, 0x3dd53b94, v192
	v_exp_f32_e32 v204, v66
	v_fmamk_f32 v66, v74, 0x3dd53b94, v192
	v_exp_f32_e32 v205, v66
	v_fmamk_f32 v66, v75, 0x3dd53b94, v192
	v_fmamk_f32 v82, v82, 0x3dd53b94, v192
	v_exp_f32_e32 v206, v66
	v_fmamk_f32 v66, v76, 0x3dd53b94, v192
	v_exp_f32_e32 v82, v82
	v_fmamk_f32 v83, v83, 0x3dd53b94, v192
	v_exp_f32_e32 v207, v66
	v_fmamk_f32 v66, v77, 0x3dd53b94, v192
	v_exp_f32_e32 v83, v83
	v_fmamk_f32 v84, v84, 0x3dd53b94, v192
	v_exp_f32_e32 v223, v66
	v_fmamk_f32 v66, v78, 0x3dd53b94, v192
	v_exp_f32_e32 v84, v84
	v_fmamk_f32 v85, v85, 0x3dd53b94, v192
	v_exp_f32_e32 v224, v66
	v_fmamk_f32 v66, v79, 0x3dd53b94, v192
	v_exp_f32_e32 v85, v85
	v_fmamk_f32 v86, v86, 0x3dd53b94, v192
	v_exp_f32_e32 v225, v66
	v_fmamk_f32 v66, v80, 0x3dd53b94, v192
	v_exp_f32_e32 v86, v86
	v_fmamk_f32 v87, v87, 0x3dd53b94, v192
	v_exp_f32_e32 v226, v66
	v_add_f32_e32 v66, 0, v82
	v_exp_f32_e32 v87, v87
	v_fmamk_f32 v88, v88, 0x3dd53b94, v192
	v_add_f32_e32 v66, v83, v66
	v_exp_f32_e32 v88, v88
	v_fmamk_f32 v89, v89, 0x3dd53b94, v192
	v_add_f32_e32 v66, v84, v66
	v_exp_f32_e32 v89, v89
	v_fmamk_f32 v90, v90, 0x3dd53b94, v192
	v_add_f32_e32 v66, v85, v66
	v_exp_f32_e32 v90, v90
	v_fmamk_f32 v91, v91, 0x3dd53b94, v192
	v_add_f32_e32 v66, v86, v66
	v_exp_f32_e32 v91, v91
	v_fmamk_f32 v92, v92, 0x3dd53b94, v192
	v_add_f32_e32 v66, v87, v66
	v_exp_f32_e32 v92, v92
	v_fmamk_f32 v93, v93, 0x3dd53b94, v192
	v_add_f32_e32 v66, v88, v66
	v_exp_f32_e32 v93, v93
	v_fmamk_f32 v94, v94, 0x3dd53b94, v192
	v_add_f32_e32 v66, v89, v66
	v_exp_f32_e32 v94, v94
	v_fmamk_f32 v95, v95, 0x3dd53b94, v192
	v_add_f32_e32 v66, v90, v66
	v_exp_f32_e32 v95, v95
	v_fmamk_f32 v96, v96, 0x3dd53b94, v192
	v_add_f32_e32 v66, v91, v66
	v_exp_f32_e32 v96, v96
	v_fmamk_f32 v97, v97, 0x3dd53b94, v192
	v_add_f32_e32 v66, v92, v66
	v_exp_f32_e32 v97, v97
	v_add_f32_e32 v66, v93, v66
	v_add_f32_e32 v66, v94, v66
	v_add_f32_e32 v66, v95, v66
	v_add_f32_e32 v66, v96, v66
	v_add_f32_e32 v66, v97, v66
	v_add_f32_e32 v66, v193, v66
	v_add_f32_e32 v66, v194, v66
	v_add_f32_e32 v66, v195, v66
	v_add_f32_e32 v66, v198, v66
	v_add_f32_e32 v66, v199, v66
	v_add_f32_e32 v66, v200, v66
	v_add_f32_e32 v66, v201, v66
	v_add_f32_e32 v66, v204, v66
	v_add_f32_e32 v66, v205, v66
	v_add_f32_e32 v66, v206, v66
	v_fmac_f32_e32 v192, 0x3dd53b94, v81
	v_add_f32_e32 v66, v207, v66
	v_exp_f32_e32 v81, v192
	v_add_f32_e32 v66, v223, v66
	v_add_f32_e32 v66, v224, v66
	v_add_f32_e32 v66, v225, v66
	v_add_f32_e32 v66, v226, v66
	v_add_f32_e32 v66, v81, v66
	v_mov_b32_e32 v67, v66
	s_nop 1
	v_permlane32_swap_b32_e32 v66, v67
	v_add_f32_e32 v220, v66, v67
	s_add_i32 s41, s41, 1
	v_fmac_f32_e32 v220, v221, v222
	v_cvt_pk_bf16_f32 v66, v82, v83
	v_cvt_pk_bf16_f32 v67, v84, v85
	v_cvt_pk_bf16_f32 v68, v86, v87
	v_cvt_pk_bf16_f32 v69, v88, v89
	v_cvt_pk_bf16_f32 v70, v90, v91
	v_cvt_pk_bf16_f32 v71, v92, v93
	v_cvt_pk_bf16_f32 v72, v94, v95
	v_cvt_pk_bf16_f32 v73, v96, v97
	v_cvt_pk_bf16_f32 v74, v193, v194
	v_cvt_pk_bf16_f32 v75, v195, v198
	v_cvt_pk_bf16_f32 v76, v199, v200
	v_cvt_pk_bf16_f32 v77, v201, v204
	v_cvt_pk_bf16_f32 v78, v205, v206
	v_cvt_pk_bf16_f32 v79, v207, v223
	v_cvt_pk_bf16_f32 v80, v224, v225
	v_cvt_pk_bf16_f32 v81, v226, v81
	v_permlane32_swap_b32_e32 v66, v68
	v_permlane32_swap_b32_e32 v67, v69
	v_permlane32_swap_b32_e32 v70, v72
	v_permlane32_swap_b32_e32 v71, v73
	v_permlane32_swap_b32_e32 v74, v76
	v_permlane32_swap_b32_e32 v75, v77
	v_permlane32_swap_b32_e32 v78, v80
	v_permlane32_swap_b32_e32 v79, v81
	v_lshl_or_b32 v221, s42, 14, v214
	ds_read_b64_tr_b16 v[82:83], v221 offset:0
	ds_read_b64_tr_b16 v[84:85], v221 offset:0x800
	ds_read_b64_tr_b16 v[86:87], v221 offset:0x1000
	ds_read_b64_tr_b16 v[88:89], v221 offset:0x1800
	ds_read_b64_tr_b16 v[90:91], v221 offset:0x2000
	ds_read_b64_tr_b16 v[92:93], v221 offset:0x2800
	ds_read_b64_tr_b16 v[94:95], v221 offset:0x3000
	ds_read_b64_tr_b16 v[96:97], v221 offset:0x3800
	ds_read_b64_tr_b16 v[192:193], v221 offset:0x200
	ds_read_b64_tr_b16 v[194:195], v221 offset:0xa00
	ds_read_b64_tr_b16 v[198:199], v221 offset:0x1200
	ds_read_b64_tr_b16 v[200:201], v221 offset:0x1a00
	ds_read_b64_tr_b16 v[204:205], v221 offset:0x2200
	ds_read_b64_tr_b16 v[206:207], v221 offset:0x2a00
	ds_read_b64_tr_b16 v[222:223], v221 offset:0x3200
	ds_read_b64_tr_b16 v[224:225], v221 offset:0x3a00
	s_waitcnt lgkmcnt(8)
; #define WAIT_V0() asm volatile("s_waitcnt vmcnt(0)" ::: "memory")
; #define SBAR() __builtin_amdgcn_sched_barrier(0)
; #define TR8(D0, A) do { A[0] = tr_read<v_rd_off(D0, 0, 0)>(vb); A[1] = tr_read<v_rd_off(D0, 0, 1)>(vb); A[2] = tr_read<v_rd_off(D0, 1, 0)>(vb); A[3] = tr_read<v_rd_off(D0, 1, 1)>(vb); \
;     A[4] = tr_read<v_rd_off(D0, 2, 0)>(vb); A[5] = tr_read<v_rd_off(D0, 2, 1)>(vb); A[6] = tr_read<v_rd_off(D0, 3, 0)>(vb); A[7] = tr_read<v_rd_off(D0, 3, 1)>(vb); } while (0)
; #define SWRITE(b) do { *(bf16x8*)(K_lds + (b) * SHM_K + kwr) = ks[0]; *(bf16x8*)(K_lds + (b) * SHM_K + kwr + 128) = ks[1];            \
;     *(bf16x8*)(K_lds + (b) * SHM_K + kwr + 256) = ks[2];                                                                        \
;     *(bf16x8*)(V_lds + (b) * SHM_V + vst0) = vs0; *(bf16x8*)(V_lds + (b) * SHM_V + vst1) = vs1; } while (0)
; DEVI void pv_pipe(f32x16* o, int vb, bf16x8 pa0, bf16x8 pa1, bf16x8 pa2, bf16x8 pa3) {
;   s16x4 a[8], b[8];
;   TR8(0, a); TR8(1, b);
;   asm volatile("s_waitcnt lgkmcnt(8)" ::: "memory"); SBAR();
;   MM4(o[0], a); SBAR();
;   TR8(2, a);
;   asm volatile("s_waitcnt lgkmcnt(8)" ::: "memory"); SBAR();
;   MM4(o[1], b); SBAR();
;   TR8(3, b);
;   asm volatile("s_waitcnt lgkmcnt(8)" ::: "memory"); SBAR();
;   MM4(o[2], a); SBAR();
;   asm volatile("s_waitcnt lgkmcnt(0)" ::: "memory"); SBAR();
;   MM4(o[3], b);
; }
; DEVI void attn_item(const u16* __restrict__ Qb, const u16* __restrict__ Kn, const u16* __restrict__ Kr, const u16* __restrict__ Vh, u16* __restrict__ Ob, int seq) {
;     ...
;     if (j + 1 < NTk) { WAIT_V0(); SWRITE(cur ^ 1); }
;     __syncthreads();
	s_nop 0
	v_mfma_f32_32x32x16_bf16 v[2:17], v[66:69], v[82:85], v[2:17]
	v_mfma_f32_32x32x16_bf16 v[2:17], v[70:73], v[86:89], v[2:17]
	v_mfma_f32_32x32x16_bf16 v[2:17], v[74:77], v[90:93], v[2:17]
	v_mfma_f32_32x32x16_bf16 v[2:17], v[78:81], v[94:97], v[2:17]
	ds_read_b64_tr_b16 v[82:83], v221 offset:0x400
	ds_read_b64_tr_b16 v[84:85], v221 offset:0xc00
	ds_read_b64_tr_b16 v[86:87], v221 offset:0x1400
	ds_read_b64_tr_b16 v[88:89], v221 offset:0x1c00
	ds_read_b64_tr_b16 v[90:91], v221 offset:0x2400
	ds_read_b64_tr_b16 v[92:93], v221 offset:0x2c00
	ds_read_b64_tr_b16 v[94:95], v221 offset:0x3400
	ds_read_b64_tr_b16 v[96:97], v221 offset:0x3c00
	s_waitcnt lgkmcnt(8)
	v_mfma_f32_32x32x16_bf16 v[50:65], v[66:69], v[192:195], v[50:65]
	v_mfma_f32_32x32x16_bf16 v[50:65], v[70:73], v[198:201], v[50:65]
	v_mfma_f32_32x32x16_bf16 v[50:65], v[74:77], v[204:207], v[50:65]
	v_mfma_f32_32x32x16_bf16 v[50:65], v[78:81], v[222:225], v[50:65]
	ds_read_b64_tr_b16 v[192:193], v221 offset:0x600
	ds_read_b64_tr_b16 v[194:195], v221 offset:0xe00
	ds_read_b64_tr_b16 v[198:199], v221 offset:0x1600
	ds_read_b64_tr_b16 v[200:201], v221 offset:0x1e00
	ds_read_b64_tr_b16 v[204:205], v221 offset:0x2600
	ds_read_b64_tr_b16 v[206:207], v221 offset:0x2e00
	ds_read_b64_tr_b16 v[222:223], v221 offset:0x3600
	ds_read_b64_tr_b16 v[224:225], v221 offset:0x3e00
	s_waitcnt lgkmcnt(8)
	v_mfma_f32_32x32x16_bf16 v[34:49], v[66:69], v[82:85], v[34:49]
	v_mfma_f32_32x32x16_bf16 v[34:49], v[70:73], v[86:89], v[34:49]
	v_mfma_f32_32x32x16_bf16 v[34:49], v[74:77], v[90:93], v[34:49]
	v_mfma_f32_32x32x16_bf16 v[34:49], v[78:81], v[94:97], v[34:49]
	s_waitcnt lgkmcnt(0)
	v_mfma_f32_32x32x16_bf16 v[18:33], v[66:69], v[192:195], v[18:33]
	s_xor_b32 s2, s42, 1
	s_waitcnt vmcnt(0)
	s_mul_i32 s3, s2, 0x6400
	s_lshl_b32 s2, s2, 14
	v_add_u32_e32 v66, s2, v216
	v_mfma_f32_32x32x16_bf16 v[18:33], v[70:73], v[198:201], v[18:33]
	v_add_u32_e32 v67, s2, v217
	v_lshl_add_u64 v[174:175], v[174:175], 0, s[96:97]
	v_lshl_add_u64 v[176:177], v[176:177], 0, s[78:79]
	v_lshl_add_u64 v[178:179], v[178:179], 0, s[96:97]
	s_cmp_eq_u32 s69, s41
	s_waitcnt vmcnt(1)
	ds_write_b128 v66, v[158:161]
	s_waitcnt vmcnt(0)
	ds_write_b128 v67, v[162:165]
	v_mfma_f32_32x32x16_bf16 v[18:33], v[74:77], v[204:207], v[18:33]
	s_waitcnt lgkmcnt(0)
	s_barrier
	v_mfma_f32_32x32x16_bf16 v[18:33], v[78:81], v[222:225], v[18:33]
	s_cbranch_scc1 .LBB0_1266
	v_mov_b32_e32 v221, v220
	s_branch .LBB0_1260

; #define SBAR() __builtin_amdgcn_sched_barrier(0)
; #define TR8(D0, A) do { A[0] = tr_read<v_rd_off(D0, 0, 0)>(vb); A[1] = tr_read<v_rd_off(D0, 0, 1)>(vb); A[2] = tr_read<v_rd_off(D0, 1, 0)>(vb); A[3] = tr_read<v_rd_off(D0, 1, 1)>(vb); \
;     A[4] = tr_read<v_rd_off(D0, 2, 0)>(vb); A[5] = tr_read<v_rd_off(D0, 2, 1)>(vb); A[6] = tr_read<v_rd_off(D0, 3, 0)>(vb); A[7] = tr_read<v_rd_off(D0, 3, 1)>(vb); } while (0)
; DEVI void partialSM(f32x16& p0, f32x16& p1, float& m_reg, float& mn, float& alpha) {
;     ...
;   const float mnC = -mn * C;
; #pragma unroll
;   for (int r = 0; r < 16; ++r) p0[r] = __builtin_amdgcn_exp2f(fmaf(p0[r], C, mnC));
; #pragma unroll
;   for (int r = 0; r < 16; ++r) p1[r] = __builtin_amdgcn_exp2f(fmaf(p1[r], C, mnC));
; }
; DEVI void finishSM(f32x16& p0, f32x16& p1, float alpha, float& l_reg, bf16x8& pa0, bf16x8& pa1, bf16x8& pa2, bf16x8& pa3) {
;   float ps = 0;
; #pragma unroll
;   for (int r = 0; r < 16; ++r) ps += p0[r];
; #pragma unroll
;   for (int r = 0; r < 16; ++r) ps += p1[r];
;   { auto rr = __builtin_amdgcn_permlane32_swap(__float_as_uint(ps), __float_as_uint(ps), false, false);
;     ps = __uint_as_float(rr[0]) + __uint_as_float(rr[1]); }
;   l_reg = l_reg * alpha + ps;
;     ...
;   PK4(p0, 0, pa0); PK4(p0, 8, pa1); PK4(p1, 0, pa2); PK4(p1, 8, pa3);
; DEVI void pv_pipe(f32x16* o, int vb, bf16x8 pa0, bf16x8 pa1, bf16x8 pa2, bf16x8 pa3) {
;   s16x4 a[8], b[8];
;   TR8(0, a); TR8(1, b);
;   asm volatile("s_waitcnt lgkmcnt(8)" ::: "memory"); SBAR();
;   MM4(o[0], a); SBAR();
;   TR8(2, a);
;   asm volatile("s_waitcnt lgkmcnt(8)" ::: "memory"); SBAR();
;   MM4(o[1], b); SBAR();
;   TR8(3, b);
;   asm volatile("s_waitcnt lgkmcnt(8)" ::: "memory"); SBAR();
;   MM4(o[2], a); SBAR();
;   asm volatile("s_waitcnt lgkmcnt(0)" ::: "memory"); SBAR();
;   MM4(o[3], b);
; }
.LBB0_1270:
	v_cndmask_b32_e64 v99, v99, v215, s[12:13]
	v_mul_f32_e32 v99, 0xbdd53b94, v99
	v_fmamk_f32 v66, v66, 0x3dd53b94, v99
	v_exp_f32_e32 v100, v66
	v_fmamk_f32 v66, v67, 0x3dd53b94, v99
	v_exp_f32_e32 v101, v66
	v_fmamk_f32 v66, v68, 0x3dd53b94, v99
	v_exp_f32_e32 v102, v66
	v_fmamk_f32 v66, v69, 0x3dd53b94, v99
	v_exp_f32_e32 v103, v66
	v_fmamk_f32 v66, v70, 0x3dd53b94, v99
	v_exp_f32_e32 v104, v66
	v_fmamk_f32 v66, v71, 0x3dd53b94, v99
	v_exp_f32_e32 v105, v66
	v_fmamk_f32 v66, v72, 0x3dd53b94, v99
	v_exp_f32_e32 v106, v66
	v_fmamk_f32 v66, v73, 0x3dd53b94, v99
	v_exp_f32_e32 v107, v66
	v_fmamk_f32 v66, v74, 0x3dd53b94, v99
	v_exp_f32_e32 v108, v66
	v_fmamk_f32 v66, v75, 0x3dd53b94, v99
	v_fmamk_f32 v82, v82, 0x3dd53b94, v99
	v_exp_f32_e32 v109, v66
	v_fmamk_f32 v66, v76, 0x3dd53b94, v99
	v_exp_f32_e32 v82, v82
	v_fmamk_f32 v83, v83, 0x3dd53b94, v99
	v_exp_f32_e32 v110, v66
	v_fmamk_f32 v66, v77, 0x3dd53b94, v99
	v_exp_f32_e32 v83, v83
	v_fmamk_f32 v84, v84, 0x3dd53b94, v99
	v_exp_f32_e32 v111, v66
	v_fmamk_f32 v66, v78, 0x3dd53b94, v99
	v_exp_f32_e32 v84, v84
	v_fmamk_f32 v85, v85, 0x3dd53b94, v99
	v_exp_f32_e32 v112, v66
	v_fmamk_f32 v66, v79, 0x3dd53b94, v99
	v_exp_f32_e32 v85, v85
	v_fmamk_f32 v86, v86, 0x3dd53b94, v99
	v_exp_f32_e32 v113, v66
	v_fmamk_f32 v66, v80, 0x3dd53b94, v99
	v_exp_f32_e32 v86, v86
	v_fmamk_f32 v87, v87, 0x3dd53b94, v99
	v_exp_f32_e32 v114, v66
	v_add_f32_e32 v66, 0, v82
	v_exp_f32_e32 v87, v87
	v_fmamk_f32 v88, v88, 0x3dd53b94, v99
	v_add_f32_e32 v66, v83, v66
	v_exp_f32_e32 v88, v88
	v_fmamk_f32 v89, v89, 0x3dd53b94, v99
	v_add_f32_e32 v66, v84, v66
	v_exp_f32_e32 v89, v89
	v_fmamk_f32 v90, v90, 0x3dd53b94, v99
	v_add_f32_e32 v66, v85, v66
	v_exp_f32_e32 v90, v90
	v_fmamk_f32 v91, v91, 0x3dd53b94, v99
	v_add_f32_e32 v66, v86, v66
	v_exp_f32_e32 v91, v91
	v_fmamk_f32 v92, v92, 0x3dd53b94, v99
	v_add_f32_e32 v66, v87, v66
	v_exp_f32_e32 v92, v92
	v_fmamk_f32 v93, v93, 0x3dd53b94, v99
	v_add_f32_e32 v66, v88, v66
	v_exp_f32_e32 v93, v93
	v_fmamk_f32 v94, v94, 0x3dd53b94, v99
	v_add_f32_e32 v66, v89, v66
	v_exp_f32_e32 v94, v94
	v_fmamk_f32 v95, v95, 0x3dd53b94, v99
	v_add_f32_e32 v66, v90, v66
	v_exp_f32_e32 v95, v95
	v_fmamk_f32 v96, v96, 0x3dd53b94, v99
	v_add_f32_e32 v66, v91, v66
	v_exp_f32_e32 v96, v96
	v_fmamk_f32 v97, v97, 0x3dd53b94, v99
	v_add_f32_e32 v66, v92, v66
	v_exp_f32_e32 v97, v97
	v_add_f32_e32 v66, v93, v66
	v_add_f32_e32 v66, v94, v66
	v_add_f32_e32 v66, v95, v66
	v_add_f32_e32 v66, v96, v66
	v_add_f32_e32 v66, v97, v66
	v_add_f32_e32 v66, v100, v66
	v_add_f32_e32 v66, v101, v66
	v_add_f32_e32 v66, v102, v66
	v_add_f32_e32 v66, v103, v66
	v_add_f32_e32 v66, v104, v66
	v_add_f32_e32 v66, v105, v66
	v_add_f32_e32 v66, v106, v66
	v_add_f32_e32 v66, v107, v66
	v_add_f32_e32 v66, v108, v66
	v_add_f32_e32 v66, v109, v66
	v_fmac_f32_e32 v99, 0x3dd53b94, v81
	v_add_f32_e32 v66, v110, v66
	v_exp_f32_e32 v99, v99
	v_add_f32_e32 v66, v111, v66
	v_add_f32_e32 v66, v112, v66
	v_add_f32_e32 v66, v113, v66
	v_add_f32_e32 v66, v114, v66
	v_add_f32_e32 v66, v99, v66
	v_mov_b32_e32 v67, v66
	s_nop 1
	v_permlane32_swap_b32_e32 v66, v67
	v_cvt_pk_bf16_f32 v68, v82, v83
	v_cvt_pk_bf16_f32 v69, v84, v85
	v_cvt_pk_bf16_f32 v70, v86, v87
	v_cvt_pk_bf16_f32 v71, v88, v89
	v_cvt_pk_bf16_f32 v72, v90, v91
	v_cvt_pk_bf16_f32 v73, v92, v93
	v_cvt_pk_bf16_f32 v74, v94, v95
	v_cvt_pk_bf16_f32 v75, v96, v97
	v_cvt_pk_bf16_f32 v76, v100, v101
	v_cvt_pk_bf16_f32 v77, v102, v103
	v_cvt_pk_bf16_f32 v78, v104, v105
	v_cvt_pk_bf16_f32 v79, v106, v107
	v_cvt_pk_bf16_f32 v80, v108, v109
	v_cvt_pk_bf16_f32 v81, v110, v111
	v_cvt_pk_bf16_f32 v82, v112, v113
	v_cvt_pk_bf16_f32 v83, v114, v99
	v_permlane32_swap_b32_e32 v68, v70
	v_permlane32_swap_b32_e32 v69, v71
	v_permlane32_swap_b32_e32 v72, v74
	v_permlane32_swap_b32_e32 v73, v75
	v_permlane32_swap_b32_e32 v76, v78
	v_permlane32_swap_b32_e32 v77, v79
	v_permlane32_swap_b32_e32 v80, v82
	v_permlane32_swap_b32_e32 v81, v83
	s_waitcnt lgkmcnt(0)
	s_barrier
	v_lshl_or_b32 v96, s41, 14, v214
	ds_read_b64_tr_b16 v[84:85], v96 offset:0
	ds_read_b64_tr_b16 v[86:87], v96 offset:0x800
	ds_read_b64_tr_b16 v[88:89], v96 offset:0x1000
	ds_read_b64_tr_b16 v[90:91], v96 offset:0x1800
	ds_read_b64_tr_b16 v[92:93], v96 offset:0x2000
	ds_read_b64_tr_b16 v[94:95], v96 offset:0x2800
	ds_read_b64_tr_b16 v[100:101], v96 offset:0x3000
	ds_read_b64_tr_b16 v[102:103], v96 offset:0x3800
	ds_read_b64_tr_b16 v[104:105], v96 offset:0x200
	ds_read_b64_tr_b16 v[106:107], v96 offset:0xa00
	ds_read_b64_tr_b16 v[108:109], v96 offset:0x1200
	ds_read_b64_tr_b16 v[110:111], v96 offset:0x1a00
	ds_read_b64_tr_b16 v[112:113], v96 offset:0x2200
	ds_read_b64_tr_b16 v[114:115], v96 offset:0x2a00
	ds_read_b64_tr_b16 v[116:117], v96 offset:0x3200
	ds_read_b64_tr_b16 v[118:119], v96 offset:0x3a00
	s_waitcnt lgkmcnt(8)
	s_nop 0
	v_mfma_f32_32x32x16_bf16 v[2:17], v[68:71], v[84:87], v[2:17]
	v_mfma_f32_32x32x16_bf16 v[2:17], v[72:75], v[88:91], v[2:17]
	v_mfma_f32_32x32x16_bf16 v[2:17], v[76:79], v[92:95], v[2:17]
	v_mfma_f32_32x32x16_bf16 v[2:17], v[80:83], v[100:103], v[2:17]
	ds_read_b64_tr_b16 v[84:85], v96 offset:0x400
	ds_read_b64_tr_b16 v[86:87], v96 offset:0xc00
	ds_read_b64_tr_b16 v[88:89], v96 offset:0x1400
	ds_read_b64_tr_b16 v[90:91], v96 offset:0x1c00
	ds_read_b64_tr_b16 v[92:93], v96 offset:0x2400
	ds_read_b64_tr_b16 v[94:95], v96 offset:0x2c00
	ds_read_b64_tr_b16 v[100:101], v96 offset:0x3400
	ds_read_b64_tr_b16 v[102:103], v96 offset:0x3c00
	s_waitcnt lgkmcnt(8)
	v_mfma_f32_32x32x16_bf16 v[50:65], v[68:71], v[104:107], v[50:65]
	v_mfma_f32_32x32x16_bf16 v[50:65], v[72:75], v[108:111], v[50:65]
	v_mfma_f32_32x32x16_bf16 v[50:65], v[76:79], v[112:115], v[50:65]
	v_mfma_f32_32x32x16_bf16 v[50:65], v[80:83], v[116:119], v[50:65]
	ds_read_b64_tr_b16 v[104:105], v96 offset:0x600
	ds_read_b64_tr_b16 v[106:107], v96 offset:0xe00
	ds_read_b64_tr_b16 v[108:109], v96 offset:0x1600
	ds_read_b64_tr_b16 v[110:111], v96 offset:0x1e00
	ds_read_b64_tr_b16 v[112:113], v96 offset:0x2600
	ds_read_b64_tr_b16 v[114:115], v96 offset:0x2e00
	ds_read_b64_tr_b16 v[116:117], v96 offset:0x3600
	ds_read_b64_tr_b16 v[118:119], v96 offset:0x3e00
	s_waitcnt lgkmcnt(8)
	v_mfma_f32_32x32x16_bf16 v[34:49], v[68:71], v[84:87], v[34:49]
	v_mfma_f32_32x32x16_bf16 v[34:49], v[72:75], v[88:91], v[34:49]
	v_mfma_f32_32x32x16_bf16 v[34:49], v[76:79], v[92:95], v[34:49]
	v_mfma_f32_32x32x16_bf16 v[34:49], v[80:83], v[100:103], v[34:49]
	s_waitcnt lgkmcnt(0)
	v_mfma_f32_32x32x16_bf16 v[18:33], v[68:71], v[104:107], v[18:33]
	s_barrier
	s_cmp_eq_u32 s101, 0
	s_cbranch_scc0 .Latt_pp_x1
	s_barrier
.Latt_pp_x1:
	v_mfma_f32_32x32x16_bf16 v[18:33], v[72:75], v[108:111], v[18:33]
	v_mfma_f32_32x32x16_bf16 v[18:33], v[76:79], v[112:115], v[18:33]
	v_mfma_f32_32x32x16_bf16 v[18:33], v[80:83], v[116:119], v[18:33]
	s_and_saveexec_b64 s[2:3], s[10:11]
	s_cbranch_execz .LBB0_1255
	v_add_f32_e32 v66, v66, v67
	v_fmac_f32_e32 v66, v220, v98
	ds_write_b32 v173, v66
	s_branch .LBB0_1255

; #define WAIT_V0() asm volatile("s_waitcnt vmcnt(0)" ::: "memory")
; #define SBAR() __builtin_amdgcn_sched_barrier(0)
; template <int EPI>
; DEVI void gemm_tile(const u16* __restrict__ Ab, long lda, const u16* __restrict__ Bb, long ldb, int K, const EpiArgs& e,
;                     bool have0 = false, const u16* __restrict__ nA = nullptr, const u16* __restrict__ nB = nullptr) {
;     ...
;   for (int t = 0; t < nt; ++t) {
;     const int cur = t & 1;
;     if (t + 1 < nt) GLDS_STAGE(cur ^ 1, t + 1);
;     else if (nA) {
; #pragma unroll
;       for (int i = 0; i < GL; ++i) {
;         __builtin_amdgcn_global_load_lds((const unsigned*)(nA + (long)i * 64 * lda + toffA), (unsigned*)(g_shm + wid * 1024 + i * 8192), 16, 0, 0);
;         __builtin_amdgcn_global_load_lds((const unsigned*)(nB + (long)i * 64 * ldb + toffB), (unsigned*)(g_shm + TILE_B + wid * 1024 + i * 8192), 16, 0, 0);
;       }
;     }
;     const char* sb = g_shm + cur * STAGE_B;
; #pragma unroll
;     for (int ks = 0; ks < 2; ++ks) {
;       bf16x8 Bf[4];
; #pragma unroll
;       for (int n = 0; n < 4; ++n) Bf[n] = *(const bf16x8*)(sb + b_base + n * 2048 + ks * 1024);
; #pragma unroll
;       for (int mh = 0; mh < 2; ++mh) {
;         bf16x8 At[4];
; #pragma unroll
;         for (int m = 0; m < 4; ++m) At[m] = *(const bf16x8*)(sb + a_base + (mh * 4 + m) * 2048 + ks * 1024);
;         __builtin_amdgcn_s_setprio(1);
; #pragma unroll
;         for (int m = 0; m < 4; ++m)
; #pragma unroll
;           for (int n = 0; n < 4; ++n) acc[mh * 4 + m][n] = __builtin_amdgcn_mfma_f32_16x16x32_bf16(Bf[n], At[m], acc[mh * 4 + m][n], 0, 0, 0);
;         __builtin_amdgcn_s_setprio(0);
;       }
;       SBAR();
;     }
;     if (t + 1 < nt) { WAIT_V0(); __syncthreads(); }
;   }
.LBB0_1302:
	s_and_b32 s3, s2, 0x10000
	v_or_b32_e32 v150, s3, v149
	v_add_u32_e32 v169, v150, v148
	v_or_b32_e32 v150, s3, v146
	v_add_u32_e32 v178, v150, v147
	ds_read_b128 v[150:153], v169 offset:32768
	ds_read_b128 v[154:157], v169 offset:34816
	ds_read_b128 v[158:161], v169 offset:36864
	ds_read_b128 v[162:165], v169 offset:38912
	ds_read_b128 v[170:173], v178
	ds_read_b128 v[174:177], v178 offset:2048
	ds_read_b128 v[214:217], v178 offset:4096
	ds_read_b128 v[218:221], v178 offset:6144
	v_writelane_b32 v240, s4, 0
	v_writelane_b32 v240, s5, 1
	v_writelane_b32 v240, s6, 2
	v_writelane_b32 v240, s7, 3
	v_writelane_b32 v240, s8, 4
	v_writelane_b32 v240, s9, 5
	v_writelane_b32 v240, s10, 6
	v_readfirstlane_b32 s4, v134
	v_readfirstlane_b32 s5, v135
	s_nop 1
	v_subrev_u32_e32 v238, s4, v134
	s_add_u32 s4, s4, s16
	s_addc_u32 s5, s5, s17
	v_readfirstlane_b32 s6, v136
	v_readfirstlane_b32 s7, v137
	s_nop 1
	v_subrev_u32_e32 v239, s6, v136
	s_add_u32 s6, s6, s16
	s_addc_u32 s7, s7, s17
	v_readfirstlane_b32 s10, v142
	s_xor_b32 s8, s3, 0x10000
	s_nop 0
	s_add_i32 s10, s10, s8
	s_add_i32 m0, s10, 0x0
	s_add_u32 s8, s4, 0x1f500080
	s_addc_u32 s9, s5, 0
	global_load_lds_dwordx4 v238, s[8:9]
	s_add_i32 m0, s10, 0x8000
	s_add_u32 s8, s6, 0x87a0080
	s_addc_u32 s9, s7, 0
	global_load_lds_dwordx4 v239, s[8:9]
	s_add_i32 m0, s10, 0x2000
	s_add_u32 s8, s4, 0x1f520080
	s_addc_u32 s9, s5, 0
	global_load_lds_dwordx4 v238, s[8:9]
.Lkl_1302:
	s_waitcnt lgkmcnt(3)
	v_mfma_f32_16x16x32_bf16 v[126:129], v[150:153], v[170:173], v[126:129]
	v_mfma_f32_16x16x32_bf16 v[122:125], v[154:157], v[170:173], v[122:125]
	v_mfma_f32_16x16x32_bf16 v[118:121], v[158:161], v[170:173], v[118:121]
	v_mfma_f32_16x16x32_bf16 v[114:117], v[162:165], v[170:173], v[114:117]
	ds_read_b128 v[170:173], v178 offset:8192
	ds_read_b128 v[222:225], v169 offset:33792
	s_add_i32 m0, s10, 0xa000
	s_add_u32 s8, s6, 0x87c0080
	s_addc_u32 s9, s7, 0
	global_load_lds_dwordx4 v239, s[8:9]
	s_waitcnt lgkmcnt(4)
	v_mfma_f32_16x16x32_bf16 v[110:113], v[150:153], v[174:177], v[110:113]
	v_mfma_f32_16x16x32_bf16 v[106:109], v[154:157], v[174:177], v[106:109]
	v_mfma_f32_16x16x32_bf16 v[102:105], v[158:161], v[174:177], v[102:105]
	v_mfma_f32_16x16x32_bf16 v[98:101], v[162:165], v[174:177], v[98:101]
	ds_read_b128 v[174:177], v178 offset:10240
	ds_read_b128 v[226:229], v169 offset:35840
	s_add_i32 m0, s10, 0x4000
	s_add_u32 s8, s4, 0x1f540080
	s_addc_u32 s9, s5, 0
	global_load_lds_dwordx4 v238, s[8:9]
	s_waitcnt lgkmcnt(5)
	v_mfma_f32_16x16x32_bf16 v[94:97], v[150:153], v[214:217], v[94:97]
	v_mfma_f32_16x16x32_bf16 v[90:93], v[154:157], v[214:217], v[90:93]
	v_mfma_f32_16x16x32_bf16 v[86:89], v[158:161], v[214:217], v[86:89]
	v_mfma_f32_16x16x32_bf16 v[82:85], v[162:165], v[214:217], v[82:85]
	ds_read_b128 v[214:217], v178 offset:12288
	ds_read_b128 v[230:233], v169 offset:37888
	s_add_i32 m0, s10, 0xc000
	s_add_u32 s8, s6, 0x87e0080
	s_addc_u32 s9, s7, 0
	global_load_lds_dwordx4 v239, s[8:9]
	s_waitcnt lgkmcnt(6)
	v_mfma_f32_16x16x32_bf16 v[78:81], v[150:153], v[218:221], v[78:81]
	v_mfma_f32_16x16x32_bf16 v[74:77], v[154:157], v[218:221], v[74:77]
	v_mfma_f32_16x16x32_bf16 v[70:73], v[158:161], v[218:221], v[70:73]
	v_mfma_f32_16x16x32_bf16 v[66:69], v[162:165], v[218:221], v[66:69]
	ds_read_b128 v[218:221], v178 offset:14336
	ds_read_b128 v[234:237], v169 offset:39936
	s_add_i32 m0, s10, 0x6000
	s_add_u32 s8, s4, 0x1f560080
	s_addc_u32 s9, s5, 0
	global_load_lds_dwordx4 v238, s[8:9]
	s_waitcnt lgkmcnt(7)
	v_mfma_f32_16x16x32_bf16 v[62:65], v[150:153], v[170:173], v[62:65]
	v_mfma_f32_16x16x32_bf16 v[58:61], v[154:157], v[170:173], v[58:61]
	v_mfma_f32_16x16x32_bf16 v[54:57], v[158:161], v[170:173], v[54:57]
	v_mfma_f32_16x16x32_bf16 v[50:53], v[162:165], v[170:173], v[50:53]
	ds_read_b128 v[170:173], v178 offset:1024
	s_add_i32 m0, s10, 0xe000
	s_add_u32 s8, s6, 0x8800080
	s_addc_u32 s9, s7, 0
	global_load_lds_dwordx4 v239, s[8:9]
	s_waitcnt lgkmcnt(6)
	v_mfma_f32_16x16x32_bf16 v[46:49], v[150:153], v[174:177], v[46:49]
	v_mfma_f32_16x16x32_bf16 v[42:45], v[154:157], v[174:177], v[42:45]
	v_mfma_f32_16x16x32_bf16 v[38:41], v[158:161], v[174:177], v[38:41]
	v_mfma_f32_16x16x32_bf16 v[34:37], v[162:165], v[174:177], v[34:37]
	ds_read_b128 v[174:177], v178 offset:3072
	s_waitcnt lgkmcnt(5)
; #define WAIT_V0() asm volatile("s_waitcnt vmcnt(0)" ::: "memory")
; #define SBAR() __builtin_amdgcn_sched_barrier(0)
; template <int EPI>
; DEVI void gemm_tile(const u16* __restrict__ Ab, long lda, const u16* __restrict__ Bb, long ldb, int K, const EpiArgs& e,
;                     bool have0 = false, const u16* __restrict__ nA = nullptr, const u16* __restrict__ nB = nullptr) {
;     ...
;   for (int t = 0; t < nt; ++t) {
;     const int cur = t & 1;
;     if (t + 1 < nt) GLDS_STAGE(cur ^ 1, t + 1);
;     else if (nA) {
; #pragma unroll
;       for (int i = 0; i < GL; ++i) {
;         __builtin_amdgcn_global_load_lds((const unsigned*)(nA + (long)i * 64 * lda + toffA), (unsigned*)(g_shm + wid * 1024 + i * 8192), 16, 0, 0);
;         __builtin_amdgcn_global_load_lds((const unsigned*)(nB + (long)i * 64 * ldb + toffB), (unsigned*)(g_shm + TILE_B + wid * 1024 + i * 8192), 16, 0, 0);
;       }
;     }
;     const char* sb = g_shm + cur * STAGE_B;
; #pragma unroll
;     for (int ks = 0; ks < 2; ++ks) {
;       bf16x8 Bf[4];
; #pragma unroll
;       for (int n = 0; n < 4; ++n) Bf[n] = *(const bf16x8*)(sb + b_base + n * 2048 + ks * 1024);
; #pragma unroll
;       for (int mh = 0; mh < 2; ++mh) {
;         bf16x8 At[4];
; #pragma unroll
;         for (int m = 0; m < 4; ++m) At[m] = *(const bf16x8*)(sb + a_base + (mh * 4 + m) * 2048 + ks * 1024);
;         __builtin_amdgcn_s_setprio(1);
; #pragma unroll
;         for (int m = 0; m < 4; ++m)
; #pragma unroll
;           for (int n = 0; n < 4; ++n) acc[mh * 4 + m][n] = __builtin_amdgcn_mfma_f32_16x16x32_bf16(Bf[n], At[m], acc[mh * 4 + m][n], 0, 0, 0);
;         __builtin_amdgcn_s_setprio(0);
;       }
;       SBAR();
;     }
;     if (t + 1 < nt) { WAIT_V0(); __syncthreads(); }
;   }
	v_mfma_f32_16x16x32_bf16 v[30:33], v[150:153], v[214:217], v[30:33]
	v_mfma_f32_16x16x32_bf16 v[26:29], v[154:157], v[214:217], v[26:29]
	v_mfma_f32_16x16x32_bf16 v[22:25], v[158:161], v[214:217], v[22:25]
	v_mfma_f32_16x16x32_bf16 v[18:21], v[162:165], v[214:217], v[18:21]
	ds_read_b128 v[214:217], v178 offset:5120
	s_waitcnt lgkmcnt(4)
	v_mfma_f32_16x16x32_bf16 v[14:17], v[150:153], v[218:221], v[14:17]
	v_mfma_f32_16x16x32_bf16 v[10:13], v[154:157], v[218:221], v[10:13]
	v_mfma_f32_16x16x32_bf16 v[6:9], v[158:161], v[218:221], v[6:9]
	v_mfma_f32_16x16x32_bf16 v[2:5], v[162:165], v[218:221], v[2:5]
	ds_read_b128 v[218:221], v178 offset:7168
	s_waitcnt lgkmcnt(3)
	v_mfma_f32_16x16x32_bf16 v[126:129], v[222:225], v[170:173], v[126:129]
	v_mfma_f32_16x16x32_bf16 v[122:125], v[226:229], v[170:173], v[122:125]
	v_mfma_f32_16x16x32_bf16 v[118:121], v[230:233], v[170:173], v[118:121]
	v_mfma_f32_16x16x32_bf16 v[114:117], v[234:237], v[170:173], v[114:117]
	ds_read_b128 v[170:173], v178 offset:9216
	s_waitcnt lgkmcnt(3)
	v_mfma_f32_16x16x32_bf16 v[110:113], v[222:225], v[174:177], v[110:113]
	v_mfma_f32_16x16x32_bf16 v[106:109], v[226:229], v[174:177], v[106:109]
	v_mfma_f32_16x16x32_bf16 v[102:105], v[230:233], v[174:177], v[102:105]
	v_mfma_f32_16x16x32_bf16 v[98:101], v[234:237], v[174:177], v[98:101]
	ds_read_b128 v[174:177], v178 offset:11264
	s_waitcnt lgkmcnt(3)
	v_mfma_f32_16x16x32_bf16 v[94:97], v[222:225], v[214:217], v[94:97]
	v_mfma_f32_16x16x32_bf16 v[90:93], v[226:229], v[214:217], v[90:93]
	v_mfma_f32_16x16x32_bf16 v[86:89], v[230:233], v[214:217], v[86:89]
	v_mfma_f32_16x16x32_bf16 v[82:85], v[234:237], v[214:217], v[82:85]
	ds_read_b128 v[214:217], v178 offset:13312
	s_waitcnt lgkmcnt(3)
	v_mfma_f32_16x16x32_bf16 v[78:81], v[222:225], v[218:221], v[78:81]
	v_mfma_f32_16x16x32_bf16 v[74:77], v[226:229], v[218:221], v[74:77]
	v_mfma_f32_16x16x32_bf16 v[70:73], v[230:233], v[218:221], v[70:73]
	v_mfma_f32_16x16x32_bf16 v[66:69], v[234:237], v[218:221], v[66:69]
	ds_read_b128 v[218:221], v178 offset:15360
	s_waitcnt lgkmcnt(3)
	v_mfma_f32_16x16x32_bf16 v[62:65], v[222:225], v[170:173], v[62:65]
	v_mfma_f32_16x16x32_bf16 v[58:61], v[226:229], v[170:173], v[58:61]
	v_mfma_f32_16x16x32_bf16 v[54:57], v[230:233], v[170:173], v[54:57]
	v_mfma_f32_16x16x32_bf16 v[50:53], v[234:237], v[170:173], v[50:53]
	s_waitcnt lgkmcnt(2)
	v_mfma_f32_16x16x32_bf16 v[46:49], v[222:225], v[174:177], v[46:49]
	v_mfma_f32_16x16x32_bf16 v[42:45], v[226:229], v[174:177], v[42:45]
	v_mfma_f32_16x16x32_bf16 v[38:41], v[230:233], v[174:177], v[38:41]
	v_mfma_f32_16x16x32_bf16 v[34:37], v[234:237], v[174:177], v[34:37]
	s_waitcnt lgkmcnt(0)
	s_waitcnt vmcnt(0)
	s_add_u32 s16, s16, 0x80
	s_addc_u32 s17, s17, 0
	s_add_i32 s2, s2, 0x10000
	s_cmpk_eq_i32 s16, 0x780
	s_waitcnt vmcnt(0)
	s_barrier
	s_cselect_b32 s100, 1, 0
	s_and_b32 s3, s2, 0x10000
	v_or_b32_e32 v150, s3, v149
	v_add_u32_e32 v169, v150, v148
	v_or_b32_e32 v150, s3, v146
	v_add_u32_e32 v178, v150, v147
	ds_read_b128 v[150:153], v169 offset:32768
	ds_read_b128 v[154:157], v169 offset:34816
	ds_read_b128 v[158:161], v169 offset:36864
	ds_read_b128 v[162:165], v169 offset:38912
	ds_read_b128 v[170:173], v178
	ds_read_b128 v[174:177], v178 offset:2048
	s_add_u32 s4, s4, 0x80
	s_addc_u32 s5, s5, 0
	s_add_u32 s6, s6, 0x80
	s_addc_u32 s7, s7, 0
	s_cmp_eq_u32 s100, 1
	s_cbranch_scc1 .Lkl_1302_s1
	v_readfirstlane_b32 s10, v142
	s_xor_b32 s8, s3, 0x10000
	s_nop 0
	s_add_i32 s10, s10, s8
	s_add_i32 m0, s10, 0x0
	s_add_u32 s8, s4, 0x1f500080
	s_addc_u32 s9, s5, 0
	global_load_lds_dwordx4 v238, s[8:9]
.Lkl_1302_s1:
	v_mfma_f32_16x16x32_bf16 v[30:33], v[222:225], v[214:217], v[30:33]
	v_mfma_f32_16x16x32_bf16 v[26:29], v[226:229], v[214:217], v[26:29]
	v_mfma_f32_16x16x32_bf16 v[22:25], v[230:233], v[214:217], v[22:25]
	v_mfma_f32_16x16x32_bf16 v[18:21], v[234:237], v[214:217], v[18:21]
	ds_read_b128 v[214:217], v178 offset:4096
	s_cmp_eq_u32 s100, 1
	s_cbranch_scc1 .Lkl_1302_s2
	s_add_i32 m0, s10, 0x8000
	s_add_u32 s8, s6, 0x87a0080
	s_addc_u32 s9, s7, 0
	global_load_lds_dwordx4 v239, s[8:9]
.Lkl_1302_s2:
	v_mfma_f32_16x16x32_bf16 v[14:17], v[222:225], v[218:221], v[14:17]
	v_mfma_f32_16x16x32_bf16 v[10:13], v[226:229], v[218:221], v[10:13]
	v_mfma_f32_16x16x32_bf16 v[6:9], v[230:233], v[218:221], v[6:9]
	v_mfma_f32_16x16x32_bf16 v[2:5], v[234:237], v[218:221], v[2:5]
	ds_read_b128 v[218:221], v178 offset:6144
	s_cmp_eq_u32 s100, 1
	s_cbranch_scc1 .Lkl_1302_s3
	s_add_i32 m0, s10, 0x2000
	s_add_u32 s8, s4, 0x1f520080
	s_addc_u32 s9, s5, 0
	global_load_lds_dwordx4 v238, s[8:9]

; #define WAIT_V0() asm volatile("s_waitcnt vmcnt(0)" ::: "memory")
; #define SBAR() __builtin_amdgcn_sched_barrier(0)
; template <int EPI>
; DEVI void gemm_tile(const u16* __restrict__ Ab, long lda, const u16* __restrict__ Bb, long ldb, int K, const EpiArgs& e,
;                     bool have0 = false, const u16* __restrict__ nA = nullptr, const u16* __restrict__ nB = nullptr) {
;     ...
;   for (int t = 0; t < nt; ++t) {
;     const int cur = t & 1;
;     if (t + 1 < nt) GLDS_STAGE(cur ^ 1, t + 1);
;     else if (nA) {
; #pragma unroll
;       for (int i = 0; i < GL; ++i) {
;         __builtin_amdgcn_global_load_lds((const unsigned*)(nA + (long)i * 64 * lda + toffA), (unsigned*)(g_shm + wid * 1024 + i * 8192), 16, 0, 0);
;         __builtin_amdgcn_global_load_lds((const unsigned*)(nB + (long)i * 64 * ldb + toffB), (unsigned*)(g_shm + TILE_B + wid * 1024 + i * 8192), 16, 0, 0);
;       }
;     }
;     const char* sb = g_shm + cur * STAGE_B;
; #pragma unroll
;     for (int ks = 0; ks < 2; ++ks) {
;       bf16x8 Bf[4];
; #pragma unroll
;       for (int n = 0; n < 4; ++n) Bf[n] = *(const bf16x8*)(sb + b_base + n * 2048 + ks * 1024);
; #pragma unroll
;       for (int mh = 0; mh < 2; ++mh) {
;         bf16x8 At[4];
; #pragma unroll
;         for (int m = 0; m < 4; ++m) At[m] = *(const bf16x8*)(sb + a_base + (mh * 4 + m) * 2048 + ks * 1024);
;         __builtin_amdgcn_s_setprio(1);
; #pragma unroll
;         for (int m = 0; m < 4; ++m)
; #pragma unroll
;           for (int n = 0; n < 4; ++n) acc[mh * 4 + m][n] = __builtin_amdgcn_mfma_f32_16x16x32_bf16(Bf[n], At[m], acc[mh * 4 + m][n], 0, 0, 0);
;         __builtin_amdgcn_s_setprio(0);
;       }
;       SBAR();
;     }
;     if (t + 1 < nt) { WAIT_V0(); __syncthreads(); }
;   }
.LBB0_1370:
	s_and_b32 s3, s2, 0x10000
	v_or_b32_e32 v149, s3, v147
	v_add_u32_e32 v169, v149, v148
	v_add_u32_e32 v149, v149, v146
	ds_read_b128 v[150:153], v169 offset:32768
	ds_read_b128 v[154:157], v169 offset:34816
	ds_read_b128 v[158:161], v169 offset:36864
	ds_read_b128 v[162:165], v169 offset:38912
	ds_read_b128 v[170:173], v149
	ds_read_b128 v[174:177], v149 offset:2048
	ds_read_b128 v[192:195], v149 offset:4096
	ds_read_b128 v[198:201], v149 offset:6144
	v_writelane_b32 v240, s4, 0
	v_writelane_b32 v240, s5, 1
	v_writelane_b32 v240, s6, 2
	v_writelane_b32 v240, s7, 3
	v_writelane_b32 v240, s8, 4
	v_writelane_b32 v240, s9, 5
	v_writelane_b32 v240, s10, 6
	v_readfirstlane_b32 s4, v132
	v_readfirstlane_b32 s5, v133
	s_nop 1
	v_subrev_u32_e32 v238, s4, v132
	s_add_u32 s4, s4, s18
	s_addc_u32 s5, s5, s19
	v_readfirstlane_b32 s6, v134
	v_readfirstlane_b32 s7, v135
	s_nop 1
	v_subrev_u32_e32 v239, s6, v134
	s_add_u32 s6, s6, s18
	s_addc_u32 s7, s7, s19
	v_readfirstlane_b32 s10, v140
	s_xor_b32 s8, s3, 0x10000
	s_nop 0
	s_add_i32 s10, s10, s8
	s_add_i32 m0, s10, 0x0
	s_add_u32 s8, s4, s12
	s_addc_u32 s9, s5, s13
	global_load_lds_dwordx4 v238, s[8:9]
	s_add_i32 m0, s10, 0x8000
	s_add_u32 s8, s6, 0xb00080
	s_addc_u32 s9, s7, 0
	global_load_lds_dwordx4 v239, s[8:9]
	s_add_i32 m0, s10, 0x2000
	s_add_u32 s8, s4, s14
	s_addc_u32 s9, s5, s15
	global_load_lds_dwordx4 v238, s[8:9]
.Lkl_1370:
	s_waitcnt lgkmcnt(3)
	v_mfma_f32_16x16x32_bf16 v[126:129], v[150:153], v[170:173], v[126:129]
	v_mfma_f32_16x16x32_bf16 v[122:125], v[154:157], v[170:173], v[122:125]
	v_mfma_f32_16x16x32_bf16 v[118:121], v[158:161], v[170:173], v[118:121]
	v_mfma_f32_16x16x32_bf16 v[114:117], v[162:165], v[170:173], v[114:117]
	ds_read_b128 v[170:173], v149 offset:8192
	ds_read_b128 v[222:225], v169 offset:33792
	s_add_i32 m0, s10, 0xa000
	s_add_u32 s8, s6, 0xb20080
	s_addc_u32 s9, s7, 0
	global_load_lds_dwordx4 v239, s[8:9]
	s_waitcnt lgkmcnt(4)
	v_mfma_f32_16x16x32_bf16 v[110:113], v[150:153], v[174:177], v[110:113]
	v_mfma_f32_16x16x32_bf16 v[106:109], v[154:157], v[174:177], v[106:109]
	v_mfma_f32_16x16x32_bf16 v[102:105], v[158:161], v[174:177], v[102:105]
	v_mfma_f32_16x16x32_bf16 v[98:101], v[162:165], v[174:177], v[98:101]
	ds_read_b128 v[174:177], v149 offset:10240
	ds_read_b128 v[226:229], v169 offset:35840
	s_add_i32 m0, s10, 0x4000
	s_add_u32 s8, s4, s26
	s_addc_u32 s9, s5, s27
	global_load_lds_dwordx4 v238, s[8:9]
	s_waitcnt lgkmcnt(5)
	v_mfma_f32_16x16x32_bf16 v[94:97], v[150:153], v[192:195], v[94:97]
	v_mfma_f32_16x16x32_bf16 v[90:93], v[154:157], v[192:195], v[90:93]
	v_mfma_f32_16x16x32_bf16 v[86:89], v[158:161], v[192:195], v[86:89]
	v_mfma_f32_16x16x32_bf16 v[82:85], v[162:165], v[192:195], v[82:85]
	ds_read_b128 v[192:195], v149 offset:12288
	ds_read_b128 v[230:233], v169 offset:37888
	s_add_i32 m0, s10, 0xc000
	s_add_u32 s8, s6, 0xb40080
	s_addc_u32 s9, s7, 0
	global_load_lds_dwordx4 v239, s[8:9]
	s_waitcnt lgkmcnt(6)
	v_mfma_f32_16x16x32_bf16 v[78:81], v[150:153], v[198:201], v[78:81]
	v_mfma_f32_16x16x32_bf16 v[74:77], v[154:157], v[198:201], v[74:77]
	v_mfma_f32_16x16x32_bf16 v[70:73], v[158:161], v[198:201], v[70:73]
	v_mfma_f32_16x16x32_bf16 v[66:69], v[162:165], v[198:201], v[66:69]
	ds_read_b128 v[198:201], v149 offset:14336
	ds_read_b128 v[234:237], v169 offset:39936
	s_add_i32 m0, s10, 0x6000
	s_add_u32 s8, s4, s30
	s_addc_u32 s9, s5, s31
	global_load_lds_dwordx4 v238, s[8:9]
	s_waitcnt lgkmcnt(7)
	v_mfma_f32_16x16x32_bf16 v[62:65], v[150:153], v[170:173], v[62:65]
	v_mfma_f32_16x16x32_bf16 v[58:61], v[154:157], v[170:173], v[58:61]
	v_mfma_f32_16x16x32_bf16 v[54:57], v[158:161], v[170:173], v[54:57]
	v_mfma_f32_16x16x32_bf16 v[50:53], v[162:165], v[170:173], v[50:53]
	ds_read_b128 v[170:173], v149 offset:1024
	s_add_i32 m0, s10, 0xe000
	s_add_u32 s8, s6, 0xb60080
	s_addc_u32 s9, s7, 0
	global_load_lds_dwordx4 v239, s[8:9]
	s_waitcnt lgkmcnt(6)
	v_mfma_f32_16x16x32_bf16 v[46:49], v[150:153], v[174:177], v[46:49]
	v_mfma_f32_16x16x32_bf16 v[42:45], v[154:157], v[174:177], v[42:45]
	v_mfma_f32_16x16x32_bf16 v[38:41], v[158:161], v[174:177], v[38:41]
	v_mfma_f32_16x16x32_bf16 v[34:37], v[162:165], v[174:177], v[34:37]
	ds_read_b128 v[174:177], v149 offset:3072
	s_waitcnt lgkmcnt(5)
	v_mfma_f32_16x16x32_bf16 v[30:33], v[150:153], v[192:195], v[30:33]
	v_mfma_f32_16x16x32_bf16 v[26:29], v[154:157], v[192:195], v[26:29]
	v_mfma_f32_16x16x32_bf16 v[22:25], v[158:161], v[192:195], v[22:25]
	v_mfma_f32_16x16x32_bf16 v[18:21], v[162:165], v[192:195], v[18:21]
	ds_read_b128 v[192:195], v149 offset:5120
	s_waitcnt lgkmcnt(4)
	v_mfma_f32_16x16x32_bf16 v[14:17], v[150:153], v[198:201], v[14:17]
	v_mfma_f32_16x16x32_bf16 v[10:13], v[154:157], v[198:201], v[10:13]
	v_mfma_f32_16x16x32_bf16 v[6:9], v[158:161], v[198:201], v[6:9]
	v_mfma_f32_16x16x32_bf16 v[2:5], v[162:165], v[198:201], v[2:5]
	ds_read_b128 v[198:201], v149 offset:7168
	s_waitcnt lgkmcnt(3)
	v_mfma_f32_16x16x32_bf16 v[126:129], v[222:225], v[170:173], v[126:129]
	v_mfma_f32_16x16x32_bf16 v[122:125], v[226:229], v[170:173], v[122:125]
	v_mfma_f32_16x16x32_bf16 v[118:121], v[230:233], v[170:173], v[118:121]
	v_mfma_f32_16x16x32_bf16 v[114:117], v[234:237], v[170:173], v[114:117]
	ds_read_b128 v[170:173], v149 offset:9216
	s_waitcnt lgkmcnt(3)
; #define WAIT_V0() asm volatile("s_waitcnt vmcnt(0)" ::: "memory")
; #define SBAR() __builtin_amdgcn_sched_barrier(0)
; template <int EPI>
; DEVI void gemm_tile(const u16* __restrict__ Ab, long lda, const u16* __restrict__ Bb, long ldb, int K, const EpiArgs& e,
;                     bool have0 = false, const u16* __restrict__ nA = nullptr, const u16* __restrict__ nB = nullptr) {
;     ...
;   for (int t = 0; t < nt; ++t) {
;     const int cur = t & 1;
;     if (t + 1 < nt) GLDS_STAGE(cur ^ 1, t + 1);
;     else if (nA) {
; #pragma unroll
;       for (int i = 0; i < GL; ++i) {
;         __builtin_amdgcn_global_load_lds((const unsigned*)(nA + (long)i * 64 * lda + toffA), (unsigned*)(g_shm + wid * 1024 + i * 8192), 16, 0, 0);
;         __builtin_amdgcn_global_load_lds((const unsigned*)(nB + (long)i * 64 * ldb + toffB), (unsigned*)(g_shm + TILE_B + wid * 1024 + i * 8192), 16, 0, 0);
;       }
;     }
;     const char* sb = g_shm + cur * STAGE_B;
; #pragma unroll
;     for (int ks = 0; ks < 2; ++ks) {
;       bf16x8 Bf[4];
; #pragma unroll
;       for (int n = 0; n < 4; ++n) Bf[n] = *(const bf16x8*)(sb + b_base + n * 2048 + ks * 1024);
; #pragma unroll
;       for (int mh = 0; mh < 2; ++mh) {
;         bf16x8 At[4];
; #pragma unroll
;         for (int m = 0; m < 4; ++m) At[m] = *(const bf16x8*)(sb + a_base + (mh * 4 + m) * 2048 + ks * 1024);
;         __builtin_amdgcn_s_setprio(1);
; #pragma unroll
;         for (int m = 0; m < 4; ++m)
; #pragma unroll
;           for (int n = 0; n < 4; ++n) acc[mh * 4 + m][n] = __builtin_amdgcn_mfma_f32_16x16x32_bf16(Bf[n], At[m], acc[mh * 4 + m][n], 0, 0, 0);
;         __builtin_amdgcn_s_setprio(0);
;       }
;       SBAR();
;     }
;     if (t + 1 < nt) { WAIT_V0(); __syncthreads(); }
;   }
	v_mfma_f32_16x16x32_bf16 v[110:113], v[222:225], v[174:177], v[110:113]
	v_mfma_f32_16x16x32_bf16 v[106:109], v[226:229], v[174:177], v[106:109]
	v_mfma_f32_16x16x32_bf16 v[102:105], v[230:233], v[174:177], v[102:105]
	v_mfma_f32_16x16x32_bf16 v[98:101], v[234:237], v[174:177], v[98:101]
	ds_read_b128 v[174:177], v149 offset:11264
	s_waitcnt lgkmcnt(3)
	v_mfma_f32_16x16x32_bf16 v[94:97], v[222:225], v[192:195], v[94:97]
	v_mfma_f32_16x16x32_bf16 v[90:93], v[226:229], v[192:195], v[90:93]
	v_mfma_f32_16x16x32_bf16 v[86:89], v[230:233], v[192:195], v[86:89]
	v_mfma_f32_16x16x32_bf16 v[82:85], v[234:237], v[192:195], v[82:85]
	ds_read_b128 v[192:195], v149 offset:13312
	s_waitcnt lgkmcnt(3)
	v_mfma_f32_16x16x32_bf16 v[78:81], v[222:225], v[198:201], v[78:81]
	v_mfma_f32_16x16x32_bf16 v[74:77], v[226:229], v[198:201], v[74:77]
	v_mfma_f32_16x16x32_bf16 v[70:73], v[230:233], v[198:201], v[70:73]
	v_mfma_f32_16x16x32_bf16 v[66:69], v[234:237], v[198:201], v[66:69]
	ds_read_b128 v[198:201], v149 offset:15360
	s_waitcnt lgkmcnt(3)
	v_mfma_f32_16x16x32_bf16 v[62:65], v[222:225], v[170:173], v[62:65]
	v_mfma_f32_16x16x32_bf16 v[58:61], v[226:229], v[170:173], v[58:61]
	v_mfma_f32_16x16x32_bf16 v[54:57], v[230:233], v[170:173], v[54:57]
	v_mfma_f32_16x16x32_bf16 v[50:53], v[234:237], v[170:173], v[50:53]
	s_waitcnt lgkmcnt(2)
	v_mfma_f32_16x16x32_bf16 v[46:49], v[222:225], v[174:177], v[46:49]
	v_mfma_f32_16x16x32_bf16 v[42:45], v[226:229], v[174:177], v[42:45]
	v_mfma_f32_16x16x32_bf16 v[38:41], v[230:233], v[174:177], v[38:41]
	v_mfma_f32_16x16x32_bf16 v[34:37], v[234:237], v[174:177], v[34:37]
	s_waitcnt lgkmcnt(0)
	s_add_i32 s2, s2, 0x10000
	s_waitcnt vmcnt(0)
	s_add_u32 s18, s18, 0x80
	s_addc_u32 s19, s19, 0
	s_cmpk_eq_i32 s18, 0x780
	s_waitcnt vmcnt(0)
	s_barrier
	s_cselect_b32 s100, 1, 0
	s_and_b32 s3, s2, 0x10000
	v_or_b32_e32 v149, s3, v147
	v_add_u32_e32 v169, v149, v148
	v_add_u32_e32 v149, v149, v146
	ds_read_b128 v[150:153], v169 offset:32768
	ds_read_b128 v[154:157], v169 offset:34816
	ds_read_b128 v[158:161], v169 offset:36864
	ds_read_b128 v[162:165], v169 offset:38912
	ds_read_b128 v[170:173], v149
	ds_read_b128 v[174:177], v149 offset:2048
	s_add_u32 s4, s4, 0x80
	s_addc_u32 s5, s5, 0
	s_add_u32 s6, s6, 0x80
	s_addc_u32 s7, s7, 0
	s_cmp_eq_u32 s100, 1
	s_cbranch_scc1 .Lkl_1370_s1
	v_readfirstlane_b32 s10, v140
	s_xor_b32 s8, s3, 0x10000
	s_nop 0
	s_add_i32 s10, s10, s8
	s_add_i32 m0, s10, 0x0
	s_add_u32 s8, s4, s12
	s_addc_u32 s9, s5, s13
	global_load_lds_dwordx4 v238, s[8:9]
.Lkl_1370_s1:
	v_mfma_f32_16x16x32_bf16 v[30:33], v[222:225], v[192:195], v[30:33]
	v_mfma_f32_16x16x32_bf16 v[26:29], v[226:229], v[192:195], v[26:29]
	v_mfma_f32_16x16x32_bf16 v[22:25], v[230:233], v[192:195], v[22:25]
	v_mfma_f32_16x16x32_bf16 v[18:21], v[234:237], v[192:195], v[18:21]
	ds_read_b128 v[192:195], v149 offset:4096
	s_cmp_eq_u32 s100, 1
	s_cbranch_scc1 .Lkl_1370_s2
	s_add_i32 m0, s10, 0x8000
	s_add_u32 s8, s6, 0xb00080
	s_addc_u32 s9, s7, 0
	global_load_lds_dwordx4 v239, s[8:9]
.Lkl_1370_s2:
	v_mfma_f32_16x16x32_bf16 v[14:17], v[222:225], v[198:201], v[14:17]
	v_mfma_f32_16x16x32_bf16 v[10:13], v[226:229], v[198:201], v[10:13]
	v_mfma_f32_16x16x32_bf16 v[6:9], v[230:233], v[198:201], v[6:9]
	v_mfma_f32_16x16x32_bf16 v[2:5], v[234:237], v[198:201], v[2:5]
	ds_read_b128 v[198:201], v149 offset:6144
	s_cmp_eq_u32 s100, 1
	s_cbranch_scc1 .Lkl_1370_s3
	s_add_i32 m0, s10, 0x2000
	s_add_u32 s8, s4, s14
	s_addc_u32 s9, s5, s15
	global_load_lds_dwordx4 v238, s[8:9]
.Lkl_1370_s3:
	s_cmp_eq_u32 s100, 1
	s_cbranch_scc0 .Lkl_1370
	s_nop 3
	v_readlane_b32 s4, v240, 0
	v_readlane_b32 s5, v240, 1
	v_readlane_b32 s6, v240, 2
	v_readlane_b32 s7, v240, 3
	v_readlane_b32 s8, v240, 4
	v_readlane_b32 s9, v240, 5
	v_readlane_b32 s10, v240, 6
	s_waitcnt lgkmcnt(0)
	s_xor_b32 s3, s3, 0x10000
	v_or_b32_e32 v149, s3, v147
	v_add_u32_e32 v169, v149, v148
	v_add_u32_e32 v149, v149, v146
	s_cmp_eq_u32 s100, 1
	s_cmp_eq_u64 s[10:11], 0
	s_cbranch_scc1 .LBB0_1358
	v_readfirstlane_b32 s2, v140
	v_lshl_add_u64 v[132:133], s[10:11], 0, v[130:131]
	s_mov_b32 m0, s2
	v_readfirstlane_b32 s2, v145
	v_lshl_add_u64 v[130:131], s[16:17], 0, v[130:131]
	global_load_lds_dwordx4 v[132:133], off
	s_mov_b32 m0, s2
	s_mov_b64 s[16:17], 0x20000
	v_readfirstlane_b32 s2, v144
	global_load_lds_dwordx4 v[130:131], off
	v_lshl_add_u64 v[134:135], v[132:133], 0, s[16:17]
	s_mov_b32 m0, s2
	v_readfirstlane_b32 s2, v143
	global_load_lds_dwordx4 v[134:135], off
	v_lshl_add_u64 v[134:135], v[130:131], 0, s[16:17]
	s_mov_b32 m0, s2
	v_readfirstlane_b32 s2, v142
	global_load_lds_dwordx4 v[134:135], off
	v_lshl_add_u64 v[134:135], v[132:133], 0, s[96:97]
	s_mov_b32 m0, s2
	v_readfirstlane_b32 s2, v141
	global_load_lds_dwordx4 v[134:135], off
	v_lshl_add_u64 v[134:135], v[130:131], 0, s[96:97]
	s_mov_b32 m0, s2
	s_mov_b64 s[16:17], 0x60000
	v_readfirstlane_b32 s2, v139
	global_load_lds_dwordx4 v[134:135], off
	v_lshl_add_u64 v[132:133], v[132:133], 0, s[16:17]
	s_mov_b32 m0, s2
	v_readfirstlane_b32 s2, v138
	global_load_lds_dwordx4 v[132:133], off
	v_lshl_add_u64 v[130:131], v[130:131], 0, s[16:17]
	s_mov_b32 m0, s2
	s_nop 0
	global_load_lds_dwordx4 v[130:131], off
	s_branch .LBB0_1358

; #define WAIT_V0() asm volatile("s_waitcnt vmcnt(0)" ::: "memory")
; #define SBAR() __builtin_amdgcn_sched_barrier(0)
; template <int EPI>
; DEVI void gemm_tile(const u16* __restrict__ Ab, long lda, const u16* __restrict__ Bb, long ldb, int K, const EpiArgs& e,
;                     bool have0 = false, const u16* __restrict__ nA = nullptr, const u16* __restrict__ nB = nullptr) {
;     ...
;   for (int t = 0; t < nt; ++t) {
;     const int cur = t & 1;
;     if (t + 1 < nt) GLDS_STAGE(cur ^ 1, t + 1);
;     else if (nA) {
; #pragma unroll
;       for (int i = 0; i < GL; ++i) {
;         __builtin_amdgcn_global_load_lds((const unsigned*)(nA + (long)i * 64 * lda + toffA), (unsigned*)(g_shm + wid * 1024 + i * 8192), 16, 0, 0);
;         __builtin_amdgcn_global_load_lds((const unsigned*)(nB + (long)i * 64 * ldb + toffB), (unsigned*)(g_shm + TILE_B + wid * 1024 + i * 8192), 16, 0, 0);
;       }
;     }
;     const char* sb = g_shm + cur * STAGE_B;
; #pragma unroll
;     for (int ks = 0; ks < 2; ++ks) {
;       bf16x8 Bf[4];
; #pragma unroll
;       for (int n = 0; n < 4; ++n) Bf[n] = *(const bf16x8*)(sb + b_base + n * 2048 + ks * 1024);
; #pragma unroll
;       for (int mh = 0; mh < 2; ++mh) {
;         bf16x8 At[4];
; #pragma unroll
;         for (int m = 0; m < 4; ++m) At[m] = *(const bf16x8*)(sb + a_base + (mh * 4 + m) * 2048 + ks * 1024);
;         __builtin_amdgcn_s_setprio(1);
; #pragma unroll
;         for (int m = 0; m < 4; ++m)
; #pragma unroll
;           for (int n = 0; n < 4; ++n) acc[mh * 4 + m][n] = __builtin_amdgcn_mfma_f32_16x16x32_bf16(Bf[n], At[m], acc[mh * 4 + m][n], 0, 0, 0);
;         __builtin_amdgcn_s_setprio(0);
;       }
;       SBAR();
;     }
;     if (t + 1 < nt) { WAIT_V0(); __syncthreads(); }
;   }
.LBB0_1404:
	s_and_b32 s26, s3, 0x10000
	v_or_b32_e32 v150, s26, v149
	v_add_u32_e32 v169, v150, v148
	v_or_b32_e32 v150, s26, v146
	v_add_u32_e32 v178, v150, v147
	ds_read_b128 v[150:153], v169 offset:32768
	ds_read_b128 v[154:157], v169 offset:34816
	ds_read_b128 v[158:161], v169 offset:36864
	ds_read_b128 v[162:165], v169 offset:38912
	ds_read_b128 v[170:173], v178
	ds_read_b128 v[174:177], v178 offset:2048
	ds_read_b128 v[192:195], v178 offset:4096
	ds_read_b128 v[198:201], v178 offset:6144
	v_writelane_b32 v240, s4, 0
	v_writelane_b32 v240, s5, 1
	v_writelane_b32 v240, s6, 2
	v_writelane_b32 v240, s7, 3
	v_writelane_b32 v240, s8, 4
	v_writelane_b32 v240, s9, 5
	v_writelane_b32 v240, s10, 6
	v_readfirstlane_b32 s4, v134
	v_readfirstlane_b32 s5, v135
	s_nop 1
	v_subrev_u32_e32 v238, s4, v134
	s_add_u32 s4, s4, s18
	s_addc_u32 s5, s5, s19
	v_readfirstlane_b32 s6, v136
	v_readfirstlane_b32 s7, v137
	s_nop 1
	v_subrev_u32_e32 v239, s6, v136
	s_add_u32 s6, s6, s18
	s_addc_u32 s7, s7, s19
	v_readfirstlane_b32 s10, v143
	s_xor_b32 s8, s26, 0x10000
	s_nop 0
	s_add_i32 s10, s10, s8
	s_add_i32 m0, s10, 0x0
	s_add_u32 s8, s4, s30
	s_addc_u32 s9, s5, s31
	global_load_lds_dwordx4 v238, s[8:9]
	s_add_i32 m0, s10, 0x8000
	s_add_u32 s8, s6, 0x1b80080
	s_addc_u32 s9, s7, 0
	global_load_lds_dwordx4 v239, s[8:9]
	s_add_i32 m0, s10, 0x2000
	s_add_u32 s8, s4, vcc_lo
	s_addc_u32 s9, s5, vcc_hi
	global_load_lds_dwordx4 v238, s[8:9]
.Lkl_1404:
	s_waitcnt lgkmcnt(3)
	v_mfma_f32_16x16x32_bf16 v[126:129], v[150:153], v[170:173], v[126:129]
	v_mfma_f32_16x16x32_bf16 v[122:125], v[154:157], v[170:173], v[122:125]
	v_mfma_f32_16x16x32_bf16 v[118:121], v[158:161], v[170:173], v[118:121]
	v_mfma_f32_16x16x32_bf16 v[114:117], v[162:165], v[170:173], v[114:117]
	ds_read_b128 v[170:173], v178 offset:8192
	ds_read_b128 v[222:225], v169 offset:33792
	s_add_i32 m0, s10, 0xa000
	s_add_u32 s8, s6, 0x1bd8080
	s_addc_u32 s9, s7, 0
	global_load_lds_dwordx4 v239, s[8:9]
	s_waitcnt lgkmcnt(4)
	v_mfma_f32_16x16x32_bf16 v[110:113], v[150:153], v[174:177], v[110:113]
	v_mfma_f32_16x16x32_bf16 v[106:109], v[154:157], v[174:177], v[106:109]
	v_mfma_f32_16x16x32_bf16 v[102:105], v[158:161], v[174:177], v[102:105]
	v_mfma_f32_16x16x32_bf16 v[98:101], v[162:165], v[174:177], v[98:101]
	ds_read_b128 v[174:177], v178 offset:10240
	ds_read_b128 v[226:229], v169 offset:35840
	s_add_i32 m0, s10, 0x4000
	s_add_u32 s8, s4, s12
	s_addc_u32 s9, s5, s13
	global_load_lds_dwordx4 v238, s[8:9]
	s_waitcnt lgkmcnt(5)
	v_mfma_f32_16x16x32_bf16 v[94:97], v[150:153], v[192:195], v[94:97]
	v_mfma_f32_16x16x32_bf16 v[90:93], v[154:157], v[192:195], v[90:93]
	v_mfma_f32_16x16x32_bf16 v[86:89], v[158:161], v[192:195], v[86:89]
	v_mfma_f32_16x16x32_bf16 v[82:85], v[162:165], v[192:195], v[82:85]
	ds_read_b128 v[192:195], v178 offset:12288
	ds_read_b128 v[230:233], v169 offset:37888
	s_add_i32 m0, s10, 0xc000
	s_add_u32 s8, s6, 0x1c30080
	s_addc_u32 s9, s7, 0
	global_load_lds_dwordx4 v239, s[8:9]
	s_waitcnt lgkmcnt(6)
	v_mfma_f32_16x16x32_bf16 v[78:81], v[150:153], v[198:201], v[78:81]
	v_mfma_f32_16x16x32_bf16 v[74:77], v[154:157], v[198:201], v[74:77]
	v_mfma_f32_16x16x32_bf16 v[70:73], v[158:161], v[198:201], v[70:73]
	v_mfma_f32_16x16x32_bf16 v[66:69], v[162:165], v[198:201], v[66:69]
	ds_read_b128 v[198:201], v178 offset:14336
	ds_read_b128 v[234:237], v169 offset:39936
	s_add_i32 m0, s10, 0x6000
	s_add_u32 s8, s4, s14
	s_addc_u32 s9, s5, s15
	global_load_lds_dwordx4 v238, s[8:9]
	s_waitcnt lgkmcnt(7)
	v_mfma_f32_16x16x32_bf16 v[62:65], v[150:153], v[170:173], v[62:65]
	v_mfma_f32_16x16x32_bf16 v[58:61], v[154:157], v[170:173], v[58:61]
	v_mfma_f32_16x16x32_bf16 v[54:57], v[158:161], v[170:173], v[54:57]
	v_mfma_f32_16x16x32_bf16 v[50:53], v[162:165], v[170:173], v[50:53]
	ds_read_b128 v[170:173], v178 offset:1024
	s_add_i32 m0, s10, 0xe000
	s_add_u32 s8, s6, 0x1c88080
	s_addc_u32 s9, s7, 0
	global_load_lds_dwordx4 v239, s[8:9]
	s_waitcnt lgkmcnt(6)
	v_mfma_f32_16x16x32_bf16 v[46:49], v[150:153], v[174:177], v[46:49]
	v_mfma_f32_16x16x32_bf16 v[42:45], v[154:157], v[174:177], v[42:45]
	v_mfma_f32_16x16x32_bf16 v[38:41], v[158:161], v[174:177], v[38:41]
	v_mfma_f32_16x16x32_bf16 v[34:37], v[162:165], v[174:177], v[34:37]
	ds_read_b128 v[174:177], v178 offset:3072
	s_waitcnt lgkmcnt(5)
	v_mfma_f32_16x16x32_bf16 v[30:33], v[150:153], v[192:195], v[30:33]
	v_mfma_f32_16x16x32_bf16 v[26:29], v[154:157], v[192:195], v[26:29]
	v_mfma_f32_16x16x32_bf16 v[22:25], v[158:161], v[192:195], v[22:25]
	v_mfma_f32_16x16x32_bf16 v[18:21], v[162:165], v[192:195], v[18:21]
	ds_read_b128 v[192:195], v178 offset:5120
	s_waitcnt lgkmcnt(4)
	v_mfma_f32_16x16x32_bf16 v[14:17], v[150:153], v[198:201], v[14:17]
	v_mfma_f32_16x16x32_bf16 v[10:13], v[154:157], v[198:201], v[10:13]
	v_mfma_f32_16x16x32_bf16 v[6:9], v[158:161], v[198:201], v[6:9]
	v_mfma_f32_16x16x32_bf16 v[2:5], v[162:165], v[198:201], v[2:5]
	ds_read_b128 v[198:201], v178 offset:7168
	s_waitcnt lgkmcnt(3)
	v_mfma_f32_16x16x32_bf16 v[126:129], v[222:225], v[170:173], v[126:129]
	v_mfma_f32_16x16x32_bf16 v[122:125], v[226:229], v[170:173], v[122:125]
	v_mfma_f32_16x16x32_bf16 v[118:121], v[230:233], v[170:173], v[118:121]
	v_mfma_f32_16x16x32_bf16 v[114:117], v[234:237], v[170:173], v[114:117]
	ds_read_b128 v[170:173], v178 offset:9216
	s_waitcnt lgkmcnt(3)
; #define WAIT_V0() asm volatile("s_waitcnt vmcnt(0)" ::: "memory")
; #define SBAR() __builtin_amdgcn_sched_barrier(0)
; template <int EPI>
; DEVI void gemm_tile(const u16* __restrict__ Ab, long lda, const u16* __restrict__ Bb, long ldb, int K, const EpiArgs& e,
;                     bool have0 = false, const u16* __restrict__ nA = nullptr, const u16* __restrict__ nB = nullptr) {
;     ...
;   for (int t = 0; t < nt; ++t) {
;     const int cur = t & 1;
;     if (t + 1 < nt) GLDS_STAGE(cur ^ 1, t + 1);
;     else if (nA) {
; #pragma unroll
;       for (int i = 0; i < GL; ++i) {
;         __builtin_amdgcn_global_load_lds((const unsigned*)(nA + (long)i * 64 * lda + toffA), (unsigned*)(g_shm + wid * 1024 + i * 8192), 16, 0, 0);
;         __builtin_amdgcn_global_load_lds((const unsigned*)(nB + (long)i * 64 * ldb + toffB), (unsigned*)(g_shm + TILE_B + wid * 1024 + i * 8192), 16, 0, 0);
;       }
;     }
;     const char* sb = g_shm + cur * STAGE_B;
; #pragma unroll
;     for (int ks = 0; ks < 2; ++ks) {
;       bf16x8 Bf[4];
; #pragma unroll
;       for (int n = 0; n < 4; ++n) Bf[n] = *(const bf16x8*)(sb + b_base + n * 2048 + ks * 1024);
; #pragma unroll
;       for (int mh = 0; mh < 2; ++mh) {
;         bf16x8 At[4];
; #pragma unroll
;         for (int m = 0; m < 4; ++m) At[m] = *(const bf16x8*)(sb + a_base + (mh * 4 + m) * 2048 + ks * 1024);
;         __builtin_amdgcn_s_setprio(1);
; #pragma unroll
;         for (int m = 0; m < 4; ++m)
; #pragma unroll
;           for (int n = 0; n < 4; ++n) acc[mh * 4 + m][n] = __builtin_amdgcn_mfma_f32_16x16x32_bf16(Bf[n], At[m], acc[mh * 4 + m][n], 0, 0, 0);
;         __builtin_amdgcn_s_setprio(0);
;       }
;       SBAR();
;     }
;     if (t + 1 < nt) { WAIT_V0(); __syncthreads(); }
;   }
	v_mfma_f32_16x16x32_bf16 v[110:113], v[222:225], v[174:177], v[110:113]
	v_mfma_f32_16x16x32_bf16 v[106:109], v[226:229], v[174:177], v[106:109]
	v_mfma_f32_16x16x32_bf16 v[102:105], v[230:233], v[174:177], v[102:105]
	v_mfma_f32_16x16x32_bf16 v[98:101], v[234:237], v[174:177], v[98:101]
	ds_read_b128 v[174:177], v178 offset:11264
	s_waitcnt lgkmcnt(3)
	v_mfma_f32_16x16x32_bf16 v[94:97], v[222:225], v[192:195], v[94:97]
	v_mfma_f32_16x16x32_bf16 v[90:93], v[226:229], v[192:195], v[90:93]
	v_mfma_f32_16x16x32_bf16 v[86:89], v[230:233], v[192:195], v[86:89]
	v_mfma_f32_16x16x32_bf16 v[82:85], v[234:237], v[192:195], v[82:85]
	ds_read_b128 v[192:195], v178 offset:13312
	s_waitcnt lgkmcnt(3)
	v_mfma_f32_16x16x32_bf16 v[78:81], v[222:225], v[198:201], v[78:81]
	v_mfma_f32_16x16x32_bf16 v[74:77], v[226:229], v[198:201], v[74:77]
	v_mfma_f32_16x16x32_bf16 v[70:73], v[230:233], v[198:201], v[70:73]
	v_mfma_f32_16x16x32_bf16 v[66:69], v[234:237], v[198:201], v[66:69]
	ds_read_b128 v[198:201], v178 offset:15360
	s_waitcnt lgkmcnt(3)
	v_mfma_f32_16x16x32_bf16 v[62:65], v[222:225], v[170:173], v[62:65]
	v_mfma_f32_16x16x32_bf16 v[58:61], v[226:229], v[170:173], v[58:61]
	v_mfma_f32_16x16x32_bf16 v[54:57], v[230:233], v[170:173], v[54:57]
	v_mfma_f32_16x16x32_bf16 v[50:53], v[234:237], v[170:173], v[50:53]
	s_waitcnt lgkmcnt(2)
	v_mfma_f32_16x16x32_bf16 v[46:49], v[222:225], v[174:177], v[46:49]
	v_mfma_f32_16x16x32_bf16 v[42:45], v[226:229], v[174:177], v[42:45]
	v_mfma_f32_16x16x32_bf16 v[38:41], v[230:233], v[174:177], v[38:41]
	v_mfma_f32_16x16x32_bf16 v[34:37], v[234:237], v[174:177], v[34:37]
	s_waitcnt lgkmcnt(0)
	s_waitcnt vmcnt(0)
	s_add_u32 s18, s18, 0x80
	s_addc_u32 s19, s19, 0
	s_add_i32 s3, s3, 0x10000
	s_cmpk_eq_i32 s18, 0x1580
	s_waitcnt vmcnt(0)
	s_barrier
	s_cselect_b32 s100, 1, 0
	s_and_b32 s26, s3, 0x10000
	v_or_b32_e32 v150, s26, v149
	v_add_u32_e32 v169, v150, v148
	v_or_b32_e32 v150, s26, v146
	v_add_u32_e32 v178, v150, v147
	ds_read_b128 v[150:153], v169 offset:32768
	ds_read_b128 v[154:157], v169 offset:34816
	ds_read_b128 v[158:161], v169 offset:36864
	ds_read_b128 v[162:165], v169 offset:38912
	ds_read_b128 v[170:173], v178
	ds_read_b128 v[174:177], v178 offset:2048
	s_add_u32 s4, s4, 0x80
	s_addc_u32 s5, s5, 0
	s_add_u32 s6, s6, 0x80
	s_addc_u32 s7, s7, 0
	s_cmp_eq_u32 s100, 1
	s_cbranch_scc1 .Lkl_1404_s1
	v_readfirstlane_b32 s10, v143
	s_xor_b32 s8, s26, 0x10000
	s_nop 0
	s_add_i32 s10, s10, s8
	s_add_i32 m0, s10, 0x0
	s_add_u32 s8, s4, s30
	s_addc_u32 s9, s5, s31
	global_load_lds_dwordx4 v238, s[8:9]
.Lkl_1404_s1:
	v_mfma_f32_16x16x32_bf16 v[30:33], v[222:225], v[192:195], v[30:33]
	v_mfma_f32_16x16x32_bf16 v[26:29], v[226:229], v[192:195], v[26:29]
	v_mfma_f32_16x16x32_bf16 v[22:25], v[230:233], v[192:195], v[22:25]
	v_mfma_f32_16x16x32_bf16 v[18:21], v[234:237], v[192:195], v[18:21]
	ds_read_b128 v[192:195], v178 offset:4096
	s_cmp_eq_u32 s100, 1
	s_cbranch_scc1 .Lkl_1404_s2
	s_add_i32 m0, s10, 0x8000
	s_add_u32 s8, s6, 0x1b80080
	s_addc_u32 s9, s7, 0
	global_load_lds_dwordx4 v239, s[8:9]
.Lkl_1404_s2:
	v_mfma_f32_16x16x32_bf16 v[14:17], v[222:225], v[198:201], v[14:17]
	v_mfma_f32_16x16x32_bf16 v[10:13], v[226:229], v[198:201], v[10:13]
	v_mfma_f32_16x16x32_bf16 v[6:9], v[230:233], v[198:201], v[6:9]
	v_mfma_f32_16x16x32_bf16 v[2:5], v[234:237], v[198:201], v[2:5]
	ds_read_b128 v[198:201], v178 offset:6144
	s_cmp_eq_u32 s100, 1
	s_cbranch_scc1 .Lkl_1404_s3
	s_add_i32 m0, s10, 0x2000
	s_add_u32 s8, s4, vcc_lo
	s_addc_u32 s9, s5, vcc_hi
	global_load_lds_dwordx4 v238, s[8:9]
.Lkl_1404_s3:
	s_cmp_eq_u32 s100, 1
	s_cbranch_scc0 .Lkl_1404
	s_nop 3
	v_readlane_b32 s4, v240, 0
	v_readlane_b32 s5, v240, 1
	v_readlane_b32 s6, v240, 2
	v_readlane_b32 s7, v240, 3
	v_readlane_b32 s8, v240, 4
	v_readlane_b32 s9, v240, 5
	v_readlane_b32 s10, v240, 6
	s_waitcnt lgkmcnt(0)
	s_xor_b32 s26, s26, 0x10000
	v_or_b32_e32 v150, s26, v149
	v_add_u32_e32 v169, v150, v148
	v_or_b32_e32 v150, s26, v146
	v_add_u32_e32 v178, v150, v147
	s_cmp_eq_u32 s100, 1
	s_cmp_eq_u64 s[10:11], 0
	s_cbranch_scc1 .LBB0_1392
	v_readfirstlane_b32 s3, v143
	v_lshl_add_u64 v[134:135], s[10:11], 0, v[132:133]
	s_mov_b32 m0, s3
	v_readfirstlane_b32 s3, v145
	v_lshl_add_u64 v[132:133], s[16:17], 0, v[132:133]
	global_load_lds_dwordx4 v[134:135], off
	s_mov_b32 m0, s3
	s_mov_b64 s[16:17], 0x58000
	v_readfirstlane_b32 s3, v144
	global_load_lds_dwordx4 v[132:133], off
	v_lshl_add_u64 v[136:137], v[134:135], 0, s[16:17]
	s_mov_b32 m0, s3
	v_readfirstlane_b32 s3, v142
	global_load_lds_dwordx4 v[136:137], off
	v_lshl_add_u64 v[136:137], v[132:133], 0, s[16:17]
	s_mov_b32 m0, s3
	s_mov_b64 s[16:17], 0xb0000
	v_readfirstlane_b32 s3, v141
	global_load_lds_dwordx4 v[136:137], off
	v_lshl_add_u64 v[136:137], v[134:135], 0, s[16:17]
	s_mov_b32 m0, s3
	v_readfirstlane_b32 s3, v140
	global_load_lds_dwordx4 v[136:137], off
	v_lshl_add_u64 v[136:137], v[132:133], 0, s[16:17]
	s_mov_b32 m0, s3
	s_mov_b64 s[16:17], 0x108000
	v_readfirstlane_b32 s3, v139
	global_load_lds_dwordx4 v[136:137], off
	v_lshl_add_u64 v[134:135], v[134:135], 0, s[16:17]
	s_mov_b32 m0, s3
	v_readfirstlane_b32 s3, v138
	global_load_lds_dwordx4 v[134:135], off
	v_lshl_add_u64 v[132:133], v[132:133], 0, s[16:17]
	s_mov_b32 m0, s3
	s_nop 0
	global_load_lds_dwordx4 v[132:133], off
	s_branch .LBB0_1392

; __global__ void __launch_bounds__(512) fwd_megakernel(Params P) {
	.amdhsa_kernel _Z14fwd_megakernel6Params
		.amdhsa_group_segment_fixed_size 139264
		.amdhsa_private_segment_fixed_size 0
		.amdhsa_kernarg_size 1448
		.amdhsa_user_sgpr_count 2
		.amdhsa_user_sgpr_dispatch_ptr 0
		.amdhsa_user_sgpr_queue_ptr 0
		.amdhsa_user_sgpr_kernarg_segment_ptr 1
		.amdhsa_user_sgpr_dispatch_id 0
		.amdhsa_user_sgpr_kernarg_preload_length 0
		.amdhsa_user_sgpr_kernarg_preload_offset 0
		.amdhsa_user_sgpr_private_segment_size 0
		.amdhsa_uses_dynamic_stack 0
		.amdhsa_enable_private_segment 0
		.amdhsa_system_sgpr_workgroup_id_x 1
		.amdhsa_system_sgpr_workgroup_id_y 0
		.amdhsa_system_sgpr_workgroup_id_z 0
		.amdhsa_system_sgpr_workgroup_info 0
		.amdhsa_system_vgpr_workitem_id 2
		.amdhsa_next_free_vgpr 256
		.amdhsa_next_free_sgpr 102
		.amdhsa_accum_offset 256
		.amdhsa_reserve_vcc 1
		.amdhsa_float_round_mode_32 0
		.amdhsa_float_round_mode_16_64 0
		.amdhsa_float_denorm_mode_32 3
		.amdhsa_float_denorm_mode_16_64 3
		.amdhsa_dx10_clamp 1
		.amdhsa_ieee_mode 1
		.amdhsa_fp16_overflow 0
		.amdhsa_tg_split 0
		.amdhsa_exception_fp_ieee_invalid_op 0
		.amdhsa_exception_fp_denorm_src 0
		.amdhsa_exception_fp_ieee_div_zero 0
		.amdhsa_exception_fp_ieee_overflow 0
		.amdhsa_exception_fp_ieee_underflow 0
		.amdhsa_exception_fp_ieee_inexact 0
		.amdhsa_exception_int_div_zero 0
	.end_amdhsa_kernel

; __global__ void __launch_bounds__(512) fwd_megakernel(Params P) {
.Lfunc_end0:
	.size	_Z14fwd_megakernel6Params, .Lfunc_end0-_Z14fwd_megakernel6Params
	.set _Z14fwd_megakernel6Params.num_vgpr, 256
	.set _Z14fwd_megakernel6Params.num_agpr, 0
	.set _Z14fwd_megakernel6Params.numbered_sgpr, 102
	.set _Z14fwd_megakernel6Params.num_named_barrier, 0
	.set _Z14fwd_megakernel6Params.private_seg_size, 0
	.set _Z14fwd_megakernel6Params.uses_vcc, 1
	.set _Z14fwd_megakernel6Params.uses_flat_scratch, 0
	.set _Z14fwd_megakernel6Params.has_dyn_sized_stack, 0
	.set _Z14fwd_megakernel6Params.has_recursion, 0
	.set _Z14fwd_megakernel6Params.has_indirect_call, 0

; __global__ void __launch_bounds__(512) fwd_megakernel(Params P) {
amdhsa.kernels:
  - .agpr_count:     0
    .args:
      - .offset:         0
        .size:           1192
        .value_kind:     by_value
      - .offset:         1192
        .size:           4
        .value_kind:     hidden_block_count_x
      - .offset:         1196
        .size:           4
        .value_kind:     hidden_block_count_y
      - .offset:         1200
        .size:           4
        .value_kind:     hidden_block_count_z
      - .offset:         1204
        .size:           2
        .value_kind:     hidden_group_size_x
      - .offset:         1206
        .size:           2
        .value_kind:     hidden_group_size_y
      - .offset:         1208
        .size:           2
        .value_kind:     hidden_group_size_z
      - .offset:         1210
        .size:           2
        .value_kind:     hidden_remainder_x
      - .offset:         1212
        .size:           2
        .value_kind:     hidden_remainder_y
      - .offset:         1214
        .size:           2
        .value_kind:     hidden_remainder_z
      - .offset:         1232
        .size:           8
        .value_kind:     hidden_global_offset_x
      - .offset:         1240
        .size:           8
        .value_kind:     hidden_global_offset_y
      - .offset:         1248
        .size:           8
        .value_kind:     hidden_global_offset_z
      - .offset:         1256
        .size:           2
        .value_kind:     hidden_grid_dims
      - .offset:         1280
        .size:           8
        .value_kind:     hidden_multigrid_sync_arg
    .group_segment_fixed_size: 139264
    .kernarg_segment_align: 8
    .kernarg_segment_size: 1448
    .language:       OpenCL C
    .language_version:
      - 2
      - 0
    .max_flat_workgroup_size: 512
    .name:           _Z14fwd_megakernel6Params
    .private_segment_fixed_size: 0
    .sgpr_count:     108
    .sgpr_spill_count: 196
    .symbol:         _Z14fwd_megakernel6Params.kd
    .uniform_work_group_size: 1
    .uses_dynamic_stack: false
    .vgpr_count:     256
    .vgpr_spill_count: 0
    .wavefront_size: 64
